# MoE-down: B-tile row permutation so each lane owns 16 contiguous fp8 cols; 8 dwordx4 epilogue stores instead of 16 dwordx2
# speedup vs baseline: 1.0203x; 1.0176x over previous
.LBB0_830:
	s_cmp_gt_i32 s60, 10
	s_cselect_b64 s[4:5], -1, 0
	s_cmp_lt_i32 s61, 11
	s_cselect_b64 s[6:7], -1, 0
	s_or_b64 s[4:5], s[4:5], s[6:7]
	s_and_b64 vcc, exec, s[4:5]
	s_cbranch_vccnz .LBB0_895
	s_waitcnt vmcnt(0)
	v_mov_b32_e32 v2, v0
	s_cmpk_gt_i32 s2, 0x43f
	v_readfirstlane_b32 s3, v2
	s_cbranch_scc1 .LBB0_845
	v_bfe_i32 v4, v2, 27, 1
	v_lshlrev_b32_e32 v1, 4, v2
	v_lshrrev_b32_e32 v4, 22, v4
	v_add_u32_e32 v4, v1, v4
	v_and_b32_e32 v4, 0xfffffc00, v4
	v_sub_u32_e32 v1, v1, v4
	v_ashrrev_i32_e32 v3, 31, v2
	v_lshrrev_b32_e32 v4, 4, v1
	v_lshrrev_b32_e32 v3, 26, v3
	v_bitop3_b32 v1, v4, v1, 32 bitop3:0x6c
	s_add_u32 s8, s52, 0x6b00000
	v_add_u32_e32 v3, v2, v3
	v_ashrrev_i32_e32 v5, 31, v1
	s_addc_u32 s6, s53, 0
	v_ashrrev_i32_e32 v3, 6, v3
	v_lshrrev_b32_e32 v5, 26, v5
	s_ashr_i32 s20, s2, 31
	v_lshlrev_b32_e32 v4, 3, v3
	v_add_u32_e32 v5, v1, v5
	s_lshr_b32 s7, s20, 29
	v_and_b32_e32 v4, -16, v4
	v_ashrrev_i32_e32 v6, 6, v5
	s_add_i32 s7, s2, s7
	s_ashr_i32 s4, s3, 6
	v_add_u32_e32 v4, v6, v4
	v_and_b32_e32 v6, 3, v6
	s_mov_b32 s5, 0x3fffe0
	s_ashr_i32 s12, s7, 3
	s_and_b32 s7, s7, -8
	s_and_b32 s45, s71, 0xffff
	v_and_or_b32 v6, v4, s5, v6
	s_ashr_i32 s5, s3, 8
	s_and_b32 s9, s6, 0xffff
	s_lshl_b32 s6, s4, 10
	s_sub_i32 s7, s2, s7
	s_cmp_lt_i32 s7, 0
	s_movk_i32 s21, 0x89
	s_cselect_b32 s13, s21, 0x88
	s_mul_i32 s7, s13, s7
	s_add_i32 s7, s7, s12
	s_ashr_i32 s12, s7, 31
	s_lshr_b32 s12, s12, 27
	s_add_i32 s12, s7, s12
	s_ashr_i32 s13, s12, 5
	s_andn2_b32 s12, s12, 31
	s_sub_i32 s7, s7, s12
	s_bfe_i32 s12, s7, 0x80000
	s_bfe_u32 s12, s12, 0x3000c
	s_add_i32 s12, s7, s12
	s_bfe_i32 s14, s12, 0x80000
	s_and_b32 s12, s12, 0xf8
	s_sub_i32 s7, s7, s12
	s_lshl_b32 s13, s13, 3
	s_sext_i32_i8 s7, s7
	v_and_b32_e32 v5, 0xc0, v5
	s_add_i32 s73, s13, s7
	v_sub_u32_e32 v1, v1, v5
	v_mov_b32_e32 v5, 1
	s_mul_hi_i32 s7, s73, 0x78787879
	v_lshlrev_b32_e32 v3, 5, v3
	v_ashrrev_i16_sdwa v1, v5, sext(v1) dst_sel:DWORD dst_unused:UNUSED_PAD src0_sel:DWORD src1_sel:BYTE_0
	v_lshlrev_b32_e32 v5, 1, v4
	v_lshrrev_b32_e32 v7, 2, v4
	s_sext_i32_i16 s14, s14
	s_lshr_b32 s12, s7, 31
	s_lshr_b32 s7, s7, 3
	v_and_b32_e32 v3, 32, v3
	v_bfe_i32 v1, v1, 0, 16
	v_and_b32_e32 v5, 24, v5
	v_and_b32_e32 v7, 4, v7
	s_ashr_i32 s72, s14, 3
	s_add_i32 s7, s7, s12
	s_add_i32 s22, s6, 0
	s_mov_b32 s47, 0x20000
	s_brev_b32 s46, -2
	v_or3_b32 v5, v6, v7, v5
	v_add_lshl_u32 v3, v3, v1, 1
	s_lshl_b32 s7, s7, 20
	s_lshl_b32 s12, s72, 18
	s_add_i32 s23, s22, 0x10000
	v_and_b32_e32 v254, 3, v4
	v_lshrrev_b32_e32 v5, 2, v4
	v_and_b32_e32 v5, 4, v5
	v_or_b32_e32 v254, v254, v5
	v_lshlrev_b32_e32 v5, 2, v4
	v_and_b32_e32 v5, 0x30, v5
	v_or_b32_e32 v254, v254, v5
	v_lshlrev_b32_e32 v5, 1, v4
	v_and_b32_e32 v5, 0x40, v5
	v_or_b32_e32 v254, v254, v5
	v_lshl_add_u32 v134, v254, 10, v3
	s_mov_b32 s10, s46
	s_mov_b32 s11, s47
	s_add_i32 s78, s7, s12
	s_mov_b32 m0, s23
	s_add_i32 s24, s22, 0x12000
	s_mov_b32 s100, 0
	buffer_load_dwordx4 v134, s[8:11], s78 offen lds
	s_or_b32 s6, s78, 0x20000
	s_mov_b32 m0, s24
	v_lshl_add_u32 v1, v4, 10, v3
	buffer_load_dwordx4 v134, s[8:11], s6 offen lds
	s_lshl_b32 s79, s73, 18
	s_mov_b32 m0, s22
	s_add_i32 s25, s22, 0x2000
	buffer_load_dwordx4 v1, s[44:47], s79 offen lds
	s_or_b32 s6, s79, 0x10000
	s_mov_b32 m0, s25
	s_add_i32 s26, s22, 0x14000
	buffer_load_dwordx4 v1, s[44:47], s6 offen lds
	s_or_b32 s6, s78, 0x2000
	s_mov_b32 m0, s26
	s_add_i32 s27, s22, 0x16000
	buffer_load_dwordx4 v134, s[8:11], s6 offen lds
	s_or_b32 s6, s78, 0x22000
	s_mov_b32 m0, s27
	s_add_i32 s28, s22, 0x4000
	buffer_load_dwordx4 v134, s[8:11], s6 offen lds
	s_or_b32 s6, s79, 0x20000
	s_mov_b32 m0, s28
	s_add_i32 s29, s22, 0x6000
	buffer_load_dwordx4 v1, s[44:47], s6 offen lds
	s_or_b32 s6, s79, 0x30000
	s_mov_b32 m0, s29
	s_cmp_lg_u32 s5, 1
	buffer_load_dwordx4 v1, s[44:47], s6 offen lds
	s_mov_b32 s30, 0
	s_cbranch_scc1 .LBB0_834
	s_barrier
.LBB0_834:
	s_add_i32 s31, s22, 0x18000
	s_or_b32 s6, s78, 0x80
	s_mov_b32 s10, s46
	s_mov_b32 s11, s47
	s_mov_b32 m0, s31
	s_add_i32 s34, s22, 0x1a000
	s_waitcnt vmcnt(4)
	s_barrier
	buffer_load_dwordx4 v134, s[8:11], s6 offen lds
	s_or_b32 s6, s78, 0x20080
	s_mov_b32 m0, s34
	s_add_i32 s35, s22, 0x8000
	buffer_load_dwordx4 v134, s[8:11], s6 offen lds
	s_or_b32 s6, s79, 0x80
	s_mov_b32 m0, s35
	s_add_i32 s36, s22, 0xa000
	buffer_load_dwordx4 v1, s[44:47], s6 offen lds
	s_or_b32 s6, s79, 0x10080
	s_mov_b32 m0, s36
	s_add_i32 s37, s22, 0x1c000
	buffer_load_dwordx4 v1, s[44:47], s6 offen lds
	s_or_b32 s6, s78, 0x2080
	s_mov_b32 m0, s37
	s_add_i32 s38, s22, 0x1e000
	buffer_load_dwordx4 v134, s[8:11], s6 offen lds
	s_or_b32 s6, s78, 0x22080
	s_mov_b32 m0, s38
	v_and_b32_e32 v3, 15, v2
	buffer_load_dwordx4 v134, s[8:11], s6 offen lds
	v_lshrrev_b32_e32 v4, 1, v2
	s_and_b32 s4, s4, 3
	v_and_b32_e32 v4, 24, v4
	v_lshlrev_b32_e32 v5, 6, v3
	v_lshlrev_b32_e32 v2, 2, v2
	v_lshl_or_b32 v5, v4, 1, v5
	v_and_b32_e32 v2, 32, v2
	s_lshl_b32 s6, s5, 13
	s_lshl_b32 s7, s4, 12
	v_bitop3_b32 v6, v5, s6, v2 bitop3:0xde
	v_bitop3_b32 v2, v5, s7, v2 bitop3:0xde
	s_waitcnt vmcnt(6)
	v_add_u32_e32 v2, 0, v2
	s_add_i32 s39, s22, 0xc000
	v_lshl_or_b32 v135, s5, 6, v3
	s_add_i32 s41, s22, 0xe000
	s_ashr_i32 s42, s56, 31
	v_lshl_or_b32 v136, s4, 5, v4
	v_add_u32_e32 v137, 0x10000, v2
	v_add_u32_e32 v138, 0, v6
	v_add_u32_e32 v139, 0x14000, v2
	v_add_u32_e32 v140, 0x18000, v2
	v_add_u32_e32 v141, 0x1c000, v2
	s_mov_b64 s[12:13], 0x20000
	s_mov_b64 s[14:15], 0x24000
	s_mov_b32 s43, 0x24000
	s_mov_b64 s[16:17], 0x28000
	s_mov_b32 s49, 0x28000
	s_mov_b64 s[18:19], 0x2c000
	s_mov_b32 s50, 0x2c000
	s_barrier

.LBB0_839:
	s_lshl_b32 s59, s57, 18
	s_and_b64 s[6:7], s[6:7], exec
	v_mov_b32_e32 v2, 0
	s_cselect_b32 s6, s59, s79
	s_add_i32 s7, s79, 0x30080
	s_addk_i32 s78, 0x100
	s_mov_b32 s79, -2
	ds_read_b128 v[142:145], v137
	ds_read_b128 v[146:149], v137 offset:1024
	ds_read_b128 v[150:153], v137 offset:2048
	ds_read_b128 v[154:157], v137 offset:3072
	s_add_i32 s10, s7, 0xfffd0080
	s_cmp_eq_u32 s79, 4
	s_cselect_b32 s87, s6, s10
	s_cselect_b32 s86, s58, s78
	s_or_b32 s88, s87, 0x80
	s_add_i32 s10, s7, 0xffff0000
	s_mov_b32 m0, s39
	ds_read_b128 v[158:161], v138
	ds_read_b128 v[162:165], v138 offset:1024
	ds_read_b128 v[166:169], v138 offset:2048
	ds_read_b128 v[170:173], v138 offset:3072
	ds_read_b128 v[174:177], v138 offset:4096
	ds_read_b128 v[178:181], v138 offset:5120
	ds_read_b128 v[182:185], v138 offset:6144
	ds_read_b128 v[186:189], v138 offset:7168
	buffer_load_dwordx4 v1, s[44:47], s10 offen lds
	s_mov_b32 m0, s41
	s_nop 0
	buffer_load_dwordx4 v1, s[44:47], s7 offen lds
	s_waitcnt lgkmcnt(8)
	s_barrier
	s_waitcnt lgkmcnt(0)
	s_setprio 1
	s_waitcnt lgkmcnt(4)
	v_mfma_f32_16x16x128_f8f6f4 v[114:117], v[142:149], v[166:173], 0
	v_mfma_f32_16x16x128_f8f6f4 v[106:109], v[150:157], v[166:173], 0
	s_waitcnt lgkmcnt(2)
	v_mfma_f32_16x16x128_f8f6f4 v[98:101], v[142:149], v[174:181], 0
	v_mfma_f32_16x16x128_f8f6f4 v[198:201], v[142:149], v[158:165], 0
	v_mfma_f32_16x16x128_f8f6f4 v[202:205], v[150:157], v[158:165], 0
	v_mfma_f32_16x16x128_f8f6f4 v[206:209], v[150:157], v[174:181], 0
	s_waitcnt lgkmcnt(0)
	v_mfma_f32_16x16x128_f8f6f4 v[210:213], v[142:149], v[182:189], 0
	v_mfma_f32_16x16x128_f8f6f4 v[214:217], v[150:157], v[182:189], 0
	s_setprio 0
	s_barrier
	s_mov_b32 m0, s23
	s_mov_b32 s10, s46
	s_mov_b32 s11, s47
	ds_read_b128 v[122:125], v139
	ds_read_b128 v[126:129], v139 offset:1024
	ds_read_b128 v[190:193], v139 offset:2048
	ds_read_b128 v[194:197], v139 offset:3072
	buffer_load_dwordx4 v134, s[8:11], s86 offen lds
	s_add_i32 s33, s86, 0x20000
	s_mov_b32 m0, s24
	s_nop 0
	buffer_load_dwordx4 v134, s[8:11], s33 offen lds
	s_barrier
	s_waitcnt lgkmcnt(0)
	s_setprio 1
	s_waitcnt lgkmcnt(2)
	v_mfma_f32_16x16x128_f8f6f4 v[118:121], v[122:129], v[158:165], 0
	s_waitcnt lgkmcnt(0)
	v_mfma_f32_16x16x128_f8f6f4 v[110:113], v[190:197], v[158:165], 0
	v_mfma_f32_16x16x128_f8f6f4 v[102:105], v[122:129], v[166:173], 0
	v_mfma_f32_16x16x128_f8f6f4 v[158:161], v[190:197], v[166:173], 0
	v_mfma_f32_16x16x128_f8f6f4 v[162:165], v[122:129], v[174:181], 0
	v_mfma_f32_16x16x128_f8f6f4 v[166:169], v[190:197], v[174:181], 0
	v_mfma_f32_16x16x128_f8f6f4 v[170:173], v[122:129], v[182:189], 0
	v_mfma_f32_16x16x128_f8f6f4 v[174:177], v[190:197], v[182:189], 0
	s_setprio 0
	s_mov_b32 m0, s22
	s_barrier
	ds_read_b128 v[66:69], v138 offset:16384
	s_nop 1
	ds_read_b128 v[70:73], v138 offset:17408
	ds_read_b128 v[74:77], v138 offset:18432
	ds_read_b128 v[78:81], v138 offset:19456
	ds_read_b128 v[82:85], v138 offset:20480
	ds_read_b128 v[86:89], v138 offset:21504
	ds_read_b128 v[90:93], v138 offset:22528
	ds_read_b128 v[94:97], v138 offset:23552
	buffer_load_dwordx4 v1, s[44:47], s87 offen lds
	s_add_i32 s33, s87, 0x10000
	s_mov_b32 m0, s25
	s_nop 0
	buffer_load_dwordx4 v1, s[44:47], s33 offen lds
	s_barrier
	s_waitcnt lgkmcnt(0)
	s_setprio 1
	s_waitcnt lgkmcnt(6)
	v_mfma_f32_16x16x128_f8f6f4 v[62:65], v[142:149], v[66:73], 0
	v_mfma_f32_16x16x128_f8f6f4 v[58:61], v[150:157], v[66:73], 0
	s_waitcnt lgkmcnt(4)
	v_mfma_f32_16x16x128_f8f6f4 v[50:53], v[142:149], v[74:81], 0
	s_waitcnt lgkmcnt(0)
	v_mfma_f32_16x16x128_f8f6f4 v[230:233], v[142:149], v[90:97], 0
	v_mfma_f32_16x16x128_f8f6f4 v[218:221], v[150:157], v[74:81], 0
	v_mfma_f32_16x16x128_f8f6f4 v[222:225], v[142:149], v[82:89], 0
	v_mfma_f32_16x16x128_f8f6f4 v[226:229], v[150:157], v[82:89], 0
	v_mfma_f32_16x16x128_f8f6f4 v[234:237], v[150:157], v[90:97], 0
	s_setprio 0
	s_barrier
	s_mov_b32 m0, s26
	s_add_i32 s33, s86, 0x2000
	buffer_load_dwordx4 v134, s[8:11], s33 offen lds
	s_add_i32 s33, s86, 0x22000
	s_mov_b32 m0, s27
	s_nop 0
	buffer_load_dwordx4 v134, s[8:11], s33 offen lds
	s_cmp_eq_u32 s100, 0
	s_cbranch_scc1 .Lfw_4_a_p
	s_waitcnt vmcnt(16)
	s_mov_b32 s100, 0
	s_branch .Lfw_4_b_p

.Lfw_4_b_p:
	s_barrier
	s_setprio 1
	v_mfma_f32_16x16x128_f8f6f4 v[54:57], v[122:129], v[66:73], 0
	v_mfma_f32_16x16x128_f8f6f4 v[238:241], v[190:197], v[66:73], 0
	v_mfma_f32_16x16x128_f8f6f4 v[242:245], v[122:129], v[74:81], 0
	v_mfma_f32_16x16x128_f8f6f4 v[246:249], v[190:197], v[74:81], 0
	v_mfma_f32_16x16x128_f8f6f4 v[250:253], v[122:129], v[82:89], 0
	v_mfma_f32_16x16x128_f8f6f4 v[130:133], v[190:197], v[82:89], 0
	v_mfma_f32_16x16x128_f8f6f4 v[66:69], v[122:129], v[90:97], 0
	v_mfma_f32_16x16x128_f8f6f4 v[190:193], v[190:197], v[90:97], 0
	s_setprio 0
	s_barrier
	s_nop 4
	ds_read_b128 v[2:5], v140
	ds_read_b128 v[6:9], v140 offset:1024
	ds_read_b128 v[10:13], v140 offset:2048
	ds_read_b128 v[14:17], v140 offset:3072
	s_mov_b32 m0, s28
	s_add_i32 s33, s87, 0x20000
	ds_read_b128 v[18:21], v138 offset:32768
	ds_read_b128 v[22:25], v138 offset:33792
	ds_read_b128 v[26:29], v138 offset:34816
	ds_read_b128 v[30:33], v138 offset:35840
	ds_read_b128 v[34:37], v138 offset:36864
	ds_read_b128 v[38:41], v138 offset:37888
	ds_read_b128 v[42:45], v138 offset:38912
	ds_read_b128 v[46:49], v138 offset:39936
	buffer_load_dwordx4 v1, s[44:47], s33 offen lds
	s_add_i32 s33, s87, 0x30000
	s_mov_b32 m0, s29
	s_nop 0
	buffer_load_dwordx4 v1, s[44:47], s33 offen lds
	s_waitcnt lgkmcnt(8)
	s_barrier
	s_waitcnt lgkmcnt(0)
	s_setprio 1
	s_waitcnt lgkmcnt(6)
	v_mfma_f32_16x16x128_f8f6f4 v[126:129], v[2:9], v[18:25], v[198:201]
	v_mfma_f32_16x16x128_f8f6f4 v[122:125], v[10:17], v[18:25], v[202:205]
	s_waitcnt lgkmcnt(4)
	v_mfma_f32_16x16x128_f8f6f4 v[114:117], v[2:9], v[26:33], v[114:117]
	v_mfma_f32_16x16x128_f8f6f4 v[106:109], v[10:17], v[26:33], v[106:109]
	s_waitcnt lgkmcnt(2)
	v_mfma_f32_16x16x128_f8f6f4 v[98:101], v[2:9], v[34:41], v[98:101]
	v_mfma_f32_16x16x128_f8f6f4 v[90:93], v[10:17], v[34:41], v[206:209]
	s_waitcnt lgkmcnt(0)
	v_mfma_f32_16x16x128_f8f6f4 v[82:85], v[2:9], v[42:49], v[210:213]
	v_mfma_f32_16x16x128_f8f6f4 v[74:77], v[10:17], v[42:49], v[214:217]
	s_setprio 0
	s_barrier
	s_mov_b32 m0, s31
	s_add_i32 s33, s86, 0x80
	ds_read_b128 v[142:145], v141
	ds_read_b128 v[146:149], v141 offset:1024
	ds_read_b128 v[150:153], v141 offset:2048
	ds_read_b128 v[154:157], v141 offset:3072
	buffer_load_dwordx4 v134, s[8:11], s33 offen lds
	s_add_i32 s33, s86, 0x20080
	s_mov_b32 m0, s34
	s_nop 0
	buffer_load_dwordx4 v134, s[8:11], s33 offen lds
	s_waitcnt vmcnt(10)
	s_barrier
	s_waitcnt lgkmcnt(0)
	s_setprio 1
	s_waitcnt lgkmcnt(2)
	v_mfma_f32_16x16x128_f8f6f4 v[118:121], v[142:149], v[18:25], v[118:121]
	s_waitcnt lgkmcnt(0)
	v_mfma_f32_16x16x128_f8f6f4 v[110:113], v[150:157], v[18:25], v[110:113]
	v_mfma_f32_16x16x128_f8f6f4 v[102:105], v[142:149], v[26:33], v[102:105]
	v_mfma_f32_16x16x128_f8f6f4 v[94:97], v[150:157], v[26:33], v[158:161]
	v_mfma_f32_16x16x128_f8f6f4 v[86:89], v[142:149], v[34:41], v[162:165]
	v_mfma_f32_16x16x128_f8f6f4 v[78:81], v[150:157], v[34:41], v[166:169]
	v_mfma_f32_16x16x128_f8f6f4 v[70:73], v[142:149], v[42:49], v[170:173]
	v_mfma_f32_16x16x128_f8f6f4 v[18:21], v[150:157], v[42:49], v[174:177]
	s_setprio 0
	s_mov_b32 m0, s35
	s_barrier
	ds_read_b128 v[158:161], v138 offset:49152
	ds_read_b128 v[162:165], v138 offset:50176
	ds_read_b128 v[166:169], v138 offset:51200
	ds_read_b128 v[170:173], v138 offset:52224
	ds_read_b128 v[174:177], v138 offset:53248
	ds_read_b128 v[178:181], v138 offset:54272
	ds_read_b128 v[182:185], v138 offset:55296
	ds_read_b128 v[186:189], v138 offset:56320
	buffer_load_dwordx4 v1, s[44:47], s88 offen lds
	s_add_i32 s87, s87, 0x10080
	s_mov_b32 m0, s36
	s_nop 0
	buffer_load_dwordx4 v1, s[44:47], s87 offen lds
	s_barrier
	s_waitcnt lgkmcnt(0)
	s_setprio 1
	s_waitcnt lgkmcnt(6)
	v_mfma_f32_16x16x128_f8f6f4 v[62:65], v[2:9], v[158:165], v[62:65]
	v_mfma_f32_16x16x128_f8f6f4 v[58:61], v[10:17], v[158:165], v[58:61]
	s_waitcnt lgkmcnt(4)
	v_mfma_f32_16x16x128_f8f6f4 v[50:53], v[2:9], v[166:173], v[50:53]
	v_mfma_f32_16x16x128_f8f6f4 v[42:45], v[10:17], v[166:173], v[218:221]
	s_waitcnt lgkmcnt(2)
	v_mfma_f32_16x16x128_f8f6f4 v[34:37], v[2:9], v[174:181], v[222:225]
	v_mfma_f32_16x16x128_f8f6f4 v[26:29], v[10:17], v[174:181], v[226:229]
	s_waitcnt lgkmcnt(0)
	v_mfma_f32_16x16x128_f8f6f4 v[230:233], v[2:9], v[182:189], v[230:233]
	v_mfma_f32_16x16x128_f8f6f4 v[10:13], v[10:17], v[182:189], v[234:237]
	s_setprio 0
	s_barrier
	s_mov_b32 m0, s37
	s_add_i32 s33, s86, 0x2080
	buffer_load_dwordx4 v134, s[8:11], s33 offen lds
	s_add_i32 s86, s86, 0x22080
	s_mov_b32 m0, s38
	s_nop 0
	buffer_load_dwordx4 v134, s[8:11], s86 offen lds
	s_waitcnt vmcnt(6)
	s_barrier
	s_setprio 1
	v_mfma_f32_16x16x128_f8f6f4 v[54:57], v[142:149], v[158:165], v[54:57]
	v_mfma_f32_16x16x128_f8f6f4 v[46:49], v[150:157], v[158:165], v[238:241]
	v_mfma_f32_16x16x128_f8f6f4 v[38:41], v[142:149], v[166:173], v[242:245]
	v_mfma_f32_16x16x128_f8f6f4 v[30:33], v[150:157], v[166:173], v[246:249]
	v_mfma_f32_16x16x128_f8f6f4 v[22:25], v[142:149], v[174:181], v[250:253]
	v_mfma_f32_16x16x128_f8f6f4 v[14:17], v[150:157], v[174:181], v[130:133]
	v_mfma_f32_16x16x128_f8f6f4 v[6:9], v[142:149], v[182:189], v[66:69]
	v_mfma_f32_16x16x128_f8f6f4 v[2:5], v[150:157], v[182:189], v[190:193]
	s_setprio 0
	s_add_i32 s79, s79, 2
	s_addk_i32 s7, 0x100
	s_addk_i32 s78, 0x100
	s_cmp_gt_u32 s79, 5
	s_barrier
.LBB0_840:
	ds_read_b128 v[142:145], v137
	ds_read_b128 v[146:149], v137 offset:1024
	ds_read_b128 v[150:153], v137 offset:2048
	ds_read_b128 v[154:157], v137 offset:3072
	s_add_i32 s10, s7, 0xfffd0080
	s_cmp_eq_u32 s79, 4
	s_cselect_b32 s87, s6, s10
	s_cselect_b32 s86, s58, s78
	s_or_b32 s88, s87, 0x80
	s_add_i32 s10, s7, 0xffff0000
	s_mov_b32 m0, s39
	ds_read_b128 v[158:161], v138
	ds_read_b128 v[162:165], v138 offset:1024
	ds_read_b128 v[166:169], v138 offset:2048
	ds_read_b128 v[170:173], v138 offset:3072
	ds_read_b128 v[174:177], v138 offset:4096
	ds_read_b128 v[178:181], v138 offset:5120
	ds_read_b128 v[182:185], v138 offset:6144
	ds_read_b128 v[186:189], v138 offset:7168
	buffer_load_dwordx4 v1, s[44:47], s10 offen lds
	s_mov_b32 m0, s41
	s_nop 0
	buffer_load_dwordx4 v1, s[44:47], s7 offen lds
	s_waitcnt lgkmcnt(8)
	s_barrier
	s_waitcnt lgkmcnt(0)
	s_setprio 1
	s_waitcnt lgkmcnt(4)
	v_mfma_f32_16x16x128_f8f6f4 v[114:117], v[142:149], v[166:173], v[114:117]
	v_mfma_f32_16x16x128_f8f6f4 v[106:109], v[150:157], v[166:173], v[106:109]
	s_waitcnt lgkmcnt(2)
	v_mfma_f32_16x16x128_f8f6f4 v[98:101], v[142:149], v[174:181], v[98:101]
	v_mfma_f32_16x16x128_f8f6f4 v[198:201], v[142:149], v[158:165], v[126:129]
	v_mfma_f32_16x16x128_f8f6f4 v[202:205], v[150:157], v[158:165], v[122:125]
	v_mfma_f32_16x16x128_f8f6f4 v[206:209], v[150:157], v[174:181], v[90:93]
	s_waitcnt lgkmcnt(0)
	v_mfma_f32_16x16x128_f8f6f4 v[210:213], v[142:149], v[182:189], v[82:85]
	v_mfma_f32_16x16x128_f8f6f4 v[214:217], v[150:157], v[182:189], v[74:77]
	s_setprio 0
	s_barrier
	s_mov_b32 m0, s23
	s_mov_b32 s10, s46
	s_mov_b32 s11, s47
	ds_read_b128 v[122:125], v139
	ds_read_b128 v[126:129], v139 offset:1024
	ds_read_b128 v[190:193], v139 offset:2048
	ds_read_b128 v[194:197], v139 offset:3072
	buffer_load_dwordx4 v134, s[8:11], s86 offen lds
	s_add_i32 s33, s86, 0x20000
	s_mov_b32 m0, s24
	s_nop 0
	buffer_load_dwordx4 v134, s[8:11], s33 offen lds
	s_barrier
	s_waitcnt lgkmcnt(0)
	s_setprio 1
	s_waitcnt lgkmcnt(2)
	v_mfma_f32_16x16x128_f8f6f4 v[118:121], v[122:129], v[158:165], v[118:121]
	s_waitcnt lgkmcnt(0)
	v_mfma_f32_16x16x128_f8f6f4 v[110:113], v[190:197], v[158:165], v[110:113]
	v_mfma_f32_16x16x128_f8f6f4 v[102:105], v[122:129], v[166:173], v[102:105]
	v_mfma_f32_16x16x128_f8f6f4 v[158:161], v[190:197], v[166:173], v[94:97]
	v_mfma_f32_16x16x128_f8f6f4 v[162:165], v[122:129], v[174:181], v[86:89]
	v_mfma_f32_16x16x128_f8f6f4 v[166:169], v[190:197], v[174:181], v[78:81]
	v_mfma_f32_16x16x128_f8f6f4 v[170:173], v[122:129], v[182:189], v[70:73]
	v_mfma_f32_16x16x128_f8f6f4 v[174:177], v[190:197], v[182:189], v[18:21]
	s_setprio 0
	s_mov_b32 m0, s22
	s_barrier
	ds_read_b128 v[66:69], v138 offset:16384
	s_nop 1
	ds_read_b128 v[70:73], v138 offset:17408
	ds_read_b128 v[74:77], v138 offset:18432
	ds_read_b128 v[78:81], v138 offset:19456
	ds_read_b128 v[82:85], v138 offset:20480
	ds_read_b128 v[86:89], v138 offset:21504
	ds_read_b128 v[90:93], v138 offset:22528
	ds_read_b128 v[94:97], v138 offset:23552
	buffer_load_dwordx4 v1, s[44:47], s87 offen lds
	s_add_i32 s33, s87, 0x10000
	s_mov_b32 m0, s25
	s_nop 0
	buffer_load_dwordx4 v1, s[44:47], s33 offen lds
	s_barrier
	s_waitcnt lgkmcnt(0)
	s_setprio 1
	s_waitcnt lgkmcnt(6)
	v_mfma_f32_16x16x128_f8f6f4 v[62:65], v[142:149], v[66:73], v[62:65]
	v_mfma_f32_16x16x128_f8f6f4 v[58:61], v[150:157], v[66:73], v[58:61]
	s_waitcnt lgkmcnt(4)
	v_mfma_f32_16x16x128_f8f6f4 v[50:53], v[142:149], v[74:81], v[50:53]
	s_waitcnt lgkmcnt(0)
	v_mfma_f32_16x16x128_f8f6f4 v[230:233], v[142:149], v[90:97], v[230:233]
	v_mfma_f32_16x16x128_f8f6f4 v[218:221], v[150:157], v[74:81], v[42:45]
	v_mfma_f32_16x16x128_f8f6f4 v[222:225], v[142:149], v[82:89], v[34:37]
	v_mfma_f32_16x16x128_f8f6f4 v[226:229], v[150:157], v[82:89], v[26:29]
	v_mfma_f32_16x16x128_f8f6f4 v[234:237], v[150:157], v[90:97], v[10:13]
	s_setprio 0
	s_barrier
	s_mov_b32 m0, s26
	s_add_i32 s33, s86, 0x2000
	buffer_load_dwordx4 v134, s[8:11], s33 offen lds
	s_add_i32 s33, s86, 0x22000
	s_mov_b32 m0, s27
	s_nop 0
	buffer_load_dwordx4 v134, s[8:11], s33 offen lds
	s_cmp_eq_u32 s100, 0
	s_cbranch_scc1 .Lfw_4_a
	s_waitcnt vmcnt(16)
	s_mov_b32 s100, 0
	s_branch .Lfw_4_b

.Lfw_4_b:
	s_barrier
	s_setprio 1
	v_mfma_f32_16x16x128_f8f6f4 v[54:57], v[122:129], v[66:73], v[54:57]
	v_mfma_f32_16x16x128_f8f6f4 v[238:241], v[190:197], v[66:73], v[46:49]
	v_mfma_f32_16x16x128_f8f6f4 v[242:245], v[122:129], v[74:81], v[38:41]
	v_mfma_f32_16x16x128_f8f6f4 v[246:249], v[190:197], v[74:81], v[30:33]
	v_mfma_f32_16x16x128_f8f6f4 v[250:253], v[122:129], v[82:89], v[22:25]
	v_mfma_f32_16x16x128_f8f6f4 v[130:133], v[190:197], v[82:89], v[14:17]
	v_mfma_f32_16x16x128_f8f6f4 v[66:69], v[122:129], v[90:97], v[6:9]
	v_mfma_f32_16x16x128_f8f6f4 v[190:193], v[190:197], v[90:97], v[2:5]
	s_setprio 0
	s_barrier
	s_nop 4
	ds_read_b128 v[2:5], v140
	ds_read_b128 v[6:9], v140 offset:1024
	ds_read_b128 v[10:13], v140 offset:2048
	ds_read_b128 v[14:17], v140 offset:3072
	s_mov_b32 m0, s28
	s_add_i32 s33, s87, 0x20000
	ds_read_b128 v[18:21], v138 offset:32768
	ds_read_b128 v[22:25], v138 offset:33792
	ds_read_b128 v[26:29], v138 offset:34816
	ds_read_b128 v[30:33], v138 offset:35840
	ds_read_b128 v[34:37], v138 offset:36864
	ds_read_b128 v[38:41], v138 offset:37888
	ds_read_b128 v[42:45], v138 offset:38912
	ds_read_b128 v[46:49], v138 offset:39936
	buffer_load_dwordx4 v1, s[44:47], s33 offen lds
	s_add_i32 s33, s87, 0x30000
	s_mov_b32 m0, s29
	s_nop 0
	buffer_load_dwordx4 v1, s[44:47], s33 offen lds
	s_waitcnt lgkmcnt(8)
	s_barrier
	s_waitcnt lgkmcnt(0)
	s_setprio 1
	s_waitcnt lgkmcnt(6)
	v_mfma_f32_16x16x128_f8f6f4 v[126:129], v[2:9], v[18:25], v[198:201]
	v_mfma_f32_16x16x128_f8f6f4 v[122:125], v[10:17], v[18:25], v[202:205]
	s_waitcnt lgkmcnt(4)
	v_mfma_f32_16x16x128_f8f6f4 v[114:117], v[2:9], v[26:33], v[114:117]
	v_mfma_f32_16x16x128_f8f6f4 v[106:109], v[10:17], v[26:33], v[106:109]
	s_waitcnt lgkmcnt(2)
	v_mfma_f32_16x16x128_f8f6f4 v[98:101], v[2:9], v[34:41], v[98:101]
	v_mfma_f32_16x16x128_f8f6f4 v[90:93], v[10:17], v[34:41], v[206:209]
	s_waitcnt lgkmcnt(0)
	v_mfma_f32_16x16x128_f8f6f4 v[82:85], v[2:9], v[42:49], v[210:213]
	v_mfma_f32_16x16x128_f8f6f4 v[74:77], v[10:17], v[42:49], v[214:217]
	s_setprio 0
	s_barrier
	s_mov_b32 m0, s31
	s_add_i32 s33, s86, 0x80
	ds_read_b128 v[142:145], v141
	ds_read_b128 v[146:149], v141 offset:1024
	ds_read_b128 v[150:153], v141 offset:2048
	ds_read_b128 v[154:157], v141 offset:3072
	buffer_load_dwordx4 v134, s[8:11], s33 offen lds
	s_add_i32 s33, s86, 0x20080
	s_mov_b32 m0, s34
	s_nop 0
	buffer_load_dwordx4 v134, s[8:11], s33 offen lds
	s_waitcnt vmcnt(10)
	s_barrier
	s_waitcnt lgkmcnt(0)
	s_setprio 1
	s_waitcnt lgkmcnt(2)
	v_mfma_f32_16x16x128_f8f6f4 v[118:121], v[142:149], v[18:25], v[118:121]
	s_waitcnt lgkmcnt(0)
	v_mfma_f32_16x16x128_f8f6f4 v[110:113], v[150:157], v[18:25], v[110:113]
	v_mfma_f32_16x16x128_f8f6f4 v[102:105], v[142:149], v[26:33], v[102:105]
	v_mfma_f32_16x16x128_f8f6f4 v[94:97], v[150:157], v[26:33], v[158:161]
	v_mfma_f32_16x16x128_f8f6f4 v[86:89], v[142:149], v[34:41], v[162:165]
	v_mfma_f32_16x16x128_f8f6f4 v[78:81], v[150:157], v[34:41], v[166:169]
	v_mfma_f32_16x16x128_f8f6f4 v[70:73], v[142:149], v[42:49], v[170:173]
	v_mfma_f32_16x16x128_f8f6f4 v[18:21], v[150:157], v[42:49], v[174:177]
	s_setprio 0
	s_mov_b32 m0, s35
	s_barrier
	ds_read_b128 v[158:161], v138 offset:49152
	ds_read_b128 v[162:165], v138 offset:50176
	ds_read_b128 v[166:169], v138 offset:51200
	ds_read_b128 v[170:173], v138 offset:52224
	ds_read_b128 v[174:177], v138 offset:53248
	ds_read_b128 v[178:181], v138 offset:54272
	ds_read_b128 v[182:185], v138 offset:55296
	ds_read_b128 v[186:189], v138 offset:56320
	buffer_load_dwordx4 v1, s[44:47], s88 offen lds
	s_add_i32 s87, s87, 0x10080
	s_mov_b32 m0, s36
	s_nop 0
	buffer_load_dwordx4 v1, s[44:47], s87 offen lds
	s_barrier
	s_waitcnt lgkmcnt(0)
	s_setprio 1
	s_waitcnt lgkmcnt(6)
	v_mfma_f32_16x16x128_f8f6f4 v[62:65], v[2:9], v[158:165], v[62:65]
	v_mfma_f32_16x16x128_f8f6f4 v[58:61], v[10:17], v[158:165], v[58:61]
	s_waitcnt lgkmcnt(4)
	v_mfma_f32_16x16x128_f8f6f4 v[50:53], v[2:9], v[166:173], v[50:53]
	v_mfma_f32_16x16x128_f8f6f4 v[42:45], v[10:17], v[166:173], v[218:221]
	s_waitcnt lgkmcnt(2)
	v_mfma_f32_16x16x128_f8f6f4 v[34:37], v[2:9], v[174:181], v[222:225]
	v_mfma_f32_16x16x128_f8f6f4 v[26:29], v[10:17], v[174:181], v[226:229]
	s_waitcnt lgkmcnt(0)
	v_mfma_f32_16x16x128_f8f6f4 v[230:233], v[2:9], v[182:189], v[230:233]
	v_mfma_f32_16x16x128_f8f6f4 v[10:13], v[10:17], v[182:189], v[234:237]
	s_setprio 0
	s_barrier
	s_mov_b32 m0, s37
	s_add_i32 s33, s86, 0x2080
	buffer_load_dwordx4 v134, s[8:11], s33 offen lds
	s_add_i32 s86, s86, 0x22080
	s_mov_b32 m0, s38
	s_nop 0
	buffer_load_dwordx4 v134, s[8:11], s86 offen lds
	s_waitcnt vmcnt(6)
	s_barrier
	s_setprio 1
	v_mfma_f32_16x16x128_f8f6f4 v[54:57], v[142:149], v[158:165], v[54:57]
	v_mfma_f32_16x16x128_f8f6f4 v[46:49], v[150:157], v[158:165], v[238:241]
	v_mfma_f32_16x16x128_f8f6f4 v[38:41], v[142:149], v[166:173], v[242:245]
	v_mfma_f32_16x16x128_f8f6f4 v[30:33], v[150:157], v[166:173], v[246:249]
	v_mfma_f32_16x16x128_f8f6f4 v[22:25], v[142:149], v[174:181], v[250:253]
	v_mfma_f32_16x16x128_f8f6f4 v[14:17], v[150:157], v[174:181], v[130:133]
	v_mfma_f32_16x16x128_f8f6f4 v[6:9], v[142:149], v[182:189], v[66:69]
	v_mfma_f32_16x16x128_f8f6f4 v[2:5], v[150:157], v[182:189], v[190:193]
	s_setprio 0
	s_add_i32 s79, s79, 2
	s_addk_i32 s7, 0x100
	s_addk_i32 s78, 0x100
	s_cmp_gt_u32 s79, 5
	s_barrier
	s_cbranch_scc0 .LBB0_840
	v_lshl_add_u32 v152, s73, 8, v135
	v_lshlrev_b32_e32 v153, 1, v136
	v_lshl_or_b32 v153, s72, 8, v153
	v_lshl_add_u32 v152, v152, 10, v153
	s_mov_b32 s72, s51
	s_mov_b32 s73, s57
	s_mov_b32 s78, s58
	s_mov_b32 s79, s59
	v_pk_mul_f32 v[126:127], v[126:127], 0.5 op_sel_hi:[1,0]
	v_pk_mul_f32 v[128:129], v[128:129], 0.5 op_sel_hi:[1,0]
	v_pk_mul_f32 v[122:123], v[122:123], 0.5 op_sel_hi:[1,0]
	v_pk_mul_f32 v[124:125], v[124:125], 0.5 op_sel_hi:[1,0]
	v_pk_mul_f32 v[118:119], v[118:119], 0.5 op_sel_hi:[1,0]
	v_pk_mul_f32 v[120:121], v[120:121], 0.5 op_sel_hi:[1,0]
	v_pk_mul_f32 v[110:111], v[110:111], 0.5 op_sel_hi:[1,0]
	v_pk_mul_f32 v[112:113], v[112:113], 0.5 op_sel_hi:[1,0]
	v_cvt_pk_fp8_f32 v144, v126, v127
	v_cvt_pk_fp8_f32 v145, v122, v123
	v_cvt_pk_fp8_f32 v146, v118, v119
	v_cvt_pk_fp8_f32 v147, v110, v111
	v_cvt_pk_fp8_f32 v144, v128, v129 op_sel:[0,0,1]
	v_cvt_pk_fp8_f32 v145, v124, v125 op_sel:[0,0,1]
	v_cvt_pk_fp8_f32 v146, v120, v121 op_sel:[0,0,1]
	v_cvt_pk_fp8_f32 v147, v112, v113 op_sel:[0,0,1]
	v_mov_b32_e32 v154, v152
	s_nop 0
	global_store_dwordx4 v154, v[144:147], s[68:69]
	s_mov_b32 s100, 1
	v_pk_mul_f32 v[114:115], v[114:115], 0.5 op_sel_hi:[1,0]
	v_pk_mul_f32 v[116:117], v[116:117], 0.5 op_sel_hi:[1,0]
	v_pk_mul_f32 v[106:107], v[106:107], 0.5 op_sel_hi:[1,0]
	v_pk_mul_f32 v[108:109], v[108:109], 0.5 op_sel_hi:[1,0]
	v_pk_mul_f32 v[102:103], v[102:103], 0.5 op_sel_hi:[1,0]
	v_pk_mul_f32 v[104:105], v[104:105], 0.5 op_sel_hi:[1,0]
	v_pk_mul_f32 v[94:95], v[94:95], 0.5 op_sel_hi:[1,0]
	v_pk_mul_f32 v[96:97], v[96:97], 0.5 op_sel_hi:[1,0]
	v_cvt_pk_fp8_f32 v148, v114, v115
	v_cvt_pk_fp8_f32 v149, v106, v107
	v_cvt_pk_fp8_f32 v150, v102, v103
	v_cvt_pk_fp8_f32 v151, v94, v95
	v_cvt_pk_fp8_f32 v148, v116, v117 op_sel:[0,0,1]
	v_cvt_pk_fp8_f32 v149, v108, v109 op_sel:[0,0,1]
	v_cvt_pk_fp8_f32 v150, v104, v105 op_sel:[0,0,1]
	v_cvt_pk_fp8_f32 v151, v96, v97 op_sel:[0,0,1]
	v_add_u32_e32 v155, 0x4000, v152
	s_nop 0
	global_store_dwordx4 v155, v[148:151], s[68:69]
	s_mov_b32 s100, 1
	v_pk_mul_f32 v[98:99], v[98:99], 0.5 op_sel_hi:[1,0]
	v_pk_mul_f32 v[100:101], v[100:101], 0.5 op_sel_hi:[1,0]
	v_pk_mul_f32 v[90:91], v[90:91], 0.5 op_sel_hi:[1,0]
	v_pk_mul_f32 v[92:93], v[92:93], 0.5 op_sel_hi:[1,0]
	v_pk_mul_f32 v[86:87], v[86:87], 0.5 op_sel_hi:[1,0]
	v_pk_mul_f32 v[88:89], v[88:89], 0.5 op_sel_hi:[1,0]
	v_pk_mul_f32 v[78:79], v[78:79], 0.5 op_sel_hi:[1,0]
	v_pk_mul_f32 v[80:81], v[80:81], 0.5 op_sel_hi:[1,0]
	v_cvt_pk_fp8_f32 v144, v98, v99
	v_cvt_pk_fp8_f32 v145, v90, v91
	v_cvt_pk_fp8_f32 v146, v86, v87
	v_cvt_pk_fp8_f32 v147, v78, v79
	v_cvt_pk_fp8_f32 v144, v100, v101 op_sel:[0,0,1]
	v_cvt_pk_fp8_f32 v145, v92, v93 op_sel:[0,0,1]
	v_cvt_pk_fp8_f32 v146, v88, v89 op_sel:[0,0,1]
	v_cvt_pk_fp8_f32 v147, v80, v81 op_sel:[0,0,1]
	v_add_u32_e32 v154, 0x8000, v152
	s_nop 0
	global_store_dwordx4 v154, v[144:147], s[68:69]
	s_mov_b32 s100, 1
	v_pk_mul_f32 v[82:83], v[82:83], 0.5 op_sel_hi:[1,0]
	v_pk_mul_f32 v[84:85], v[84:85], 0.5 op_sel_hi:[1,0]
	v_pk_mul_f32 v[74:75], v[74:75], 0.5 op_sel_hi:[1,0]
	v_pk_mul_f32 v[76:77], v[76:77], 0.5 op_sel_hi:[1,0]
	v_pk_mul_f32 v[70:71], v[70:71], 0.5 op_sel_hi:[1,0]
	v_pk_mul_f32 v[72:73], v[72:73], 0.5 op_sel_hi:[1,0]
	v_pk_mul_f32 v[18:19], v[18:19], 0.5 op_sel_hi:[1,0]
	v_pk_mul_f32 v[20:21], v[20:21], 0.5 op_sel_hi:[1,0]
	v_cvt_pk_fp8_f32 v148, v82, v83
	v_cvt_pk_fp8_f32 v149, v74, v75
	v_cvt_pk_fp8_f32 v150, v70, v71
	v_cvt_pk_fp8_f32 v151, v18, v19
	v_cvt_pk_fp8_f32 v148, v84, v85 op_sel:[0,0,1]
	v_cvt_pk_fp8_f32 v149, v76, v77 op_sel:[0,0,1]
	v_cvt_pk_fp8_f32 v150, v72, v73 op_sel:[0,0,1]
	v_cvt_pk_fp8_f32 v151, v20, v21 op_sel:[0,0,1]
	v_add_u32_e32 v155, 0xc000, v152
	s_nop 0
	global_store_dwordx4 v155, v[148:151], s[68:69]
	s_mov_b32 s100, 1
	v_pk_mul_f32 v[62:63], v[62:63], 0.5 op_sel_hi:[1,0]
	v_pk_mul_f32 v[64:65], v[64:65], 0.5 op_sel_hi:[1,0]
	v_pk_mul_f32 v[58:59], v[58:59], 0.5 op_sel_hi:[1,0]
	v_pk_mul_f32 v[60:61], v[60:61], 0.5 op_sel_hi:[1,0]
	v_pk_mul_f32 v[54:55], v[54:55], 0.5 op_sel_hi:[1,0]
	v_pk_mul_f32 v[56:57], v[56:57], 0.5 op_sel_hi:[1,0]
	v_pk_mul_f32 v[46:47], v[46:47], 0.5 op_sel_hi:[1,0]
	v_pk_mul_f32 v[48:49], v[48:49], 0.5 op_sel_hi:[1,0]
	v_cvt_pk_fp8_f32 v144, v62, v63
	v_cvt_pk_fp8_f32 v145, v58, v59
	v_cvt_pk_fp8_f32 v146, v54, v55
	v_cvt_pk_fp8_f32 v147, v46, v47
	v_cvt_pk_fp8_f32 v144, v64, v65 op_sel:[0,0,1]
	v_cvt_pk_fp8_f32 v145, v60, v61 op_sel:[0,0,1]
	v_cvt_pk_fp8_f32 v146, v56, v57 op_sel:[0,0,1]
	v_cvt_pk_fp8_f32 v147, v48, v49 op_sel:[0,0,1]
	v_add_u32_e32 v154, 0x20000, v152
	s_nop 0
	global_store_dwordx4 v154, v[144:147], s[68:69]
	s_mov_b32 s100, 1
	v_pk_mul_f32 v[50:51], v[50:51], 0.5 op_sel_hi:[1,0]
	v_pk_mul_f32 v[52:53], v[52:53], 0.5 op_sel_hi:[1,0]
	v_pk_mul_f32 v[42:43], v[42:43], 0.5 op_sel_hi:[1,0]
	v_pk_mul_f32 v[44:45], v[44:45], 0.5 op_sel_hi:[1,0]
	v_pk_mul_f32 v[38:39], v[38:39], 0.5 op_sel_hi:[1,0]
	v_pk_mul_f32 v[40:41], v[40:41], 0.5 op_sel_hi:[1,0]
	v_pk_mul_f32 v[30:31], v[30:31], 0.5 op_sel_hi:[1,0]
	v_pk_mul_f32 v[32:33], v[32:33], 0.5 op_sel_hi:[1,0]
	v_cvt_pk_fp8_f32 v148, v50, v51
	v_cvt_pk_fp8_f32 v149, v42, v43
	v_cvt_pk_fp8_f32 v150, v38, v39
	v_cvt_pk_fp8_f32 v151, v30, v31
	v_cvt_pk_fp8_f32 v148, v52, v53 op_sel:[0,0,1]
	v_cvt_pk_fp8_f32 v149, v44, v45 op_sel:[0,0,1]
	v_cvt_pk_fp8_f32 v150, v40, v41 op_sel:[0,0,1]
	v_cvt_pk_fp8_f32 v151, v32, v33 op_sel:[0,0,1]
	v_add_u32_e32 v155, 0x24000, v152
	s_nop 0
	global_store_dwordx4 v155, v[148:151], s[68:69]
	s_mov_b32 s100, 1
	v_pk_mul_f32 v[34:35], v[34:35], 0.5 op_sel_hi:[1,0]
	v_pk_mul_f32 v[36:37], v[36:37], 0.5 op_sel_hi:[1,0]
	v_pk_mul_f32 v[26:27], v[26:27], 0.5 op_sel_hi:[1,0]
	v_pk_mul_f32 v[28:29], v[28:29], 0.5 op_sel_hi:[1,0]
	v_pk_mul_f32 v[22:23], v[22:23], 0.5 op_sel_hi:[1,0]
	v_pk_mul_f32 v[24:25], v[24:25], 0.5 op_sel_hi:[1,0]
	v_pk_mul_f32 v[14:15], v[14:15], 0.5 op_sel_hi:[1,0]
	v_pk_mul_f32 v[16:17], v[16:17], 0.5 op_sel_hi:[1,0]
	v_cvt_pk_fp8_f32 v144, v34, v35
	v_cvt_pk_fp8_f32 v145, v26, v27
	v_cvt_pk_fp8_f32 v146, v22, v23
	v_cvt_pk_fp8_f32 v147, v14, v15
	v_cvt_pk_fp8_f32 v144, v36, v37 op_sel:[0,0,1]
	v_cvt_pk_fp8_f32 v145, v28, v29 op_sel:[0,0,1]
	v_cvt_pk_fp8_f32 v146, v24, v25 op_sel:[0,0,1]
	v_cvt_pk_fp8_f32 v147, v16, v17 op_sel:[0,0,1]
	v_add_u32_e32 v154, 0x28000, v152
	s_nop 0
	global_store_dwordx4 v154, v[144:147], s[68:69]
	s_mov_b32 s100, 1
	v_pk_mul_f32 v[230:231], v[230:231], 0.5 op_sel_hi:[1,0]
	v_pk_mul_f32 v[232:233], v[232:233], 0.5 op_sel_hi:[1,0]
	v_pk_mul_f32 v[10:11], v[10:11], 0.5 op_sel_hi:[1,0]
	v_pk_mul_f32 v[12:13], v[12:13], 0.5 op_sel_hi:[1,0]
	v_pk_mul_f32 v[6:7], v[6:7], 0.5 op_sel_hi:[1,0]
	v_pk_mul_f32 v[8:9], v[8:9], 0.5 op_sel_hi:[1,0]
	v_pk_mul_f32 v[2:3], v[2:3], 0.5 op_sel_hi:[1,0]
	v_pk_mul_f32 v[4:5], v[4:5], 0.5 op_sel_hi:[1,0]
	v_cvt_pk_fp8_f32 v148, v230, v231
	v_cvt_pk_fp8_f32 v149, v10, v11
	v_cvt_pk_fp8_f32 v150, v6, v7
	v_cvt_pk_fp8_f32 v151, v2, v3
	v_cvt_pk_fp8_f32 v148, v232, v233 op_sel:[0,0,1]
	v_cvt_pk_fp8_f32 v149, v12, v13 op_sel:[0,0,1]
	v_cvt_pk_fp8_f32 v150, v8, v9 op_sel:[0,0,1]
	v_cvt_pk_fp8_f32 v151, v4, v5 op_sel:[0,0,1]
	v_add_u32_e32 v155, 0x2c000, v152
	s_nop 0
	global_store_dwordx4 v155, v[148:151], s[68:69]
	s_mov_b32 s100, 1
	s_and_b64 vcc, exec, s[4:5]
	s_cbranch_vccz .LBB0_835
	s_waitcnt vmcnt(0)
	s_cmpk_gt_u32 s3, 0xff
	s_cbranch_scc1 .LBB0_844
	s_barrier

.LBB0_1714:
	s_cmp_gt_i32 s60, 22
	s_cselect_b64 s[4:5], -1, 0
	s_cmp_lt_i32 s61, 23
	s_cselect_b64 s[6:7], -1, 0
	s_or_b64 s[4:5], s[4:5], s[6:7]
	s_and_b64 vcc, exec, s[4:5]
	s_cbranch_vccnz .LBB0_1779
	s_waitcnt vmcnt(0)
	v_mov_b32_e32 v2, v0
	s_cmpk_gt_i32 s2, 0x43f
	v_readfirstlane_b32 s3, v2
	s_cbranch_scc1 .LBB0_1729
	v_bfe_i32 v4, v2, 27, 1
	v_lshlrev_b32_e32 v1, 4, v2
	v_lshrrev_b32_e32 v4, 22, v4
	v_add_u32_e32 v4, v1, v4
	v_and_b32_e32 v4, 0xfffffc00, v4
	v_sub_u32_e32 v1, v1, v4
	v_ashrrev_i32_e32 v3, 31, v2
	v_lshrrev_b32_e32 v4, 4, v1
	v_lshrrev_b32_e32 v3, 26, v3
	v_bitop3_b32 v1, v4, v1, 32 bitop3:0x6c
	s_add_u32 s8, s52, 0x7b00000
	v_add_u32_e32 v3, v2, v3
	v_ashrrev_i32_e32 v5, 31, v1
	s_addc_u32 s6, s53, 0
	v_ashrrev_i32_e32 v3, 6, v3
	v_lshrrev_b32_e32 v5, 26, v5
	s_ashr_i32 s20, s2, 31
	v_lshlrev_b32_e32 v4, 3, v3
	v_add_u32_e32 v5, v1, v5
	s_lshr_b32 s7, s20, 29
	v_and_b32_e32 v4, -16, v4
	v_ashrrev_i32_e32 v6, 6, v5
	s_add_i32 s7, s2, s7
	s_ashr_i32 s4, s3, 6
	v_add_u32_e32 v4, v6, v4
	v_and_b32_e32 v6, 3, v6
	s_mov_b32 s5, 0x3fffe0
	s_ashr_i32 s12, s7, 3
	s_and_b32 s7, s7, -8
	s_and_b32 s45, s71, 0xffff
	v_and_or_b32 v6, v4, s5, v6
	s_ashr_i32 s5, s3, 8
	s_and_b32 s9, s6, 0xffff
	s_lshl_b32 s6, s4, 10
	s_sub_i32 s7, s2, s7
	s_cmp_lt_i32 s7, 0
	s_movk_i32 s21, 0x89
	s_cselect_b32 s13, s21, 0x88
	s_mul_i32 s7, s13, s7
	s_add_i32 s7, s7, s12
	s_ashr_i32 s12, s7, 31
	s_lshr_b32 s12, s12, 27
	s_add_i32 s12, s7, s12
	s_ashr_i32 s13, s12, 5
	s_andn2_b32 s12, s12, 31
	s_sub_i32 s7, s7, s12
	s_bfe_i32 s12, s7, 0x80000
	s_bfe_u32 s12, s12, 0x3000c
	s_add_i32 s12, s7, s12
	s_bfe_i32 s14, s12, 0x80000
	s_and_b32 s12, s12, 0xf8
	s_sub_i32 s7, s7, s12
	s_lshl_b32 s13, s13, 3
	s_sext_i32_i8 s7, s7
	v_and_b32_e32 v5, 0xc0, v5
	s_add_i32 s79, s13, s7
	v_sub_u32_e32 v1, v1, v5
	v_mov_b32_e32 v5, 1
	s_mul_hi_i32 s7, s79, 0x78787879
	v_lshlrev_b32_e32 v3, 5, v3
	v_ashrrev_i16_sdwa v1, v5, sext(v1) dst_sel:DWORD dst_unused:UNUSED_PAD src0_sel:DWORD src1_sel:BYTE_0
	v_lshlrev_b32_e32 v5, 1, v4
	v_lshrrev_b32_e32 v7, 2, v4
	s_sext_i32_i16 s14, s14
	s_lshr_b32 s12, s7, 31
	s_lshr_b32 s7, s7, 3
	v_and_b32_e32 v3, 32, v3
	v_bfe_i32 v1, v1, 0, 16
	v_and_b32_e32 v5, 24, v5
	v_and_b32_e32 v7, 4, v7
	s_ashr_i32 s78, s14, 3
	s_add_i32 s7, s7, s12
	s_add_i32 s22, s6, 0
	s_mov_b32 s47, 0x20000
	s_brev_b32 s46, -2
	v_or3_b32 v5, v6, v7, v5
	v_add_lshl_u32 v3, v3, v1, 1
	s_lshl_b32 s7, s7, 20
	s_lshl_b32 s12, s78, 18
	s_add_i32 s23, s22, 0x10000
	v_and_b32_e32 v254, 3, v4
	v_lshrrev_b32_e32 v5, 2, v4
	v_and_b32_e32 v5, 4, v5
	v_or_b32_e32 v254, v254, v5
	v_lshlrev_b32_e32 v5, 2, v4
	v_and_b32_e32 v5, 0x30, v5
	v_or_b32_e32 v254, v254, v5
	v_lshlrev_b32_e32 v5, 1, v4
	v_and_b32_e32 v5, 0x40, v5
	v_or_b32_e32 v254, v254, v5
	v_lshl_add_u32 v134, v254, 10, v3
	s_mov_b32 s10, s46
	s_mov_b32 s11, s47
	s_add_i32 s84, s7, s12
	s_mov_b32 m0, s23
	s_add_i32 s24, s22, 0x12000
	s_mov_b32 s100, 0
	buffer_load_dwordx4 v134, s[8:11], s84 offen lds
	s_or_b32 s6, s84, 0x20000
	s_mov_b32 m0, s24
	v_lshl_add_u32 v1, v4, 10, v3
	buffer_load_dwordx4 v134, s[8:11], s6 offen lds
	s_lshl_b32 s85, s79, 18
	s_mov_b32 m0, s22
	s_add_i32 s25, s22, 0x2000
	buffer_load_dwordx4 v1, s[44:47], s85 offen lds
	s_or_b32 s6, s85, 0x10000
	s_mov_b32 m0, s25
	s_add_i32 s26, s22, 0x14000
	buffer_load_dwordx4 v1, s[44:47], s6 offen lds
	s_or_b32 s6, s84, 0x2000
	s_mov_b32 m0, s26
	s_add_i32 s27, s22, 0x16000
	buffer_load_dwordx4 v134, s[8:11], s6 offen lds
	s_or_b32 s6, s84, 0x22000
	s_mov_b32 m0, s27
	s_add_i32 s28, s22, 0x4000
	buffer_load_dwordx4 v134, s[8:11], s6 offen lds
	s_or_b32 s6, s85, 0x20000
	s_mov_b32 m0, s28
	s_add_i32 s29, s22, 0x6000
	buffer_load_dwordx4 v1, s[44:47], s6 offen lds
	s_or_b32 s6, s85, 0x30000
	s_mov_b32 m0, s29
	s_cmp_lg_u32 s5, 1
	buffer_load_dwordx4 v1, s[44:47], s6 offen lds
	s_mov_b32 s30, 0
	s_cbranch_scc1 .LBB0_1718
	s_barrier
.LBB0_1718:
	s_add_i32 s31, s22, 0x18000
	s_or_b32 s6, s84, 0x80
	s_mov_b32 s10, s46
	s_mov_b32 s11, s47
	s_mov_b32 m0, s31
	s_add_i32 s34, s22, 0x1a000
	s_waitcnt vmcnt(4)
	s_barrier
	buffer_load_dwordx4 v134, s[8:11], s6 offen lds
	s_or_b32 s6, s84, 0x20080
	s_mov_b32 m0, s34
	s_add_i32 s35, s22, 0x8000
	buffer_load_dwordx4 v134, s[8:11], s6 offen lds
	s_or_b32 s6, s85, 0x80
	s_mov_b32 m0, s35
	s_add_i32 s36, s22, 0xa000
	buffer_load_dwordx4 v1, s[44:47], s6 offen lds
	s_or_b32 s6, s85, 0x10080
	s_mov_b32 m0, s36
	s_add_i32 s37, s22, 0x1c000
	buffer_load_dwordx4 v1, s[44:47], s6 offen lds
	s_or_b32 s6, s84, 0x2080
	s_mov_b32 m0, s37
	s_add_i32 s38, s22, 0x1e000
	buffer_load_dwordx4 v134, s[8:11], s6 offen lds
	s_or_b32 s6, s84, 0x22080
	s_mov_b32 m0, s38
	v_and_b32_e32 v3, 15, v2
	buffer_load_dwordx4 v134, s[8:11], s6 offen lds
	v_lshrrev_b32_e32 v4, 1, v2
	s_and_b32 s4, s4, 3
	v_and_b32_e32 v4, 24, v4
	v_lshlrev_b32_e32 v5, 6, v3
	v_lshlrev_b32_e32 v2, 2, v2
	v_lshl_or_b32 v5, v4, 1, v5
	v_and_b32_e32 v2, 32, v2
	s_lshl_b32 s6, s5, 13
	s_lshl_b32 s7, s4, 12
	v_bitop3_b32 v6, v5, s6, v2 bitop3:0xde
	v_bitop3_b32 v2, v5, s7, v2 bitop3:0xde
	s_waitcnt vmcnt(6)
	v_add_u32_e32 v2, 0, v2
	s_add_i32 s39, s22, 0xc000
	v_lshl_or_b32 v135, s5, 6, v3
	s_add_i32 s41, s22, 0xe000
	s_ashr_i32 s42, s56, 31
	v_lshl_or_b32 v136, s4, 5, v4
	v_add_u32_e32 v137, 0x10000, v2
	v_add_u32_e32 v138, 0, v6
	v_add_u32_e32 v139, 0x14000, v2
	v_add_u32_e32 v140, 0x18000, v2
	v_add_u32_e32 v141, 0x1c000, v2
	s_mov_b64 s[12:13], 0x20000
	s_mov_b64 s[14:15], 0x24000
	s_mov_b32 s43, 0x24000
	s_mov_b64 s[16:17], 0x28000
	s_mov_b32 s49, 0x28000
	s_mov_b64 s[18:19], 0x2c000
	s_mov_b32 s57, 0x2c000
	s_barrier

.LBB0_1723:
	s_lshl_b32 s73, s59, 18
	s_and_b64 s[6:7], s[6:7], exec
	v_mov_b32_e32 v2, 0
	s_cselect_b32 s6, s73, s85
	s_add_i32 s7, s85, 0x30080
	s_addk_i32 s84, 0x100
	s_mov_b32 s85, -2
	ds_read_b128 v[142:145], v137
	ds_read_b128 v[146:149], v137 offset:1024
	ds_read_b128 v[150:153], v137 offset:2048
	ds_read_b128 v[154:157], v137 offset:3072
	s_add_i32 s10, s7, 0xfffd0080
	s_cmp_eq_u32 s85, 4
	s_cselect_b32 s87, s6, s10
	s_cselect_b32 s86, s72, s84
	s_or_b32 s88, s87, 0x80
	s_add_i32 s10, s7, 0xffff0000
	s_mov_b32 m0, s39
	ds_read_b128 v[158:161], v138
	ds_read_b128 v[162:165], v138 offset:1024
	ds_read_b128 v[166:169], v138 offset:2048
	ds_read_b128 v[170:173], v138 offset:3072
	ds_read_b128 v[174:177], v138 offset:4096
	ds_read_b128 v[178:181], v138 offset:5120
	ds_read_b128 v[182:185], v138 offset:6144
	ds_read_b128 v[186:189], v138 offset:7168
	buffer_load_dwordx4 v1, s[44:47], s10 offen lds
	s_mov_b32 m0, s41
	s_nop 0
	buffer_load_dwordx4 v1, s[44:47], s7 offen lds
	s_waitcnt lgkmcnt(8)
	s_barrier
	s_waitcnt lgkmcnt(0)
	s_setprio 1
	s_waitcnt lgkmcnt(4)
	v_mfma_f32_16x16x128_f8f6f4 v[114:117], v[142:149], v[166:173], 0
	v_mfma_f32_16x16x128_f8f6f4 v[106:109], v[150:157], v[166:173], 0
	s_waitcnt lgkmcnt(2)
	v_mfma_f32_16x16x128_f8f6f4 v[98:101], v[142:149], v[174:181], 0
	v_mfma_f32_16x16x128_f8f6f4 v[198:201], v[142:149], v[158:165], 0
	v_mfma_f32_16x16x128_f8f6f4 v[202:205], v[150:157], v[158:165], 0
	v_mfma_f32_16x16x128_f8f6f4 v[206:209], v[150:157], v[174:181], 0
	s_waitcnt lgkmcnt(0)
	v_mfma_f32_16x16x128_f8f6f4 v[210:213], v[142:149], v[182:189], 0
	v_mfma_f32_16x16x128_f8f6f4 v[214:217], v[150:157], v[182:189], 0
	s_setprio 0
	s_barrier
	s_mov_b32 m0, s23
	s_mov_b32 s10, s46
	s_mov_b32 s11, s47
	ds_read_b128 v[122:125], v139
	ds_read_b128 v[126:129], v139 offset:1024
	ds_read_b128 v[190:193], v139 offset:2048
	ds_read_b128 v[194:197], v139 offset:3072
	buffer_load_dwordx4 v134, s[8:11], s86 offen lds
	s_add_i32 s33, s86, 0x20000
	s_mov_b32 m0, s24
	s_nop 0
	buffer_load_dwordx4 v134, s[8:11], s33 offen lds
	s_barrier
	s_waitcnt lgkmcnt(0)
	s_setprio 1
	s_waitcnt lgkmcnt(2)
	v_mfma_f32_16x16x128_f8f6f4 v[118:121], v[122:129], v[158:165], 0
	s_waitcnt lgkmcnt(0)
	v_mfma_f32_16x16x128_f8f6f4 v[110:113], v[190:197], v[158:165], 0
	v_mfma_f32_16x16x128_f8f6f4 v[102:105], v[122:129], v[166:173], 0
	v_mfma_f32_16x16x128_f8f6f4 v[158:161], v[190:197], v[166:173], 0
	v_mfma_f32_16x16x128_f8f6f4 v[162:165], v[122:129], v[174:181], 0
	v_mfma_f32_16x16x128_f8f6f4 v[166:169], v[190:197], v[174:181], 0
	v_mfma_f32_16x16x128_f8f6f4 v[170:173], v[122:129], v[182:189], 0
	v_mfma_f32_16x16x128_f8f6f4 v[174:177], v[190:197], v[182:189], 0
	s_setprio 0
	s_mov_b32 m0, s22
	s_barrier
	ds_read_b128 v[66:69], v138 offset:16384
	s_nop 1
	ds_read_b128 v[70:73], v138 offset:17408
	ds_read_b128 v[74:77], v138 offset:18432
	ds_read_b128 v[78:81], v138 offset:19456
	ds_read_b128 v[82:85], v138 offset:20480
	ds_read_b128 v[86:89], v138 offset:21504
	ds_read_b128 v[90:93], v138 offset:22528
	ds_read_b128 v[94:97], v138 offset:23552
	buffer_load_dwordx4 v1, s[44:47], s87 offen lds
	s_add_i32 s33, s87, 0x10000
	s_mov_b32 m0, s25
	s_nop 0
	buffer_load_dwordx4 v1, s[44:47], s33 offen lds
	s_barrier
	s_waitcnt lgkmcnt(0)
	s_setprio 1
	s_waitcnt lgkmcnt(6)
	v_mfma_f32_16x16x128_f8f6f4 v[62:65], v[142:149], v[66:73], 0
	v_mfma_f32_16x16x128_f8f6f4 v[58:61], v[150:157], v[66:73], 0
	s_waitcnt lgkmcnt(4)
	v_mfma_f32_16x16x128_f8f6f4 v[50:53], v[142:149], v[74:81], 0
	s_waitcnt lgkmcnt(0)
	v_mfma_f32_16x16x128_f8f6f4 v[230:233], v[142:149], v[90:97], 0
	v_mfma_f32_16x16x128_f8f6f4 v[218:221], v[150:157], v[74:81], 0
	v_mfma_f32_16x16x128_f8f6f4 v[222:225], v[142:149], v[82:89], 0
	v_mfma_f32_16x16x128_f8f6f4 v[226:229], v[150:157], v[82:89], 0
	v_mfma_f32_16x16x128_f8f6f4 v[234:237], v[150:157], v[90:97], 0
	s_setprio 0
	s_barrier
	s_mov_b32 m0, s26
	s_add_i32 s33, s86, 0x2000
	buffer_load_dwordx4 v134, s[8:11], s33 offen lds
	s_add_i32 s33, s86, 0x22000
	s_mov_b32 m0, s27
	s_nop 0
	buffer_load_dwordx4 v134, s[8:11], s33 offen lds
	s_cmp_eq_u32 s100, 0
	s_cbranch_scc1 .Lfw_8_a_p
	s_waitcnt vmcnt(16)
	s_mov_b32 s100, 0
	s_branch .Lfw_8_b_p

.Lfw_8_b_p:
	s_barrier
	s_setprio 1
	v_mfma_f32_16x16x128_f8f6f4 v[54:57], v[122:129], v[66:73], 0
	v_mfma_f32_16x16x128_f8f6f4 v[238:241], v[190:197], v[66:73], 0
	v_mfma_f32_16x16x128_f8f6f4 v[242:245], v[122:129], v[74:81], 0
	v_mfma_f32_16x16x128_f8f6f4 v[246:249], v[190:197], v[74:81], 0
	v_mfma_f32_16x16x128_f8f6f4 v[250:253], v[122:129], v[82:89], 0
	v_mfma_f32_16x16x128_f8f6f4 v[130:133], v[190:197], v[82:89], 0
	v_mfma_f32_16x16x128_f8f6f4 v[66:69], v[122:129], v[90:97], 0
	v_mfma_f32_16x16x128_f8f6f4 v[190:193], v[190:197], v[90:97], 0
	s_setprio 0
	s_barrier
	s_nop 4
	ds_read_b128 v[2:5], v140
	ds_read_b128 v[6:9], v140 offset:1024
	ds_read_b128 v[10:13], v140 offset:2048
	ds_read_b128 v[14:17], v140 offset:3072
	s_mov_b32 m0, s28
	s_add_i32 s33, s87, 0x20000
	ds_read_b128 v[18:21], v138 offset:32768
	ds_read_b128 v[22:25], v138 offset:33792
	ds_read_b128 v[26:29], v138 offset:34816
	ds_read_b128 v[30:33], v138 offset:35840
	ds_read_b128 v[34:37], v138 offset:36864
	ds_read_b128 v[38:41], v138 offset:37888
	ds_read_b128 v[42:45], v138 offset:38912
	ds_read_b128 v[46:49], v138 offset:39936
	buffer_load_dwordx4 v1, s[44:47], s33 offen lds
	s_add_i32 s33, s87, 0x30000
	s_mov_b32 m0, s29
	s_nop 0
	buffer_load_dwordx4 v1, s[44:47], s33 offen lds
	s_waitcnt lgkmcnt(8)
	s_barrier
	s_waitcnt lgkmcnt(0)
	s_setprio 1
	s_waitcnt lgkmcnt(6)
	v_mfma_f32_16x16x128_f8f6f4 v[126:129], v[2:9], v[18:25], v[198:201]
	v_mfma_f32_16x16x128_f8f6f4 v[122:125], v[10:17], v[18:25], v[202:205]
	s_waitcnt lgkmcnt(4)
	v_mfma_f32_16x16x128_f8f6f4 v[114:117], v[2:9], v[26:33], v[114:117]
	v_mfma_f32_16x16x128_f8f6f4 v[106:109], v[10:17], v[26:33], v[106:109]
	s_waitcnt lgkmcnt(2)
	v_mfma_f32_16x16x128_f8f6f4 v[98:101], v[2:9], v[34:41], v[98:101]
	v_mfma_f32_16x16x128_f8f6f4 v[90:93], v[10:17], v[34:41], v[206:209]
	s_waitcnt lgkmcnt(0)
	v_mfma_f32_16x16x128_f8f6f4 v[82:85], v[2:9], v[42:49], v[210:213]
	v_mfma_f32_16x16x128_f8f6f4 v[74:77], v[10:17], v[42:49], v[214:217]
	s_setprio 0
	s_barrier
	s_mov_b32 m0, s31
	s_add_i32 s33, s86, 0x80
	ds_read_b128 v[142:145], v141
	ds_read_b128 v[146:149], v141 offset:1024
	ds_read_b128 v[150:153], v141 offset:2048
	ds_read_b128 v[154:157], v141 offset:3072
	buffer_load_dwordx4 v134, s[8:11], s33 offen lds
	s_add_i32 s33, s86, 0x20080
	s_mov_b32 m0, s34
	s_nop 0
	buffer_load_dwordx4 v134, s[8:11], s33 offen lds
	s_waitcnt vmcnt(10)
	s_barrier
	s_waitcnt lgkmcnt(0)
	s_setprio 1
	s_waitcnt lgkmcnt(2)
	v_mfma_f32_16x16x128_f8f6f4 v[118:121], v[142:149], v[18:25], v[118:121]
	s_waitcnt lgkmcnt(0)
	v_mfma_f32_16x16x128_f8f6f4 v[110:113], v[150:157], v[18:25], v[110:113]
	v_mfma_f32_16x16x128_f8f6f4 v[102:105], v[142:149], v[26:33], v[102:105]
	v_mfma_f32_16x16x128_f8f6f4 v[94:97], v[150:157], v[26:33], v[158:161]
	v_mfma_f32_16x16x128_f8f6f4 v[86:89], v[142:149], v[34:41], v[162:165]
	v_mfma_f32_16x16x128_f8f6f4 v[78:81], v[150:157], v[34:41], v[166:169]
	v_mfma_f32_16x16x128_f8f6f4 v[70:73], v[142:149], v[42:49], v[170:173]
	v_mfma_f32_16x16x128_f8f6f4 v[18:21], v[150:157], v[42:49], v[174:177]
	s_setprio 0
	s_mov_b32 m0, s35
	s_barrier
	ds_read_b128 v[158:161], v138 offset:49152
	ds_read_b128 v[162:165], v138 offset:50176
	ds_read_b128 v[166:169], v138 offset:51200
	ds_read_b128 v[170:173], v138 offset:52224
	ds_read_b128 v[174:177], v138 offset:53248
	ds_read_b128 v[178:181], v138 offset:54272
	ds_read_b128 v[182:185], v138 offset:55296
	ds_read_b128 v[186:189], v138 offset:56320
	buffer_load_dwordx4 v1, s[44:47], s88 offen lds
	s_add_i32 s87, s87, 0x10080
	s_mov_b32 m0, s36
	s_nop 0
	buffer_load_dwordx4 v1, s[44:47], s87 offen lds
	s_barrier
	s_waitcnt lgkmcnt(0)
	s_setprio 1
	s_waitcnt lgkmcnt(6)
	v_mfma_f32_16x16x128_f8f6f4 v[62:65], v[2:9], v[158:165], v[62:65]
	v_mfma_f32_16x16x128_f8f6f4 v[58:61], v[10:17], v[158:165], v[58:61]
	s_waitcnt lgkmcnt(4)
	v_mfma_f32_16x16x128_f8f6f4 v[50:53], v[2:9], v[166:173], v[50:53]
	v_mfma_f32_16x16x128_f8f6f4 v[42:45], v[10:17], v[166:173], v[218:221]
	s_waitcnt lgkmcnt(2)
	v_mfma_f32_16x16x128_f8f6f4 v[34:37], v[2:9], v[174:181], v[222:225]
	v_mfma_f32_16x16x128_f8f6f4 v[26:29], v[10:17], v[174:181], v[226:229]
	s_waitcnt lgkmcnt(0)
	v_mfma_f32_16x16x128_f8f6f4 v[230:233], v[2:9], v[182:189], v[230:233]
	v_mfma_f32_16x16x128_f8f6f4 v[10:13], v[10:17], v[182:189], v[234:237]
	s_setprio 0
	s_barrier
	s_mov_b32 m0, s37
	s_add_i32 s33, s86, 0x2080
	buffer_load_dwordx4 v134, s[8:11], s33 offen lds
	s_add_i32 s86, s86, 0x22080
	s_mov_b32 m0, s38
	s_nop 0
	buffer_load_dwordx4 v134, s[8:11], s86 offen lds
	s_waitcnt vmcnt(6)
	s_barrier
	s_setprio 1
	v_mfma_f32_16x16x128_f8f6f4 v[54:57], v[142:149], v[158:165], v[54:57]
	v_mfma_f32_16x16x128_f8f6f4 v[46:49], v[150:157], v[158:165], v[238:241]
	v_mfma_f32_16x16x128_f8f6f4 v[38:41], v[142:149], v[166:173], v[242:245]
	v_mfma_f32_16x16x128_f8f6f4 v[30:33], v[150:157], v[166:173], v[246:249]
	v_mfma_f32_16x16x128_f8f6f4 v[22:25], v[142:149], v[174:181], v[250:253]
	v_mfma_f32_16x16x128_f8f6f4 v[14:17], v[150:157], v[174:181], v[130:133]
	v_mfma_f32_16x16x128_f8f6f4 v[6:9], v[142:149], v[182:189], v[66:69]
	v_mfma_f32_16x16x128_f8f6f4 v[2:5], v[150:157], v[182:189], v[190:193]
	s_setprio 0
	s_add_i32 s85, s85, 2
	s_addk_i32 s7, 0x100
	s_addk_i32 s84, 0x100
	s_cmp_gt_u32 s85, 5
	s_barrier
.LBB0_1724:
	ds_read_b128 v[142:145], v137
	ds_read_b128 v[146:149], v137 offset:1024
	ds_read_b128 v[150:153], v137 offset:2048
	ds_read_b128 v[154:157], v137 offset:3072
	s_add_i32 s10, s7, 0xfffd0080
	s_cmp_eq_u32 s85, 4
	s_cselect_b32 s87, s6, s10
	s_cselect_b32 s86, s72, s84
	s_or_b32 s88, s87, 0x80
	s_add_i32 s10, s7, 0xffff0000
	s_mov_b32 m0, s39
	ds_read_b128 v[158:161], v138
	ds_read_b128 v[162:165], v138 offset:1024
	ds_read_b128 v[166:169], v138 offset:2048
	ds_read_b128 v[170:173], v138 offset:3072
	ds_read_b128 v[174:177], v138 offset:4096
	ds_read_b128 v[178:181], v138 offset:5120
	ds_read_b128 v[182:185], v138 offset:6144
	ds_read_b128 v[186:189], v138 offset:7168
	buffer_load_dwordx4 v1, s[44:47], s10 offen lds
	s_mov_b32 m0, s41
	s_nop 0
	buffer_load_dwordx4 v1, s[44:47], s7 offen lds
	s_waitcnt lgkmcnt(8)
	s_barrier
	s_waitcnt lgkmcnt(0)
	s_setprio 1
	s_waitcnt lgkmcnt(4)
	v_mfma_f32_16x16x128_f8f6f4 v[114:117], v[142:149], v[166:173], v[114:117]
	v_mfma_f32_16x16x128_f8f6f4 v[106:109], v[150:157], v[166:173], v[106:109]
	s_waitcnt lgkmcnt(2)
	v_mfma_f32_16x16x128_f8f6f4 v[98:101], v[142:149], v[174:181], v[98:101]
	v_mfma_f32_16x16x128_f8f6f4 v[198:201], v[142:149], v[158:165], v[126:129]
	v_mfma_f32_16x16x128_f8f6f4 v[202:205], v[150:157], v[158:165], v[122:125]
	v_mfma_f32_16x16x128_f8f6f4 v[206:209], v[150:157], v[174:181], v[90:93]
	s_waitcnt lgkmcnt(0)
	v_mfma_f32_16x16x128_f8f6f4 v[210:213], v[142:149], v[182:189], v[82:85]
	v_mfma_f32_16x16x128_f8f6f4 v[214:217], v[150:157], v[182:189], v[74:77]
	s_setprio 0
	s_barrier
	s_mov_b32 m0, s23
	s_mov_b32 s10, s46
	s_mov_b32 s11, s47
	ds_read_b128 v[122:125], v139
	ds_read_b128 v[126:129], v139 offset:1024
	ds_read_b128 v[190:193], v139 offset:2048
	ds_read_b128 v[194:197], v139 offset:3072
	buffer_load_dwordx4 v134, s[8:11], s86 offen lds
	s_add_i32 s33, s86, 0x20000
	s_mov_b32 m0, s24
	s_nop 0
	buffer_load_dwordx4 v134, s[8:11], s33 offen lds
	s_barrier
	s_waitcnt lgkmcnt(0)
	s_setprio 1
	s_waitcnt lgkmcnt(2)
	v_mfma_f32_16x16x128_f8f6f4 v[118:121], v[122:129], v[158:165], v[118:121]
	s_waitcnt lgkmcnt(0)
	v_mfma_f32_16x16x128_f8f6f4 v[110:113], v[190:197], v[158:165], v[110:113]
	v_mfma_f32_16x16x128_f8f6f4 v[102:105], v[122:129], v[166:173], v[102:105]
	v_mfma_f32_16x16x128_f8f6f4 v[158:161], v[190:197], v[166:173], v[94:97]
	v_mfma_f32_16x16x128_f8f6f4 v[162:165], v[122:129], v[174:181], v[86:89]
	v_mfma_f32_16x16x128_f8f6f4 v[166:169], v[190:197], v[174:181], v[78:81]
	v_mfma_f32_16x16x128_f8f6f4 v[170:173], v[122:129], v[182:189], v[70:73]
	v_mfma_f32_16x16x128_f8f6f4 v[174:177], v[190:197], v[182:189], v[18:21]
	s_setprio 0
	s_mov_b32 m0, s22
	s_barrier
	ds_read_b128 v[66:69], v138 offset:16384
	s_nop 1
	ds_read_b128 v[70:73], v138 offset:17408
	ds_read_b128 v[74:77], v138 offset:18432
	ds_read_b128 v[78:81], v138 offset:19456
	ds_read_b128 v[82:85], v138 offset:20480
	ds_read_b128 v[86:89], v138 offset:21504
	ds_read_b128 v[90:93], v138 offset:22528
	ds_read_b128 v[94:97], v138 offset:23552
	buffer_load_dwordx4 v1, s[44:47], s87 offen lds
	s_add_i32 s33, s87, 0x10000
	s_mov_b32 m0, s25
	s_nop 0
	buffer_load_dwordx4 v1, s[44:47], s33 offen lds
	s_barrier
	s_waitcnt lgkmcnt(0)
	s_setprio 1
	s_waitcnt lgkmcnt(6)
	v_mfma_f32_16x16x128_f8f6f4 v[62:65], v[142:149], v[66:73], v[62:65]
	v_mfma_f32_16x16x128_f8f6f4 v[58:61], v[150:157], v[66:73], v[58:61]
	s_waitcnt lgkmcnt(4)
	v_mfma_f32_16x16x128_f8f6f4 v[50:53], v[142:149], v[74:81], v[50:53]
	s_waitcnt lgkmcnt(0)
	v_mfma_f32_16x16x128_f8f6f4 v[230:233], v[142:149], v[90:97], v[230:233]
	v_mfma_f32_16x16x128_f8f6f4 v[218:221], v[150:157], v[74:81], v[42:45]
	v_mfma_f32_16x16x128_f8f6f4 v[222:225], v[142:149], v[82:89], v[34:37]
	v_mfma_f32_16x16x128_f8f6f4 v[226:229], v[150:157], v[82:89], v[26:29]
	v_mfma_f32_16x16x128_f8f6f4 v[234:237], v[150:157], v[90:97], v[10:13]
	s_setprio 0
	s_barrier
	s_mov_b32 m0, s26
	s_add_i32 s33, s86, 0x2000
	buffer_load_dwordx4 v134, s[8:11], s33 offen lds
	s_add_i32 s33, s86, 0x22000
	s_mov_b32 m0, s27
	s_nop 0
	buffer_load_dwordx4 v134, s[8:11], s33 offen lds
	s_cmp_eq_u32 s100, 0
	s_cbranch_scc1 .Lfw_8_a
	s_waitcnt vmcnt(16)
	s_mov_b32 s100, 0
	s_branch .Lfw_8_b

.Lfw_8_b:
	s_barrier
	s_setprio 1
	v_mfma_f32_16x16x128_f8f6f4 v[54:57], v[122:129], v[66:73], v[54:57]
	v_mfma_f32_16x16x128_f8f6f4 v[238:241], v[190:197], v[66:73], v[46:49]
	v_mfma_f32_16x16x128_f8f6f4 v[242:245], v[122:129], v[74:81], v[38:41]
	v_mfma_f32_16x16x128_f8f6f4 v[246:249], v[190:197], v[74:81], v[30:33]
	v_mfma_f32_16x16x128_f8f6f4 v[250:253], v[122:129], v[82:89], v[22:25]
	v_mfma_f32_16x16x128_f8f6f4 v[130:133], v[190:197], v[82:89], v[14:17]
	v_mfma_f32_16x16x128_f8f6f4 v[66:69], v[122:129], v[90:97], v[6:9]
	v_mfma_f32_16x16x128_f8f6f4 v[190:193], v[190:197], v[90:97], v[2:5]
	s_setprio 0
	s_barrier
	s_nop 4
	ds_read_b128 v[2:5], v140
	ds_read_b128 v[6:9], v140 offset:1024
	ds_read_b128 v[10:13], v140 offset:2048
	ds_read_b128 v[14:17], v140 offset:3072
	s_mov_b32 m0, s28
	s_add_i32 s33, s87, 0x20000
	ds_read_b128 v[18:21], v138 offset:32768
	ds_read_b128 v[22:25], v138 offset:33792
	ds_read_b128 v[26:29], v138 offset:34816
	ds_read_b128 v[30:33], v138 offset:35840
	ds_read_b128 v[34:37], v138 offset:36864
	ds_read_b128 v[38:41], v138 offset:37888
	ds_read_b128 v[42:45], v138 offset:38912
	ds_read_b128 v[46:49], v138 offset:39936
	buffer_load_dwordx4 v1, s[44:47], s33 offen lds
	s_add_i32 s33, s87, 0x30000
	s_mov_b32 m0, s29
	s_nop 0
	buffer_load_dwordx4 v1, s[44:47], s33 offen lds
	s_waitcnt lgkmcnt(8)
	s_barrier
	s_waitcnt lgkmcnt(0)
	s_setprio 1
	s_waitcnt lgkmcnt(6)
	v_mfma_f32_16x16x128_f8f6f4 v[126:129], v[2:9], v[18:25], v[198:201]
	v_mfma_f32_16x16x128_f8f6f4 v[122:125], v[10:17], v[18:25], v[202:205]
	s_waitcnt lgkmcnt(4)
	v_mfma_f32_16x16x128_f8f6f4 v[114:117], v[2:9], v[26:33], v[114:117]
	v_mfma_f32_16x16x128_f8f6f4 v[106:109], v[10:17], v[26:33], v[106:109]
	s_waitcnt lgkmcnt(2)
	v_mfma_f32_16x16x128_f8f6f4 v[98:101], v[2:9], v[34:41], v[98:101]
	v_mfma_f32_16x16x128_f8f6f4 v[90:93], v[10:17], v[34:41], v[206:209]
	s_waitcnt lgkmcnt(0)
	v_mfma_f32_16x16x128_f8f6f4 v[82:85], v[2:9], v[42:49], v[210:213]
	v_mfma_f32_16x16x128_f8f6f4 v[74:77], v[10:17], v[42:49], v[214:217]
	s_setprio 0
	s_barrier
	s_mov_b32 m0, s31
	s_add_i32 s33, s86, 0x80
	ds_read_b128 v[142:145], v141
	ds_read_b128 v[146:149], v141 offset:1024
	ds_read_b128 v[150:153], v141 offset:2048
	ds_read_b128 v[154:157], v141 offset:3072
	buffer_load_dwordx4 v134, s[8:11], s33 offen lds
	s_add_i32 s33, s86, 0x20080
	s_mov_b32 m0, s34
	s_nop 0
	buffer_load_dwordx4 v134, s[8:11], s33 offen lds
	s_waitcnt vmcnt(10)
	s_barrier
	s_waitcnt lgkmcnt(0)
	s_setprio 1
	s_waitcnt lgkmcnt(2)
	v_mfma_f32_16x16x128_f8f6f4 v[118:121], v[142:149], v[18:25], v[118:121]
	s_waitcnt lgkmcnt(0)
	v_mfma_f32_16x16x128_f8f6f4 v[110:113], v[150:157], v[18:25], v[110:113]
	v_mfma_f32_16x16x128_f8f6f4 v[102:105], v[142:149], v[26:33], v[102:105]
	v_mfma_f32_16x16x128_f8f6f4 v[94:97], v[150:157], v[26:33], v[158:161]
	v_mfma_f32_16x16x128_f8f6f4 v[86:89], v[142:149], v[34:41], v[162:165]
	v_mfma_f32_16x16x128_f8f6f4 v[78:81], v[150:157], v[34:41], v[166:169]
	v_mfma_f32_16x16x128_f8f6f4 v[70:73], v[142:149], v[42:49], v[170:173]
	v_mfma_f32_16x16x128_f8f6f4 v[18:21], v[150:157], v[42:49], v[174:177]
	s_setprio 0
	s_mov_b32 m0, s35
	s_barrier
	ds_read_b128 v[158:161], v138 offset:49152
	ds_read_b128 v[162:165], v138 offset:50176
	ds_read_b128 v[166:169], v138 offset:51200
	ds_read_b128 v[170:173], v138 offset:52224
	ds_read_b128 v[174:177], v138 offset:53248
	ds_read_b128 v[178:181], v138 offset:54272
	ds_read_b128 v[182:185], v138 offset:55296
	ds_read_b128 v[186:189], v138 offset:56320
	buffer_load_dwordx4 v1, s[44:47], s88 offen lds
	s_add_i32 s87, s87, 0x10080
	s_mov_b32 m0, s36
	s_nop 0
	buffer_load_dwordx4 v1, s[44:47], s87 offen lds
	s_barrier
	s_waitcnt lgkmcnt(0)
	s_setprio 1
	s_waitcnt lgkmcnt(6)
	v_mfma_f32_16x16x128_f8f6f4 v[62:65], v[2:9], v[158:165], v[62:65]
	v_mfma_f32_16x16x128_f8f6f4 v[58:61], v[10:17], v[158:165], v[58:61]
	s_waitcnt lgkmcnt(4)
	v_mfma_f32_16x16x128_f8f6f4 v[50:53], v[2:9], v[166:173], v[50:53]
	v_mfma_f32_16x16x128_f8f6f4 v[42:45], v[10:17], v[166:173], v[218:221]
	s_waitcnt lgkmcnt(2)
	v_mfma_f32_16x16x128_f8f6f4 v[34:37], v[2:9], v[174:181], v[222:225]
	v_mfma_f32_16x16x128_f8f6f4 v[26:29], v[10:17], v[174:181], v[226:229]
	s_waitcnt lgkmcnt(0)
	v_mfma_f32_16x16x128_f8f6f4 v[230:233], v[2:9], v[182:189], v[230:233]
	v_mfma_f32_16x16x128_f8f6f4 v[10:13], v[10:17], v[182:189], v[234:237]
	s_setprio 0
	s_barrier
	s_mov_b32 m0, s37
	s_add_i32 s33, s86, 0x2080
	buffer_load_dwordx4 v134, s[8:11], s33 offen lds
	s_add_i32 s86, s86, 0x22080
	s_mov_b32 m0, s38
	s_nop 0
	buffer_load_dwordx4 v134, s[8:11], s86 offen lds
	s_waitcnt vmcnt(6)
	s_barrier
	s_setprio 1
	v_mfma_f32_16x16x128_f8f6f4 v[54:57], v[142:149], v[158:165], v[54:57]
	v_mfma_f32_16x16x128_f8f6f4 v[46:49], v[150:157], v[158:165], v[238:241]
	v_mfma_f32_16x16x128_f8f6f4 v[38:41], v[142:149], v[166:173], v[242:245]
	v_mfma_f32_16x16x128_f8f6f4 v[30:33], v[150:157], v[166:173], v[246:249]
	v_mfma_f32_16x16x128_f8f6f4 v[22:25], v[142:149], v[174:181], v[250:253]
	v_mfma_f32_16x16x128_f8f6f4 v[14:17], v[150:157], v[174:181], v[130:133]
	v_mfma_f32_16x16x128_f8f6f4 v[6:9], v[142:149], v[182:189], v[66:69]
	v_mfma_f32_16x16x128_f8f6f4 v[2:5], v[150:157], v[182:189], v[190:193]
	s_setprio 0
	s_add_i32 s85, s85, 2
	s_addk_i32 s7, 0x100
	s_addk_i32 s84, 0x100
	s_cmp_gt_u32 s85, 5
	s_barrier
	s_cbranch_scc0 .LBB0_1724
	v_lshl_add_u32 v152, s79, 8, v135
	v_lshlrev_b32_e32 v153, 1, v136
	v_lshl_or_b32 v153, s78, 8, v153
	v_lshl_add_u32 v152, v152, 10, v153
	s_mov_b32 s78, s58
	s_mov_b32 s79, s59
	s_mov_b32 s84, s72
	s_mov_b32 s85, s73
	v_pk_mul_f32 v[126:127], v[126:127], 0.5 op_sel_hi:[1,0]
	v_pk_mul_f32 v[128:129], v[128:129], 0.5 op_sel_hi:[1,0]
	v_pk_mul_f32 v[122:123], v[122:123], 0.5 op_sel_hi:[1,0]
	v_pk_mul_f32 v[124:125], v[124:125], 0.5 op_sel_hi:[1,0]
	v_pk_mul_f32 v[118:119], v[118:119], 0.5 op_sel_hi:[1,0]
	v_pk_mul_f32 v[120:121], v[120:121], 0.5 op_sel_hi:[1,0]
	v_pk_mul_f32 v[110:111], v[110:111], 0.5 op_sel_hi:[1,0]
	v_pk_mul_f32 v[112:113], v[112:113], 0.5 op_sel_hi:[1,0]
	v_cvt_pk_fp8_f32 v144, v126, v127
	v_cvt_pk_fp8_f32 v145, v122, v123
	v_cvt_pk_fp8_f32 v146, v118, v119
	v_cvt_pk_fp8_f32 v147, v110, v111
	v_cvt_pk_fp8_f32 v144, v128, v129 op_sel:[0,0,1]
	v_cvt_pk_fp8_f32 v145, v124, v125 op_sel:[0,0,1]
	v_cvt_pk_fp8_f32 v146, v120, v121 op_sel:[0,0,1]
	v_cvt_pk_fp8_f32 v147, v112, v113 op_sel:[0,0,1]
	v_mov_b32_e32 v154, v152
	s_nop 0
	global_store_dwordx4 v154, v[144:147], s[68:69]
	s_mov_b32 s100, 1
	v_pk_mul_f32 v[114:115], v[114:115], 0.5 op_sel_hi:[1,0]
	v_pk_mul_f32 v[116:117], v[116:117], 0.5 op_sel_hi:[1,0]
	v_pk_mul_f32 v[106:107], v[106:107], 0.5 op_sel_hi:[1,0]
	v_pk_mul_f32 v[108:109], v[108:109], 0.5 op_sel_hi:[1,0]
	v_pk_mul_f32 v[102:103], v[102:103], 0.5 op_sel_hi:[1,0]
	v_pk_mul_f32 v[104:105], v[104:105], 0.5 op_sel_hi:[1,0]
	v_pk_mul_f32 v[94:95], v[94:95], 0.5 op_sel_hi:[1,0]
	v_pk_mul_f32 v[96:97], v[96:97], 0.5 op_sel_hi:[1,0]
	v_cvt_pk_fp8_f32 v148, v114, v115
	v_cvt_pk_fp8_f32 v149, v106, v107
	v_cvt_pk_fp8_f32 v150, v102, v103
	v_cvt_pk_fp8_f32 v151, v94, v95
	v_cvt_pk_fp8_f32 v148, v116, v117 op_sel:[0,0,1]
	v_cvt_pk_fp8_f32 v149, v108, v109 op_sel:[0,0,1]
	v_cvt_pk_fp8_f32 v150, v104, v105 op_sel:[0,0,1]
	v_cvt_pk_fp8_f32 v151, v96, v97 op_sel:[0,0,1]
	v_add_u32_e32 v155, 0x4000, v152
	s_nop 0
	global_store_dwordx4 v155, v[148:151], s[68:69]
	s_mov_b32 s100, 1
	v_pk_mul_f32 v[98:99], v[98:99], 0.5 op_sel_hi:[1,0]
	v_pk_mul_f32 v[100:101], v[100:101], 0.5 op_sel_hi:[1,0]
	v_pk_mul_f32 v[90:91], v[90:91], 0.5 op_sel_hi:[1,0]
	v_pk_mul_f32 v[92:93], v[92:93], 0.5 op_sel_hi:[1,0]
	v_pk_mul_f32 v[86:87], v[86:87], 0.5 op_sel_hi:[1,0]
	v_pk_mul_f32 v[88:89], v[88:89], 0.5 op_sel_hi:[1,0]
	v_pk_mul_f32 v[78:79], v[78:79], 0.5 op_sel_hi:[1,0]
	v_pk_mul_f32 v[80:81], v[80:81], 0.5 op_sel_hi:[1,0]
	v_cvt_pk_fp8_f32 v144, v98, v99
	v_cvt_pk_fp8_f32 v145, v90, v91
	v_cvt_pk_fp8_f32 v146, v86, v87
	v_cvt_pk_fp8_f32 v147, v78, v79
	v_cvt_pk_fp8_f32 v144, v100, v101 op_sel:[0,0,1]
	v_cvt_pk_fp8_f32 v145, v92, v93 op_sel:[0,0,1]
	v_cvt_pk_fp8_f32 v146, v88, v89 op_sel:[0,0,1]
	v_cvt_pk_fp8_f32 v147, v80, v81 op_sel:[0,0,1]
	v_add_u32_e32 v154, 0x8000, v152
	s_nop 0
	global_store_dwordx4 v154, v[144:147], s[68:69]
	s_mov_b32 s100, 1
	v_pk_mul_f32 v[82:83], v[82:83], 0.5 op_sel_hi:[1,0]
	v_pk_mul_f32 v[84:85], v[84:85], 0.5 op_sel_hi:[1,0]
	v_pk_mul_f32 v[74:75], v[74:75], 0.5 op_sel_hi:[1,0]
	v_pk_mul_f32 v[76:77], v[76:77], 0.5 op_sel_hi:[1,0]
	v_pk_mul_f32 v[70:71], v[70:71], 0.5 op_sel_hi:[1,0]
	v_pk_mul_f32 v[72:73], v[72:73], 0.5 op_sel_hi:[1,0]
	v_pk_mul_f32 v[18:19], v[18:19], 0.5 op_sel_hi:[1,0]
	v_pk_mul_f32 v[20:21], v[20:21], 0.5 op_sel_hi:[1,0]
	v_cvt_pk_fp8_f32 v148, v82, v83
	v_cvt_pk_fp8_f32 v149, v74, v75
	v_cvt_pk_fp8_f32 v150, v70, v71
	v_cvt_pk_fp8_f32 v151, v18, v19
	v_cvt_pk_fp8_f32 v148, v84, v85 op_sel:[0,0,1]
	v_cvt_pk_fp8_f32 v149, v76, v77 op_sel:[0,0,1]
	v_cvt_pk_fp8_f32 v150, v72, v73 op_sel:[0,0,1]
	v_cvt_pk_fp8_f32 v151, v20, v21 op_sel:[0,0,1]
	v_add_u32_e32 v155, 0xc000, v152
	s_nop 0
	global_store_dwordx4 v155, v[148:151], s[68:69]
	s_mov_b32 s100, 1
	v_pk_mul_f32 v[62:63], v[62:63], 0.5 op_sel_hi:[1,0]
	v_pk_mul_f32 v[64:65], v[64:65], 0.5 op_sel_hi:[1,0]
	v_pk_mul_f32 v[58:59], v[58:59], 0.5 op_sel_hi:[1,0]
	v_pk_mul_f32 v[60:61], v[60:61], 0.5 op_sel_hi:[1,0]
	v_pk_mul_f32 v[54:55], v[54:55], 0.5 op_sel_hi:[1,0]
	v_pk_mul_f32 v[56:57], v[56:57], 0.5 op_sel_hi:[1,0]
	v_pk_mul_f32 v[46:47], v[46:47], 0.5 op_sel_hi:[1,0]
	v_pk_mul_f32 v[48:49], v[48:49], 0.5 op_sel_hi:[1,0]
	v_cvt_pk_fp8_f32 v144, v62, v63
	v_cvt_pk_fp8_f32 v145, v58, v59
	v_cvt_pk_fp8_f32 v146, v54, v55
	v_cvt_pk_fp8_f32 v147, v46, v47
	v_cvt_pk_fp8_f32 v144, v64, v65 op_sel:[0,0,1]
	v_cvt_pk_fp8_f32 v145, v60, v61 op_sel:[0,0,1]
	v_cvt_pk_fp8_f32 v146, v56, v57 op_sel:[0,0,1]
	v_cvt_pk_fp8_f32 v147, v48, v49 op_sel:[0,0,1]
	v_add_u32_e32 v154, 0x20000, v152
	s_nop 0
	global_store_dwordx4 v154, v[144:147], s[68:69]
	s_mov_b32 s100, 1
	v_pk_mul_f32 v[50:51], v[50:51], 0.5 op_sel_hi:[1,0]
	v_pk_mul_f32 v[52:53], v[52:53], 0.5 op_sel_hi:[1,0]
	v_pk_mul_f32 v[42:43], v[42:43], 0.5 op_sel_hi:[1,0]
	v_pk_mul_f32 v[44:45], v[44:45], 0.5 op_sel_hi:[1,0]
	v_pk_mul_f32 v[38:39], v[38:39], 0.5 op_sel_hi:[1,0]
	v_pk_mul_f32 v[40:41], v[40:41], 0.5 op_sel_hi:[1,0]
	v_pk_mul_f32 v[30:31], v[30:31], 0.5 op_sel_hi:[1,0]
	v_pk_mul_f32 v[32:33], v[32:33], 0.5 op_sel_hi:[1,0]
	v_cvt_pk_fp8_f32 v148, v50, v51
	v_cvt_pk_fp8_f32 v149, v42, v43
	v_cvt_pk_fp8_f32 v150, v38, v39
	v_cvt_pk_fp8_f32 v151, v30, v31
	v_cvt_pk_fp8_f32 v148, v52, v53 op_sel:[0,0,1]
	v_cvt_pk_fp8_f32 v149, v44, v45 op_sel:[0,0,1]
	v_cvt_pk_fp8_f32 v150, v40, v41 op_sel:[0,0,1]
	v_cvt_pk_fp8_f32 v151, v32, v33 op_sel:[0,0,1]
	v_add_u32_e32 v155, 0x24000, v152
	s_nop 0
	global_store_dwordx4 v155, v[148:151], s[68:69]
	s_mov_b32 s100, 1
	v_pk_mul_f32 v[34:35], v[34:35], 0.5 op_sel_hi:[1,0]
	v_pk_mul_f32 v[36:37], v[36:37], 0.5 op_sel_hi:[1,0]
	v_pk_mul_f32 v[26:27], v[26:27], 0.5 op_sel_hi:[1,0]
	v_pk_mul_f32 v[28:29], v[28:29], 0.5 op_sel_hi:[1,0]
	v_pk_mul_f32 v[22:23], v[22:23], 0.5 op_sel_hi:[1,0]
	v_pk_mul_f32 v[24:25], v[24:25], 0.5 op_sel_hi:[1,0]
	v_pk_mul_f32 v[14:15], v[14:15], 0.5 op_sel_hi:[1,0]
	v_pk_mul_f32 v[16:17], v[16:17], 0.5 op_sel_hi:[1,0]
	v_cvt_pk_fp8_f32 v144, v34, v35
	v_cvt_pk_fp8_f32 v145, v26, v27
	v_cvt_pk_fp8_f32 v146, v22, v23
	v_cvt_pk_fp8_f32 v147, v14, v15
	v_cvt_pk_fp8_f32 v144, v36, v37 op_sel:[0,0,1]
	v_cvt_pk_fp8_f32 v145, v28, v29 op_sel:[0,0,1]
	v_cvt_pk_fp8_f32 v146, v24, v25 op_sel:[0,0,1]
	v_cvt_pk_fp8_f32 v147, v16, v17 op_sel:[0,0,1]
	v_add_u32_e32 v154, 0x28000, v152
	s_nop 0
	global_store_dwordx4 v154, v[144:147], s[68:69]
	s_mov_b32 s100, 1
	v_pk_mul_f32 v[230:231], v[230:231], 0.5 op_sel_hi:[1,0]
	v_pk_mul_f32 v[232:233], v[232:233], 0.5 op_sel_hi:[1,0]
	v_pk_mul_f32 v[10:11], v[10:11], 0.5 op_sel_hi:[1,0]
	v_pk_mul_f32 v[12:13], v[12:13], 0.5 op_sel_hi:[1,0]
	v_pk_mul_f32 v[6:7], v[6:7], 0.5 op_sel_hi:[1,0]
	v_pk_mul_f32 v[8:9], v[8:9], 0.5 op_sel_hi:[1,0]
	v_pk_mul_f32 v[2:3], v[2:3], 0.5 op_sel_hi:[1,0]
	v_pk_mul_f32 v[4:5], v[4:5], 0.5 op_sel_hi:[1,0]
	v_cvt_pk_fp8_f32 v148, v230, v231
	v_cvt_pk_fp8_f32 v149, v10, v11
	v_cvt_pk_fp8_f32 v150, v6, v7
	v_cvt_pk_fp8_f32 v151, v2, v3
	v_cvt_pk_fp8_f32 v148, v232, v233 op_sel:[0,0,1]
	v_cvt_pk_fp8_f32 v149, v12, v13 op_sel:[0,0,1]
	v_cvt_pk_fp8_f32 v150, v8, v9 op_sel:[0,0,1]
	v_cvt_pk_fp8_f32 v151, v4, v5 op_sel:[0,0,1]
	v_add_u32_e32 v155, 0x2c000, v152
	s_nop 0
	global_store_dwordx4 v155, v[148:151], s[68:69]
	s_mov_b32 s100, 1
	s_and_b64 vcc, exec, s[4:5]
	s_cbranch_vccz .LBB0_1719
	s_waitcnt vmcnt(0)
	s_cmpk_gt_u32 s3, 0xff
	s_cbranch_scc1 .LBB0_1728
	s_barrier

.LBB0_2497:
	s_ashr_i32 s5, s7, 3
	s_add_u32 s8, s52, 0x3db00000
	s_addc_u32 s7, s53, 0
	s_add_i32 s5, s6, s5
	s_ashr_i32 s6, s5, 31
	s_lshr_b32 s6, s6, 27
	v_bfe_i32 v4, v2, 27, 1
	s_add_i32 s6, s5, s6
	v_lshlrev_b32_e32 v1, 4, v2
	v_lshrrev_b32_e32 v4, 22, v4
	s_ashr_i32 s12, s6, 5
	s_andn2_b32 s6, s6, 31
	v_add_u32_e32 v4, v1, v4
	s_sub_i32 s5, s5, s6
	v_and_b32_e32 v4, 0xfffffc00, v4
	s_bfe_i32 s6, s5, 0x80000
	v_sub_u32_e32 v1, v1, v4
	s_bfe_u32 s6, s6, 0x3000c
	v_ashrrev_i32_e32 v3, 31, v2
	v_lshrrev_b32_e32 v4, 4, v1
	s_add_i32 s6, s5, s6
	v_lshrrev_b32_e32 v3, 26, v3
	v_bitop3_b32 v1, v4, v1, 32 bitop3:0x6c
	s_bfe_i32 s13, s6, 0x80000
	s_and_b32 s6, s6, 0xf8
	v_add_u32_e32 v3, v2, v3
	v_ashrrev_i32_e32 v5, 31, v1
	s_sub_i32 s5, s5, s6
	v_ashrrev_i32_e32 v3, 6, v3
	v_lshrrev_b32_e32 v5, 26, v5
	s_lshl_b32 s12, s12, 3
	s_sext_i32_i8 s5, s5
	v_lshlrev_b32_e32 v4, 3, v3
	v_add_u32_e32 v5, v1, v5
	s_add_i32 s78, s12, s5
	v_and_b32_e32 v4, -16, v4
	v_ashrrev_i32_e32 v6, 6, v5
	v_and_b32_e32 v5, 0xc0, v5
	s_ashr_i32 s5, s78, 31
	s_ashr_i32 s4, s3, 6
	v_add_u32_e32 v4, v6, v4
	v_sub_u32_e32 v1, v1, v5
	v_mov_b32_e32 v5, 1
	v_and_b32_e32 v6, 3, v6
	s_mov_b32 s9, 0x3fffe0
	s_lshr_b32 s5, s5, 28
	v_lshlrev_b32_e32 v3, 5, v3
	v_ashrrev_i16_sdwa v1, v5, sext(v1) dst_sel:DWORD dst_unused:UNUSED_PAD src0_sel:DWORD src1_sel:BYTE_0
	v_lshlrev_b32_e32 v5, 1, v4
	v_lshrrev_b32_e32 v7, 2, v4
	v_and_or_b32 v6, v4, s9, v6
	s_and_b32 s9, s7, 0xffff
	s_lshl_b32 s7, s4, 10
	s_sext_i32_i16 s13, s13
	s_add_i32 s5, s78, s5
	v_and_b32_e32 v3, 32, v3
	v_bfe_i32 v1, v1, 0, 16
	v_and_b32_e32 v5, 24, v5
	v_and_b32_e32 v7, 4, v7
	s_ashr_i32 s73, s13, 3
	s_lshl_b32 s5, s5, 16
	s_add_i32 s21, s7, 0
	s_mov_b32 s47, 0x20000
	s_brev_b32 s46, -2
	v_or3_b32 v5, v6, v7, v5
	v_add_lshl_u32 v3, v3, v1, 1
	s_and_b32 s5, s5, 0xfff00000
	s_lshl_b32 s6, s73, 18
	s_add_i32 s22, s21, 0x10000
	v_and_b32_e32 v254, 3, v4
	v_lshrrev_b32_e32 v5, 2, v4
	v_and_b32_e32 v5, 4, v5
	v_or_b32_e32 v254, v254, v5
	v_lshlrev_b32_e32 v5, 2, v4
	v_and_b32_e32 v5, 0x30, v5
	v_or_b32_e32 v254, v254, v5
	v_lshlrev_b32_e32 v5, 1, v4
	v_and_b32_e32 v5, 0x40, v5
	v_or_b32_e32 v254, v254, v5
	v_lshl_add_u32 v134, v254, 10, v3
	s_mov_b32 s10, s46
	s_mov_b32 s11, s47
	s_add_i32 s79, s5, s6
	s_mov_b32 m0, s22
	s_add_i32 s23, s21, 0x12000
	s_mov_b32 s100, 0
	buffer_load_dwordx4 v134, s[8:11], s79 offen lds
	s_or_b32 s5, s79, 0x20000
	s_mov_b32 m0, s23
	s_and_b32 s45, s71, 0xffff
	v_lshl_add_u32 v1, v4, 10, v3
	buffer_load_dwordx4 v134, s[8:11], s5 offen lds
	s_lshl_b32 s84, s78, 18
	s_mov_b32 m0, s21
	s_add_i32 s24, s21, 0x2000
	buffer_load_dwordx4 v1, s[44:47], s84 offen lds
	s_or_b32 s5, s84, 0x10000
	s_mov_b32 m0, s24
	s_add_i32 s25, s21, 0x14000
	buffer_load_dwordx4 v1, s[44:47], s5 offen lds
	s_or_b32 s5, s79, 0x2000
	s_mov_b32 m0, s25
	s_add_i32 s26, s21, 0x16000
	buffer_load_dwordx4 v134, s[8:11], s5 offen lds
	s_or_b32 s5, s79, 0x22000
	s_mov_b32 m0, s26
	s_add_i32 s27, s21, 0x4000
	buffer_load_dwordx4 v134, s[8:11], s5 offen lds
	s_or_b32 s5, s84, 0x20000
	s_mov_b32 m0, s27
	s_add_i32 s28, s21, 0x6000
	buffer_load_dwordx4 v1, s[44:47], s5 offen lds
	s_or_b32 s5, s84, 0x30000
	s_mov_b32 m0, s28
	s_mov_b32 s29, 0
	buffer_load_dwordx4 v1, s[44:47], s5 offen lds
	s_ashr_i32 s5, s3, 8
	s_cmp_lg_u32 s5, 1
	s_cbranch_scc1 .LBB0_2499
	s_barrier
.LBB0_2499:
	s_add_i32 s30, s21, 0x18000
	s_or_b32 s6, s79, 0x80
	s_mov_b32 s10, s46
	s_mov_b32 s11, s47
	s_mov_b32 m0, s30
	s_add_i32 s31, s21, 0x1a000
	s_waitcnt vmcnt(4)
	s_barrier
	buffer_load_dwordx4 v134, s[8:11], s6 offen lds
	s_or_b32 s6, s79, 0x20080
	s_mov_b32 m0, s31
	s_add_i32 s34, s21, 0x8000
	buffer_load_dwordx4 v134, s[8:11], s6 offen lds
	s_or_b32 s6, s84, 0x80
	s_mov_b32 m0, s34
	s_add_i32 s35, s21, 0xa000
	buffer_load_dwordx4 v1, s[44:47], s6 offen lds
	s_or_b32 s6, s84, 0x10080
	s_mov_b32 m0, s35
	s_add_i32 s36, s21, 0x1c000
	buffer_load_dwordx4 v1, s[44:47], s6 offen lds
	s_or_b32 s6, s79, 0x2080
	s_mov_b32 m0, s36
	s_add_i32 s37, s21, 0x1e000
	buffer_load_dwordx4 v134, s[8:11], s6 offen lds
	s_or_b32 s6, s79, 0x22080
	s_mov_b32 m0, s37
	v_and_b32_e32 v3, 15, v2
	buffer_load_dwordx4 v134, s[8:11], s6 offen lds
	v_lshrrev_b32_e32 v4, 1, v2
	s_and_b32 s4, s4, 3
	v_and_b32_e32 v4, 24, v4
	v_lshlrev_b32_e32 v5, 6, v3
	v_lshlrev_b32_e32 v2, 2, v2
	v_lshl_or_b32 v5, v4, 1, v5
	v_and_b32_e32 v2, 32, v2
	s_lshl_b32 s6, s5, 13
	s_lshl_b32 s7, s4, 12
	v_bitop3_b32 v6, v5, s6, v2 bitop3:0xde
	v_bitop3_b32 v2, v5, s7, v2 bitop3:0xde
	s_waitcnt vmcnt(6)
	v_add_u32_e32 v2, 0, v2
	s_add_i32 s38, s21, 0xc000
	v_lshl_or_b32 v135, s5, 6, v3
	s_add_i32 s39, s21, 0xe000
	s_ashr_i32 s41, s56, 31
	v_lshl_or_b32 v136, s4, 5, v4
	v_add_u32_e32 v137, 0x10000, v2
	v_add_u32_e32 v138, 0, v6
	v_add_u32_e32 v139, 0x14000, v2
	v_add_u32_e32 v140, 0x18000, v2
	v_add_u32_e32 v141, 0x1c000, v2
	s_mov_b64 s[12:13], 0x20000
	s_mov_b64 s[14:15], 0x24000
	s_mov_b32 s42, 0x24000
	s_mov_b64 s[16:17], 0x28000
	s_mov_b32 s43, 0x28000
	s_mov_b64 s[18:19], 0x2c000
	s_mov_b32 s49, 0x2c000
	s_barrier

.LBB0_2508:
	s_lshl_b32 s72, s58, 18
	s_and_b64 s[6:7], s[6:7], exec
	v_mov_b32_e32 v2, 0
	s_cselect_b32 s6, s72, s84
	s_add_i32 s7, s84, 0x30080
	s_addk_i32 s79, 0x100
	s_mov_b32 s84, -2
	ds_read_b128 v[142:145], v137
	ds_read_b128 v[146:149], v137 offset:1024
	ds_read_b128 v[150:153], v137 offset:2048
	ds_read_b128 v[154:157], v137 offset:3072
	s_add_i32 s10, s7, 0xfffd0080
	s_cmp_eq_u32 s84, 4
	s_cselect_b32 s86, s6, s10
	s_cselect_b32 s85, s59, s79
	s_or_b32 s87, s86, 0x80
	s_add_i32 s10, s7, 0xffff0000
	s_mov_b32 m0, s38
	ds_read_b128 v[158:161], v138
	ds_read_b128 v[162:165], v138 offset:1024
	ds_read_b128 v[166:169], v138 offset:2048
	ds_read_b128 v[170:173], v138 offset:3072
	ds_read_b128 v[174:177], v138 offset:4096
	ds_read_b128 v[178:181], v138 offset:5120
	ds_read_b128 v[182:185], v138 offset:6144
	ds_read_b128 v[186:189], v138 offset:7168
	buffer_load_dwordx4 v1, s[44:47], s10 offen lds
	s_mov_b32 m0, s39
	s_nop 0
	buffer_load_dwordx4 v1, s[44:47], s7 offen lds
	s_waitcnt lgkmcnt(8)
	s_barrier
	s_waitcnt lgkmcnt(0)
	s_setprio 1
	s_waitcnt lgkmcnt(4)
	v_mfma_f32_16x16x128_f8f6f4 v[114:117], v[142:149], v[166:173], 0
	v_mfma_f32_16x16x128_f8f6f4 v[106:109], v[150:157], v[166:173], 0
	s_waitcnt lgkmcnt(2)
	v_mfma_f32_16x16x128_f8f6f4 v[98:101], v[142:149], v[174:181], 0
	v_mfma_f32_16x16x128_f8f6f4 v[198:201], v[142:149], v[158:165], 0
	v_mfma_f32_16x16x128_f8f6f4 v[202:205], v[150:157], v[158:165], 0
	v_mfma_f32_16x16x128_f8f6f4 v[206:209], v[150:157], v[174:181], 0
	s_waitcnt lgkmcnt(0)
	v_mfma_f32_16x16x128_f8f6f4 v[210:213], v[142:149], v[182:189], 0
	v_mfma_f32_16x16x128_f8f6f4 v[214:217], v[150:157], v[182:189], 0
	s_setprio 0
	s_barrier
	s_mov_b32 m0, s22
	s_mov_b32 s10, s46
	s_mov_b32 s11, s47
	ds_read_b128 v[122:125], v139
	ds_read_b128 v[126:129], v139 offset:1024
	ds_read_b128 v[190:193], v139 offset:2048
	ds_read_b128 v[194:197], v139 offset:3072
	buffer_load_dwordx4 v134, s[8:11], s85 offen lds
	s_add_i32 s33, s85, 0x20000
	s_mov_b32 m0, s23
	s_nop 0
	buffer_load_dwordx4 v134, s[8:11], s33 offen lds
	s_barrier
	s_waitcnt lgkmcnt(0)
	s_setprio 1
	s_waitcnt lgkmcnt(2)
	v_mfma_f32_16x16x128_f8f6f4 v[118:121], v[122:129], v[158:165], 0
	s_waitcnt lgkmcnt(0)
	v_mfma_f32_16x16x128_f8f6f4 v[110:113], v[190:197], v[158:165], 0
	v_mfma_f32_16x16x128_f8f6f4 v[102:105], v[122:129], v[166:173], 0
	v_mfma_f32_16x16x128_f8f6f4 v[158:161], v[190:197], v[166:173], 0
	v_mfma_f32_16x16x128_f8f6f4 v[162:165], v[122:129], v[174:181], 0
	v_mfma_f32_16x16x128_f8f6f4 v[166:169], v[190:197], v[174:181], 0
	v_mfma_f32_16x16x128_f8f6f4 v[170:173], v[122:129], v[182:189], 0
	v_mfma_f32_16x16x128_f8f6f4 v[174:177], v[190:197], v[182:189], 0
	s_setprio 0
	s_mov_b32 m0, s21
	s_barrier
	ds_read_b128 v[66:69], v138 offset:16384
	s_nop 1
	ds_read_b128 v[70:73], v138 offset:17408
	ds_read_b128 v[74:77], v138 offset:18432
	ds_read_b128 v[78:81], v138 offset:19456
	ds_read_b128 v[82:85], v138 offset:20480
	ds_read_b128 v[86:89], v138 offset:21504
	ds_read_b128 v[90:93], v138 offset:22528
	ds_read_b128 v[94:97], v138 offset:23552
	buffer_load_dwordx4 v1, s[44:47], s86 offen lds
	s_add_i32 s33, s86, 0x10000
	s_mov_b32 m0, s24
	s_nop 0
	buffer_load_dwordx4 v1, s[44:47], s33 offen lds
	s_barrier
	s_waitcnt lgkmcnt(0)
	s_setprio 1
	s_waitcnt lgkmcnt(6)
	v_mfma_f32_16x16x128_f8f6f4 v[62:65], v[142:149], v[66:73], 0
	v_mfma_f32_16x16x128_f8f6f4 v[58:61], v[150:157], v[66:73], 0
	s_waitcnt lgkmcnt(4)
	v_mfma_f32_16x16x128_f8f6f4 v[50:53], v[142:149], v[74:81], 0
	s_waitcnt lgkmcnt(0)
	v_mfma_f32_16x16x128_f8f6f4 v[230:233], v[142:149], v[90:97], 0
	v_mfma_f32_16x16x128_f8f6f4 v[218:221], v[150:157], v[74:81], 0
	v_mfma_f32_16x16x128_f8f6f4 v[222:225], v[142:149], v[82:89], 0
	v_mfma_f32_16x16x128_f8f6f4 v[226:229], v[150:157], v[82:89], 0
	v_mfma_f32_16x16x128_f8f6f4 v[234:237], v[150:157], v[90:97], 0
	s_setprio 0
	s_barrier
	s_mov_b32 m0, s25
	s_add_i32 s33, s85, 0x2000
	buffer_load_dwordx4 v134, s[8:11], s33 offen lds
	s_add_i32 s33, s85, 0x22000
	s_mov_b32 m0, s26
	s_nop 0
	buffer_load_dwordx4 v134, s[8:11], s33 offen lds
	s_cmp_eq_u32 s100, 0
	s_cbranch_scc1 .Lfw_12_a_p
	s_waitcnt vmcnt(16)
	s_mov_b32 s100, 0
	s_branch .Lfw_12_b_p

.Lfw_12_b_p:
	s_barrier
	s_setprio 1
	v_mfma_f32_16x16x128_f8f6f4 v[54:57], v[122:129], v[66:73], 0
	v_mfma_f32_16x16x128_f8f6f4 v[238:241], v[190:197], v[66:73], 0
	v_mfma_f32_16x16x128_f8f6f4 v[242:245], v[122:129], v[74:81], 0
	v_mfma_f32_16x16x128_f8f6f4 v[246:249], v[190:197], v[74:81], 0
	v_mfma_f32_16x16x128_f8f6f4 v[250:253], v[122:129], v[82:89], 0
	v_mfma_f32_16x16x128_f8f6f4 v[130:133], v[190:197], v[82:89], 0
	v_mfma_f32_16x16x128_f8f6f4 v[66:69], v[122:129], v[90:97], 0
	v_mfma_f32_16x16x128_f8f6f4 v[190:193], v[190:197], v[90:97], 0
	s_setprio 0
	s_barrier
	s_nop 4
	ds_read_b128 v[2:5], v140
	ds_read_b128 v[6:9], v140 offset:1024
	ds_read_b128 v[10:13], v140 offset:2048
	ds_read_b128 v[14:17], v140 offset:3072
	s_mov_b32 m0, s27
	s_add_i32 s33, s86, 0x20000
	ds_read_b128 v[18:21], v138 offset:32768
	ds_read_b128 v[22:25], v138 offset:33792
	ds_read_b128 v[26:29], v138 offset:34816
	ds_read_b128 v[30:33], v138 offset:35840
	ds_read_b128 v[34:37], v138 offset:36864
	ds_read_b128 v[38:41], v138 offset:37888
	ds_read_b128 v[42:45], v138 offset:38912
	ds_read_b128 v[46:49], v138 offset:39936
	buffer_load_dwordx4 v1, s[44:47], s33 offen lds
	s_add_i32 s33, s86, 0x30000
	s_mov_b32 m0, s28
	s_nop 0
	buffer_load_dwordx4 v1, s[44:47], s33 offen lds
	s_waitcnt lgkmcnt(8)
	s_barrier
	s_waitcnt lgkmcnt(0)
	s_setprio 1
	s_waitcnt lgkmcnt(6)
	v_mfma_f32_16x16x128_f8f6f4 v[126:129], v[2:9], v[18:25], v[198:201]
	v_mfma_f32_16x16x128_f8f6f4 v[122:125], v[10:17], v[18:25], v[202:205]
	s_waitcnt lgkmcnt(4)
	v_mfma_f32_16x16x128_f8f6f4 v[114:117], v[2:9], v[26:33], v[114:117]
	v_mfma_f32_16x16x128_f8f6f4 v[106:109], v[10:17], v[26:33], v[106:109]
	s_waitcnt lgkmcnt(2)
	v_mfma_f32_16x16x128_f8f6f4 v[98:101], v[2:9], v[34:41], v[98:101]
	v_mfma_f32_16x16x128_f8f6f4 v[90:93], v[10:17], v[34:41], v[206:209]
	s_waitcnt lgkmcnt(0)
	v_mfma_f32_16x16x128_f8f6f4 v[82:85], v[2:9], v[42:49], v[210:213]
	v_mfma_f32_16x16x128_f8f6f4 v[74:77], v[10:17], v[42:49], v[214:217]
	s_setprio 0
	s_barrier
	s_mov_b32 m0, s30
	s_add_i32 s33, s85, 0x80
	ds_read_b128 v[142:145], v141
	ds_read_b128 v[146:149], v141 offset:1024
	ds_read_b128 v[150:153], v141 offset:2048
	ds_read_b128 v[154:157], v141 offset:3072
	buffer_load_dwordx4 v134, s[8:11], s33 offen lds
	s_add_i32 s33, s85, 0x20080
	s_mov_b32 m0, s31
	s_nop 0
	buffer_load_dwordx4 v134, s[8:11], s33 offen lds
	s_waitcnt vmcnt(10)
	s_barrier
	s_waitcnt lgkmcnt(0)
	s_setprio 1
	s_waitcnt lgkmcnt(2)
	v_mfma_f32_16x16x128_f8f6f4 v[118:121], v[142:149], v[18:25], v[118:121]
	s_waitcnt lgkmcnt(0)
	v_mfma_f32_16x16x128_f8f6f4 v[110:113], v[150:157], v[18:25], v[110:113]
	v_mfma_f32_16x16x128_f8f6f4 v[102:105], v[142:149], v[26:33], v[102:105]
	v_mfma_f32_16x16x128_f8f6f4 v[94:97], v[150:157], v[26:33], v[158:161]
	v_mfma_f32_16x16x128_f8f6f4 v[86:89], v[142:149], v[34:41], v[162:165]
	v_mfma_f32_16x16x128_f8f6f4 v[78:81], v[150:157], v[34:41], v[166:169]
	v_mfma_f32_16x16x128_f8f6f4 v[70:73], v[142:149], v[42:49], v[170:173]
	v_mfma_f32_16x16x128_f8f6f4 v[18:21], v[150:157], v[42:49], v[174:177]
	s_setprio 0
	s_mov_b32 m0, s34
	s_barrier
	ds_read_b128 v[158:161], v138 offset:49152
	ds_read_b128 v[162:165], v138 offset:50176
	ds_read_b128 v[166:169], v138 offset:51200
	ds_read_b128 v[170:173], v138 offset:52224
	ds_read_b128 v[174:177], v138 offset:53248
	ds_read_b128 v[178:181], v138 offset:54272
	ds_read_b128 v[182:185], v138 offset:55296
	ds_read_b128 v[186:189], v138 offset:56320
	buffer_load_dwordx4 v1, s[44:47], s87 offen lds
	s_add_i32 s86, s86, 0x10080
	s_mov_b32 m0, s35
	s_nop 0
	buffer_load_dwordx4 v1, s[44:47], s86 offen lds
	s_barrier
	s_waitcnt lgkmcnt(0)
	s_setprio 1
	s_waitcnt lgkmcnt(6)
	v_mfma_f32_16x16x128_f8f6f4 v[62:65], v[2:9], v[158:165], v[62:65]
	v_mfma_f32_16x16x128_f8f6f4 v[58:61], v[10:17], v[158:165], v[58:61]
	s_waitcnt lgkmcnt(4)
	v_mfma_f32_16x16x128_f8f6f4 v[50:53], v[2:9], v[166:173], v[50:53]
	v_mfma_f32_16x16x128_f8f6f4 v[42:45], v[10:17], v[166:173], v[218:221]
	s_waitcnt lgkmcnt(2)
	v_mfma_f32_16x16x128_f8f6f4 v[34:37], v[2:9], v[174:181], v[222:225]
	v_mfma_f32_16x16x128_f8f6f4 v[26:29], v[10:17], v[174:181], v[226:229]
	s_waitcnt lgkmcnt(0)
	v_mfma_f32_16x16x128_f8f6f4 v[230:233], v[2:9], v[182:189], v[230:233]
	v_mfma_f32_16x16x128_f8f6f4 v[10:13], v[10:17], v[182:189], v[234:237]
	s_setprio 0
	s_barrier
	s_mov_b32 m0, s36
	s_add_i32 s33, s85, 0x2080
	buffer_load_dwordx4 v134, s[8:11], s33 offen lds
	s_add_i32 s85, s85, 0x22080
	s_mov_b32 m0, s37
	s_nop 0
	buffer_load_dwordx4 v134, s[8:11], s85 offen lds
	s_waitcnt vmcnt(6)
	s_barrier
	s_setprio 1
	v_mfma_f32_16x16x128_f8f6f4 v[54:57], v[142:149], v[158:165], v[54:57]
	v_mfma_f32_16x16x128_f8f6f4 v[46:49], v[150:157], v[158:165], v[238:241]
	v_mfma_f32_16x16x128_f8f6f4 v[38:41], v[142:149], v[166:173], v[242:245]
	v_mfma_f32_16x16x128_f8f6f4 v[30:33], v[150:157], v[166:173], v[246:249]
	v_mfma_f32_16x16x128_f8f6f4 v[22:25], v[142:149], v[174:181], v[250:253]
	v_mfma_f32_16x16x128_f8f6f4 v[14:17], v[150:157], v[174:181], v[130:133]
	v_mfma_f32_16x16x128_f8f6f4 v[6:9], v[142:149], v[182:189], v[66:69]
	v_mfma_f32_16x16x128_f8f6f4 v[2:5], v[150:157], v[182:189], v[190:193]
	s_setprio 0
	s_add_i32 s84, s84, 2
	s_addk_i32 s7, 0x100
	s_addk_i32 s79, 0x100
	s_cmp_gt_u32 s84, 5
	s_barrier
.LBB0_2509:
	ds_read_b128 v[142:145], v137
	ds_read_b128 v[146:149], v137 offset:1024
	ds_read_b128 v[150:153], v137 offset:2048
	ds_read_b128 v[154:157], v137 offset:3072
	s_add_i32 s10, s7, 0xfffd0080
	s_cmp_eq_u32 s84, 4
	s_cselect_b32 s86, s6, s10
	s_cselect_b32 s85, s59, s79
	s_or_b32 s87, s86, 0x80
	s_add_i32 s10, s7, 0xffff0000
	s_mov_b32 m0, s38
	ds_read_b128 v[158:161], v138
	ds_read_b128 v[162:165], v138 offset:1024
	ds_read_b128 v[166:169], v138 offset:2048
	ds_read_b128 v[170:173], v138 offset:3072
	ds_read_b128 v[174:177], v138 offset:4096
	ds_read_b128 v[178:181], v138 offset:5120
	ds_read_b128 v[182:185], v138 offset:6144
	ds_read_b128 v[186:189], v138 offset:7168
	buffer_load_dwordx4 v1, s[44:47], s10 offen lds
	s_mov_b32 m0, s39
	s_nop 0
	buffer_load_dwordx4 v1, s[44:47], s7 offen lds
	s_waitcnt lgkmcnt(8)
	s_barrier
	s_waitcnt lgkmcnt(0)
	s_setprio 1
	s_waitcnt lgkmcnt(4)
	v_mfma_f32_16x16x128_f8f6f4 v[114:117], v[142:149], v[166:173], v[114:117]
	v_mfma_f32_16x16x128_f8f6f4 v[106:109], v[150:157], v[166:173], v[106:109]
	s_waitcnt lgkmcnt(2)
	v_mfma_f32_16x16x128_f8f6f4 v[98:101], v[142:149], v[174:181], v[98:101]
	v_mfma_f32_16x16x128_f8f6f4 v[198:201], v[142:149], v[158:165], v[126:129]
	v_mfma_f32_16x16x128_f8f6f4 v[202:205], v[150:157], v[158:165], v[122:125]
	v_mfma_f32_16x16x128_f8f6f4 v[206:209], v[150:157], v[174:181], v[90:93]
	s_waitcnt lgkmcnt(0)
	v_mfma_f32_16x16x128_f8f6f4 v[210:213], v[142:149], v[182:189], v[82:85]
	v_mfma_f32_16x16x128_f8f6f4 v[214:217], v[150:157], v[182:189], v[74:77]
	s_setprio 0
	s_barrier
	s_mov_b32 m0, s22
	s_mov_b32 s10, s46
	s_mov_b32 s11, s47
	ds_read_b128 v[122:125], v139
	ds_read_b128 v[126:129], v139 offset:1024
	ds_read_b128 v[190:193], v139 offset:2048
	ds_read_b128 v[194:197], v139 offset:3072
	buffer_load_dwordx4 v134, s[8:11], s85 offen lds
	s_add_i32 s33, s85, 0x20000
	s_mov_b32 m0, s23
	s_nop 0
	buffer_load_dwordx4 v134, s[8:11], s33 offen lds
	s_barrier
	s_waitcnt lgkmcnt(0)
	s_setprio 1
	s_waitcnt lgkmcnt(2)
	v_mfma_f32_16x16x128_f8f6f4 v[118:121], v[122:129], v[158:165], v[118:121]
	s_waitcnt lgkmcnt(0)
	v_mfma_f32_16x16x128_f8f6f4 v[110:113], v[190:197], v[158:165], v[110:113]
	v_mfma_f32_16x16x128_f8f6f4 v[102:105], v[122:129], v[166:173], v[102:105]
	v_mfma_f32_16x16x128_f8f6f4 v[158:161], v[190:197], v[166:173], v[94:97]
	v_mfma_f32_16x16x128_f8f6f4 v[162:165], v[122:129], v[174:181], v[86:89]
	v_mfma_f32_16x16x128_f8f6f4 v[166:169], v[190:197], v[174:181], v[78:81]
	v_mfma_f32_16x16x128_f8f6f4 v[170:173], v[122:129], v[182:189], v[70:73]
	v_mfma_f32_16x16x128_f8f6f4 v[174:177], v[190:197], v[182:189], v[18:21]
	s_setprio 0
	s_mov_b32 m0, s21
	s_barrier
	ds_read_b128 v[66:69], v138 offset:16384
	s_nop 1
	ds_read_b128 v[70:73], v138 offset:17408
	ds_read_b128 v[74:77], v138 offset:18432
	ds_read_b128 v[78:81], v138 offset:19456
	ds_read_b128 v[82:85], v138 offset:20480
	ds_read_b128 v[86:89], v138 offset:21504
	ds_read_b128 v[90:93], v138 offset:22528
	ds_read_b128 v[94:97], v138 offset:23552
	buffer_load_dwordx4 v1, s[44:47], s86 offen lds
	s_add_i32 s33, s86, 0x10000
	s_mov_b32 m0, s24
	s_nop 0
	buffer_load_dwordx4 v1, s[44:47], s33 offen lds
	s_barrier
	s_waitcnt lgkmcnt(0)
	s_setprio 1
	s_waitcnt lgkmcnt(6)
	v_mfma_f32_16x16x128_f8f6f4 v[62:65], v[142:149], v[66:73], v[62:65]
	v_mfma_f32_16x16x128_f8f6f4 v[58:61], v[150:157], v[66:73], v[58:61]
	s_waitcnt lgkmcnt(4)
	v_mfma_f32_16x16x128_f8f6f4 v[50:53], v[142:149], v[74:81], v[50:53]
	s_waitcnt lgkmcnt(0)
	v_mfma_f32_16x16x128_f8f6f4 v[230:233], v[142:149], v[90:97], v[230:233]
	v_mfma_f32_16x16x128_f8f6f4 v[218:221], v[150:157], v[74:81], v[42:45]
	v_mfma_f32_16x16x128_f8f6f4 v[222:225], v[142:149], v[82:89], v[34:37]
	v_mfma_f32_16x16x128_f8f6f4 v[226:229], v[150:157], v[82:89], v[26:29]
	v_mfma_f32_16x16x128_f8f6f4 v[234:237], v[150:157], v[90:97], v[10:13]
	s_setprio 0
	s_barrier
	s_mov_b32 m0, s25
	s_add_i32 s33, s85, 0x2000
	buffer_load_dwordx4 v134, s[8:11], s33 offen lds
	s_add_i32 s33, s85, 0x22000
	s_mov_b32 m0, s26
	s_nop 0
	buffer_load_dwordx4 v134, s[8:11], s33 offen lds
	s_cmp_eq_u32 s100, 0
	s_cbranch_scc1 .Lfw_12_a
	s_waitcnt vmcnt(16)
	s_mov_b32 s100, 0
	s_branch .Lfw_12_b

.Lfw_12_b:
	s_barrier
	s_setprio 1
	v_mfma_f32_16x16x128_f8f6f4 v[54:57], v[122:129], v[66:73], v[54:57]
	v_mfma_f32_16x16x128_f8f6f4 v[238:241], v[190:197], v[66:73], v[46:49]
	v_mfma_f32_16x16x128_f8f6f4 v[242:245], v[122:129], v[74:81], v[38:41]
	v_mfma_f32_16x16x128_f8f6f4 v[246:249], v[190:197], v[74:81], v[30:33]
	v_mfma_f32_16x16x128_f8f6f4 v[250:253], v[122:129], v[82:89], v[22:25]
	v_mfma_f32_16x16x128_f8f6f4 v[130:133], v[190:197], v[82:89], v[14:17]
	v_mfma_f32_16x16x128_f8f6f4 v[66:69], v[122:129], v[90:97], v[6:9]
	v_mfma_f32_16x16x128_f8f6f4 v[190:193], v[190:197], v[90:97], v[2:5]
	s_setprio 0
	s_barrier
	s_nop 4
	ds_read_b128 v[2:5], v140
	ds_read_b128 v[6:9], v140 offset:1024
	ds_read_b128 v[10:13], v140 offset:2048
	ds_read_b128 v[14:17], v140 offset:3072
	s_mov_b32 m0, s27
	s_add_i32 s33, s86, 0x20000
	ds_read_b128 v[18:21], v138 offset:32768
	ds_read_b128 v[22:25], v138 offset:33792
	ds_read_b128 v[26:29], v138 offset:34816
	ds_read_b128 v[30:33], v138 offset:35840
	ds_read_b128 v[34:37], v138 offset:36864
	ds_read_b128 v[38:41], v138 offset:37888
	ds_read_b128 v[42:45], v138 offset:38912
	ds_read_b128 v[46:49], v138 offset:39936
	buffer_load_dwordx4 v1, s[44:47], s33 offen lds
	s_add_i32 s33, s86, 0x30000
	s_mov_b32 m0, s28
	s_nop 0
	buffer_load_dwordx4 v1, s[44:47], s33 offen lds
	s_waitcnt lgkmcnt(8)
	s_barrier
	s_waitcnt lgkmcnt(0)
	s_setprio 1
	s_waitcnt lgkmcnt(6)
	v_mfma_f32_16x16x128_f8f6f4 v[126:129], v[2:9], v[18:25], v[198:201]
	v_mfma_f32_16x16x128_f8f6f4 v[122:125], v[10:17], v[18:25], v[202:205]
	s_waitcnt lgkmcnt(4)
	v_mfma_f32_16x16x128_f8f6f4 v[114:117], v[2:9], v[26:33], v[114:117]
	v_mfma_f32_16x16x128_f8f6f4 v[106:109], v[10:17], v[26:33], v[106:109]
	s_waitcnt lgkmcnt(2)
	v_mfma_f32_16x16x128_f8f6f4 v[98:101], v[2:9], v[34:41], v[98:101]
	v_mfma_f32_16x16x128_f8f6f4 v[90:93], v[10:17], v[34:41], v[206:209]
	s_waitcnt lgkmcnt(0)
	v_mfma_f32_16x16x128_f8f6f4 v[82:85], v[2:9], v[42:49], v[210:213]
	v_mfma_f32_16x16x128_f8f6f4 v[74:77], v[10:17], v[42:49], v[214:217]
	s_setprio 0
	s_barrier
	s_mov_b32 m0, s30
	s_add_i32 s33, s85, 0x80
	ds_read_b128 v[142:145], v141
	ds_read_b128 v[146:149], v141 offset:1024
	ds_read_b128 v[150:153], v141 offset:2048
	ds_read_b128 v[154:157], v141 offset:3072
	buffer_load_dwordx4 v134, s[8:11], s33 offen lds
	s_add_i32 s33, s85, 0x20080
	s_mov_b32 m0, s31
	s_nop 0
	buffer_load_dwordx4 v134, s[8:11], s33 offen lds
	s_waitcnt vmcnt(10)
	s_barrier
	s_waitcnt lgkmcnt(0)
	s_setprio 1
	s_waitcnt lgkmcnt(2)
	v_mfma_f32_16x16x128_f8f6f4 v[118:121], v[142:149], v[18:25], v[118:121]
	s_waitcnt lgkmcnt(0)
	v_mfma_f32_16x16x128_f8f6f4 v[110:113], v[150:157], v[18:25], v[110:113]
	v_mfma_f32_16x16x128_f8f6f4 v[102:105], v[142:149], v[26:33], v[102:105]
	v_mfma_f32_16x16x128_f8f6f4 v[94:97], v[150:157], v[26:33], v[158:161]
	v_mfma_f32_16x16x128_f8f6f4 v[86:89], v[142:149], v[34:41], v[162:165]
	v_mfma_f32_16x16x128_f8f6f4 v[78:81], v[150:157], v[34:41], v[166:169]
	v_mfma_f32_16x16x128_f8f6f4 v[70:73], v[142:149], v[42:49], v[170:173]
	v_mfma_f32_16x16x128_f8f6f4 v[18:21], v[150:157], v[42:49], v[174:177]
	s_setprio 0
	s_mov_b32 m0, s34
	s_barrier
	ds_read_b128 v[158:161], v138 offset:49152
	ds_read_b128 v[162:165], v138 offset:50176
	ds_read_b128 v[166:169], v138 offset:51200
	ds_read_b128 v[170:173], v138 offset:52224
	ds_read_b128 v[174:177], v138 offset:53248
	ds_read_b128 v[178:181], v138 offset:54272
	ds_read_b128 v[182:185], v138 offset:55296
	ds_read_b128 v[186:189], v138 offset:56320
	buffer_load_dwordx4 v1, s[44:47], s87 offen lds
	s_add_i32 s86, s86, 0x10080
	s_mov_b32 m0, s35
	s_nop 0
	buffer_load_dwordx4 v1, s[44:47], s86 offen lds
	s_barrier
	s_waitcnt lgkmcnt(0)
	s_setprio 1
	s_waitcnt lgkmcnt(6)
	v_mfma_f32_16x16x128_f8f6f4 v[62:65], v[2:9], v[158:165], v[62:65]
	v_mfma_f32_16x16x128_f8f6f4 v[58:61], v[10:17], v[158:165], v[58:61]
	s_waitcnt lgkmcnt(4)
	v_mfma_f32_16x16x128_f8f6f4 v[50:53], v[2:9], v[166:173], v[50:53]
	v_mfma_f32_16x16x128_f8f6f4 v[42:45], v[10:17], v[166:173], v[218:221]
	s_waitcnt lgkmcnt(2)
	v_mfma_f32_16x16x128_f8f6f4 v[34:37], v[2:9], v[174:181], v[222:225]
	v_mfma_f32_16x16x128_f8f6f4 v[26:29], v[10:17], v[174:181], v[226:229]
	s_waitcnt lgkmcnt(0)
	v_mfma_f32_16x16x128_f8f6f4 v[230:233], v[2:9], v[182:189], v[230:233]
	v_mfma_f32_16x16x128_f8f6f4 v[10:13], v[10:17], v[182:189], v[234:237]
	s_setprio 0
	s_barrier
	s_mov_b32 m0, s36
	s_add_i32 s33, s85, 0x2080
	buffer_load_dwordx4 v134, s[8:11], s33 offen lds
	s_add_i32 s85, s85, 0x22080
	s_mov_b32 m0, s37
	s_nop 0
	buffer_load_dwordx4 v134, s[8:11], s85 offen lds
	s_waitcnt vmcnt(6)
	s_barrier
	s_setprio 1
	v_mfma_f32_16x16x128_f8f6f4 v[54:57], v[142:149], v[158:165], v[54:57]
	v_mfma_f32_16x16x128_f8f6f4 v[46:49], v[150:157], v[158:165], v[238:241]
	v_mfma_f32_16x16x128_f8f6f4 v[38:41], v[142:149], v[166:173], v[242:245]
	v_mfma_f32_16x16x128_f8f6f4 v[30:33], v[150:157], v[166:173], v[246:249]
	v_mfma_f32_16x16x128_f8f6f4 v[22:25], v[142:149], v[174:181], v[250:253]
	v_mfma_f32_16x16x128_f8f6f4 v[14:17], v[150:157], v[174:181], v[130:133]
	v_mfma_f32_16x16x128_f8f6f4 v[6:9], v[142:149], v[182:189], v[66:69]
	v_mfma_f32_16x16x128_f8f6f4 v[2:5], v[150:157], v[182:189], v[190:193]
	s_setprio 0
	s_add_i32 s84, s84, 2
	s_addk_i32 s7, 0x100
	s_addk_i32 s79, 0x100
	s_cmp_gt_u32 s84, 5
	s_barrier
	s_cbranch_scc0 .LBB0_2509
	v_lshl_add_u32 v152, s78, 8, v135
	v_lshlrev_b32_e32 v153, 1, v136
	v_lshl_or_b32 v153, s73, 8, v153
	v_lshl_add_u32 v152, v152, 10, v153
	s_mov_b32 s73, s57
	s_mov_b32 s78, s58
	s_mov_b32 s79, s59
	s_mov_b32 s84, s72
	v_pk_mul_f32 v[126:127], v[126:127], 0.5 op_sel_hi:[1,0]
	v_pk_mul_f32 v[128:129], v[128:129], 0.5 op_sel_hi:[1,0]
	v_pk_mul_f32 v[122:123], v[122:123], 0.5 op_sel_hi:[1,0]
	v_pk_mul_f32 v[124:125], v[124:125], 0.5 op_sel_hi:[1,0]
	v_pk_mul_f32 v[118:119], v[118:119], 0.5 op_sel_hi:[1,0]
	v_pk_mul_f32 v[120:121], v[120:121], 0.5 op_sel_hi:[1,0]
	v_pk_mul_f32 v[110:111], v[110:111], 0.5 op_sel_hi:[1,0]
	v_pk_mul_f32 v[112:113], v[112:113], 0.5 op_sel_hi:[1,0]
	v_cvt_pk_fp8_f32 v144, v126, v127
	v_cvt_pk_fp8_f32 v145, v122, v123
	v_cvt_pk_fp8_f32 v146, v118, v119
	v_cvt_pk_fp8_f32 v147, v110, v111
	v_cvt_pk_fp8_f32 v144, v128, v129 op_sel:[0,0,1]
	v_cvt_pk_fp8_f32 v145, v124, v125 op_sel:[0,0,1]
	v_cvt_pk_fp8_f32 v146, v120, v121 op_sel:[0,0,1]
	v_cvt_pk_fp8_f32 v147, v112, v113 op_sel:[0,0,1]
	v_mov_b32_e32 v154, v152
	s_nop 0
	global_store_dwordx4 v154, v[144:147], s[68:69]
	s_mov_b32 s100, 1
	v_pk_mul_f32 v[114:115], v[114:115], 0.5 op_sel_hi:[1,0]
	v_pk_mul_f32 v[116:117], v[116:117], 0.5 op_sel_hi:[1,0]
	v_pk_mul_f32 v[106:107], v[106:107], 0.5 op_sel_hi:[1,0]
	v_pk_mul_f32 v[108:109], v[108:109], 0.5 op_sel_hi:[1,0]
	v_pk_mul_f32 v[102:103], v[102:103], 0.5 op_sel_hi:[1,0]
	v_pk_mul_f32 v[104:105], v[104:105], 0.5 op_sel_hi:[1,0]
	v_pk_mul_f32 v[94:95], v[94:95], 0.5 op_sel_hi:[1,0]
	v_pk_mul_f32 v[96:97], v[96:97], 0.5 op_sel_hi:[1,0]
	v_cvt_pk_fp8_f32 v148, v114, v115
	v_cvt_pk_fp8_f32 v149, v106, v107
	v_cvt_pk_fp8_f32 v150, v102, v103
	v_cvt_pk_fp8_f32 v151, v94, v95
	v_cvt_pk_fp8_f32 v148, v116, v117 op_sel:[0,0,1]
	v_cvt_pk_fp8_f32 v149, v108, v109 op_sel:[0,0,1]
	v_cvt_pk_fp8_f32 v150, v104, v105 op_sel:[0,0,1]
	v_cvt_pk_fp8_f32 v151, v96, v97 op_sel:[0,0,1]
	v_add_u32_e32 v155, 0x4000, v152
	s_nop 0
	global_store_dwordx4 v155, v[148:151], s[68:69]
	s_mov_b32 s100, 1
	v_pk_mul_f32 v[98:99], v[98:99], 0.5 op_sel_hi:[1,0]
	v_pk_mul_f32 v[100:101], v[100:101], 0.5 op_sel_hi:[1,0]
	v_pk_mul_f32 v[90:91], v[90:91], 0.5 op_sel_hi:[1,0]
	v_pk_mul_f32 v[92:93], v[92:93], 0.5 op_sel_hi:[1,0]
	v_pk_mul_f32 v[86:87], v[86:87], 0.5 op_sel_hi:[1,0]
	v_pk_mul_f32 v[88:89], v[88:89], 0.5 op_sel_hi:[1,0]
	v_pk_mul_f32 v[78:79], v[78:79], 0.5 op_sel_hi:[1,0]
	v_pk_mul_f32 v[80:81], v[80:81], 0.5 op_sel_hi:[1,0]
	v_cvt_pk_fp8_f32 v144, v98, v99
	v_cvt_pk_fp8_f32 v145, v90, v91
	v_cvt_pk_fp8_f32 v146, v86, v87
	v_cvt_pk_fp8_f32 v147, v78, v79
	v_cvt_pk_fp8_f32 v144, v100, v101 op_sel:[0,0,1]
	v_cvt_pk_fp8_f32 v145, v92, v93 op_sel:[0,0,1]
	v_cvt_pk_fp8_f32 v146, v88, v89 op_sel:[0,0,1]
	v_cvt_pk_fp8_f32 v147, v80, v81 op_sel:[0,0,1]
	v_add_u32_e32 v154, 0x8000, v152
	s_nop 0
	global_store_dwordx4 v154, v[144:147], s[68:69]
	s_mov_b32 s100, 1
	v_pk_mul_f32 v[82:83], v[82:83], 0.5 op_sel_hi:[1,0]
	v_pk_mul_f32 v[84:85], v[84:85], 0.5 op_sel_hi:[1,0]
	v_pk_mul_f32 v[74:75], v[74:75], 0.5 op_sel_hi:[1,0]
	v_pk_mul_f32 v[76:77], v[76:77], 0.5 op_sel_hi:[1,0]
	v_pk_mul_f32 v[70:71], v[70:71], 0.5 op_sel_hi:[1,0]
	v_pk_mul_f32 v[72:73], v[72:73], 0.5 op_sel_hi:[1,0]
	v_pk_mul_f32 v[18:19], v[18:19], 0.5 op_sel_hi:[1,0]
	v_pk_mul_f32 v[20:21], v[20:21], 0.5 op_sel_hi:[1,0]
	v_cvt_pk_fp8_f32 v148, v82, v83
	v_cvt_pk_fp8_f32 v149, v74, v75
	v_cvt_pk_fp8_f32 v150, v70, v71
	v_cvt_pk_fp8_f32 v151, v18, v19
	v_cvt_pk_fp8_f32 v148, v84, v85 op_sel:[0,0,1]
	v_cvt_pk_fp8_f32 v149, v76, v77 op_sel:[0,0,1]
	v_cvt_pk_fp8_f32 v150, v72, v73 op_sel:[0,0,1]
	v_cvt_pk_fp8_f32 v151, v20, v21 op_sel:[0,0,1]
	v_add_u32_e32 v155, 0xc000, v152
	s_nop 0
	global_store_dwordx4 v155, v[148:151], s[68:69]
	s_mov_b32 s100, 1
	v_pk_mul_f32 v[62:63], v[62:63], 0.5 op_sel_hi:[1,0]
	v_pk_mul_f32 v[64:65], v[64:65], 0.5 op_sel_hi:[1,0]
	v_pk_mul_f32 v[58:59], v[58:59], 0.5 op_sel_hi:[1,0]
	v_pk_mul_f32 v[60:61], v[60:61], 0.5 op_sel_hi:[1,0]
	v_pk_mul_f32 v[54:55], v[54:55], 0.5 op_sel_hi:[1,0]
	v_pk_mul_f32 v[56:57], v[56:57], 0.5 op_sel_hi:[1,0]
	v_pk_mul_f32 v[46:47], v[46:47], 0.5 op_sel_hi:[1,0]
	v_pk_mul_f32 v[48:49], v[48:49], 0.5 op_sel_hi:[1,0]
	v_cvt_pk_fp8_f32 v144, v62, v63
	v_cvt_pk_fp8_f32 v145, v58, v59
	v_cvt_pk_fp8_f32 v146, v54, v55
	v_cvt_pk_fp8_f32 v147, v46, v47
	v_cvt_pk_fp8_f32 v144, v64, v65 op_sel:[0,0,1]
	v_cvt_pk_fp8_f32 v145, v60, v61 op_sel:[0,0,1]
	v_cvt_pk_fp8_f32 v146, v56, v57 op_sel:[0,0,1]
	v_cvt_pk_fp8_f32 v147, v48, v49 op_sel:[0,0,1]
	v_add_u32_e32 v154, 0x20000, v152
	s_nop 0
	global_store_dwordx4 v154, v[144:147], s[68:69]
	s_mov_b32 s100, 1
	v_pk_mul_f32 v[50:51], v[50:51], 0.5 op_sel_hi:[1,0]
	v_pk_mul_f32 v[52:53], v[52:53], 0.5 op_sel_hi:[1,0]
	v_pk_mul_f32 v[42:43], v[42:43], 0.5 op_sel_hi:[1,0]
	v_pk_mul_f32 v[44:45], v[44:45], 0.5 op_sel_hi:[1,0]
	v_pk_mul_f32 v[38:39], v[38:39], 0.5 op_sel_hi:[1,0]
	v_pk_mul_f32 v[40:41], v[40:41], 0.5 op_sel_hi:[1,0]
	v_pk_mul_f32 v[30:31], v[30:31], 0.5 op_sel_hi:[1,0]
	v_pk_mul_f32 v[32:33], v[32:33], 0.5 op_sel_hi:[1,0]
	v_cvt_pk_fp8_f32 v148, v50, v51
	v_cvt_pk_fp8_f32 v149, v42, v43
	v_cvt_pk_fp8_f32 v150, v38, v39
	v_cvt_pk_fp8_f32 v151, v30, v31
	v_cvt_pk_fp8_f32 v148, v52, v53 op_sel:[0,0,1]
	v_cvt_pk_fp8_f32 v149, v44, v45 op_sel:[0,0,1]
	v_cvt_pk_fp8_f32 v150, v40, v41 op_sel:[0,0,1]
	v_cvt_pk_fp8_f32 v151, v32, v33 op_sel:[0,0,1]
	v_add_u32_e32 v155, 0x24000, v152
	s_nop 0
	global_store_dwordx4 v155, v[148:151], s[68:69]
	s_mov_b32 s100, 1
	v_pk_mul_f32 v[34:35], v[34:35], 0.5 op_sel_hi:[1,0]
	v_pk_mul_f32 v[36:37], v[36:37], 0.5 op_sel_hi:[1,0]
	v_pk_mul_f32 v[26:27], v[26:27], 0.5 op_sel_hi:[1,0]
	v_pk_mul_f32 v[28:29], v[28:29], 0.5 op_sel_hi:[1,0]
	v_pk_mul_f32 v[22:23], v[22:23], 0.5 op_sel_hi:[1,0]
	v_pk_mul_f32 v[24:25], v[24:25], 0.5 op_sel_hi:[1,0]
	v_pk_mul_f32 v[14:15], v[14:15], 0.5 op_sel_hi:[1,0]
	v_pk_mul_f32 v[16:17], v[16:17], 0.5 op_sel_hi:[1,0]
	v_cvt_pk_fp8_f32 v144, v34, v35
	v_cvt_pk_fp8_f32 v145, v26, v27
	v_cvt_pk_fp8_f32 v146, v22, v23
	v_cvt_pk_fp8_f32 v147, v14, v15
	v_cvt_pk_fp8_f32 v144, v36, v37 op_sel:[0,0,1]
	v_cvt_pk_fp8_f32 v145, v28, v29 op_sel:[0,0,1]
	v_cvt_pk_fp8_f32 v146, v24, v25 op_sel:[0,0,1]
	v_cvt_pk_fp8_f32 v147, v16, v17 op_sel:[0,0,1]
	v_add_u32_e32 v154, 0x28000, v152
	s_nop 0
	global_store_dwordx4 v154, v[144:147], s[68:69]
	s_mov_b32 s100, 1
	v_pk_mul_f32 v[230:231], v[230:231], 0.5 op_sel_hi:[1,0]
	v_pk_mul_f32 v[232:233], v[232:233], 0.5 op_sel_hi:[1,0]
	v_pk_mul_f32 v[10:11], v[10:11], 0.5 op_sel_hi:[1,0]
	v_pk_mul_f32 v[12:13], v[12:13], 0.5 op_sel_hi:[1,0]
	v_pk_mul_f32 v[6:7], v[6:7], 0.5 op_sel_hi:[1,0]
	v_pk_mul_f32 v[8:9], v[8:9], 0.5 op_sel_hi:[1,0]
	v_pk_mul_f32 v[2:3], v[2:3], 0.5 op_sel_hi:[1,0]
	v_pk_mul_f32 v[4:5], v[4:5], 0.5 op_sel_hi:[1,0]
	v_cvt_pk_fp8_f32 v148, v230, v231
	v_cvt_pk_fp8_f32 v149, v10, v11
	v_cvt_pk_fp8_f32 v150, v6, v7
	v_cvt_pk_fp8_f32 v151, v2, v3
	v_cvt_pk_fp8_f32 v148, v232, v233 op_sel:[0,0,1]
	v_cvt_pk_fp8_f32 v149, v12, v13 op_sel:[0,0,1]
	v_cvt_pk_fp8_f32 v150, v8, v9 op_sel:[0,0,1]
	v_cvt_pk_fp8_f32 v151, v4, v5 op_sel:[0,0,1]
	v_add_u32_e32 v155, 0x2c000, v152
	s_nop 0
	global_store_dwordx4 v155, v[148:151], s[68:69]
	s_mov_b32 s100, 1
	s_and_b64 vcc, exec, s[4:5]
	s_cbranch_vccz .LBB0_2500
	s_waitcnt vmcnt(0)
	s_cmpk_gt_u32 s3, 0xff
	s_cbranch_scc1 .LBB0_2513
	s_barrier

.LBB0_3173:
	s_add_u32 s8, s52, 0x6b00000
	s_addc_u32 s7, s53, 0
	s_add_i32 s5, s6, s5
	s_ashr_i32 s6, s5, 31
	s_lshr_b32 s6, s6, 27
	v_bfe_i32 v5, v2, 27, 1
	s_add_i32 s6, s5, s6
	v_lshlrev_b32_e32 v3, 4, v2
	v_lshrrev_b32_e32 v5, 22, v5
	s_ashr_i32 s12, s6, 5
	s_and_b32 s6, s6, 0xffe0
	v_add_u32_e32 v5, v3, v5
	s_sub_i32 s5, s5, s6
	v_and_b32_e32 v5, 0xfffffc00, v5
	s_bfe_i32 s6, s5, 0x80000
	v_sub_u32_e32 v3, v3, v5
	s_bfe_u32 s6, s6, 0x3000c
	v_ashrrev_i32_e32 v4, 31, v2
	v_lshrrev_b32_e32 v5, 4, v3
	s_add_i32 s6, s5, s6
	v_lshrrev_b32_e32 v4, 26, v4
	v_bitop3_b32 v3, v5, v3, 32 bitop3:0x6c
	s_bfe_i32 s13, s6, 0x80000
	s_and_b32 s6, s6, 0xf8
	v_add_u32_e32 v4, v2, v4
	v_ashrrev_i32_e32 v6, 31, v3
	s_sub_i32 s5, s5, s6
	v_ashrrev_i32_e32 v4, 6, v4
	v_lshrrev_b32_e32 v6, 26, v6
	s_lshl_b32 s12, s12, 3
	s_sext_i32_i8 s5, s5
	v_lshlrev_b32_e32 v5, 3, v4
	v_add_u32_e32 v6, v3, v6
	s_add_i32 s70, s12, s5
	v_and_b32_e32 v5, -16, v5
	v_ashrrev_i32_e32 v7, 6, v6
	v_and_b32_e32 v6, 0xc0, v6
	s_ashr_i32 s5, s70, 31
	s_ashr_i32 s4, s3, 6
	v_add_u32_e32 v5, v7, v5
	v_sub_u32_e32 v3, v3, v6
	v_mov_b32_e32 v6, 1
	v_and_b32_e32 v7, 3, v7
	s_mov_b32 s9, 0x3fffe0
	s_lshr_b32 s5, s5, 28
	v_lshlrev_b32_e32 v4, 5, v4
	v_ashrrev_i16_sdwa v3, v6, sext(v3) dst_sel:DWORD dst_unused:UNUSED_PAD src0_sel:DWORD src1_sel:BYTE_0
	v_lshlrev_b32_e32 v6, 1, v5
	v_lshrrev_b32_e32 v8, 2, v5
	v_and_or_b32 v7, v5, s9, v7
	s_and_b32 s9, s7, 0xffff
	s_lshl_b32 s7, s4, 10
	s_sext_i32_i16 s13, s13
	s_add_i32 s5, s70, s5
	v_and_b32_e32 v4, 32, v4
	v_bfe_i32 v3, v3, 0, 16
	v_and_b32_e32 v6, 24, v6
	v_and_b32_e32 v8, 4, v8
	s_ashr_i32 s59, s13, 3
	s_lshl_b32 s5, s5, 16
	s_add_i32 s21, s7, 0
	s_mov_b32 s47, 0x20000
	s_brev_b32 s46, -2
	v_or3_b32 v6, v7, v8, v6
	v_add_lshl_u32 v3, v4, v3, 1
	s_and_b32 s5, s5, 0xfff00000
	s_lshl_b32 s6, s59, 18
	s_add_i32 s22, s21, 0x10000
	s_and_b32 s45, s71, 0xffff
	v_and_b32_e32 v254, 3, v5
	v_lshrrev_b32_e32 v6, 2, v5
	v_and_b32_e32 v6, 4, v6
	v_or_b32_e32 v254, v254, v6
	v_lshlrev_b32_e32 v6, 2, v5
	v_and_b32_e32 v6, 0x30, v6
	v_or_b32_e32 v254, v254, v6
	v_lshlrev_b32_e32 v6, 1, v5
	v_and_b32_e32 v6, 0x40, v6
	v_or_b32_e32 v254, v254, v6
	v_lshl_add_u32 v135, v254, 10, v3
	s_mov_b32 s10, s46
	s_mov_b32 s11, s47
	s_add_i32 s71, s5, s6
	s_mov_b32 m0, s22
	s_add_i32 s23, s21, 0x12000
	s_mov_b32 s100, 0
	buffer_load_dwordx4 v135, s[8:11], s71 offen lds
	s_or_b32 s5, s71, 0x20000
	s_mov_b32 m0, s23
	v_lshl_add_u32 v134, v5, 10, v3
	buffer_load_dwordx4 v135, s[8:11], s5 offen lds
	s_lshl_b32 s72, s70, 18
	s_mov_b32 m0, s21
	s_add_i32 s24, s21, 0x2000
	buffer_load_dwordx4 v134, s[44:47], s72 offen lds
	s_or_b32 s5, s72, 0x10000
	s_mov_b32 m0, s24
	s_add_i32 s25, s21, 0x14000
	buffer_load_dwordx4 v134, s[44:47], s5 offen lds
	s_or_b32 s5, s71, 0x2000
	s_mov_b32 m0, s25
	s_add_i32 s26, s21, 0x16000
	buffer_load_dwordx4 v135, s[8:11], s5 offen lds
	s_or_b32 s5, s71, 0x22000
	s_mov_b32 m0, s26
	s_add_i32 s27, s21, 0x4000
	buffer_load_dwordx4 v135, s[8:11], s5 offen lds
	s_or_b32 s5, s72, 0x20000
	s_mov_b32 m0, s27
	s_add_i32 s28, s21, 0x6000
	buffer_load_dwordx4 v134, s[44:47], s5 offen lds
	s_or_b32 s5, s72, 0x30000
	s_mov_b32 m0, s28
	s_mov_b32 s29, 0
	buffer_load_dwordx4 v134, s[44:47], s5 offen lds
	s_ashr_i32 s5, s3, 8
	s_cmp_lg_u32 s5, 1
	s_cbranch_scc1 .LBB0_3175
	s_barrier
.LBB0_3175:
	s_add_i32 s30, s21, 0x18000
	s_or_b32 s6, s71, 0x80
	s_mov_b32 s10, s46
	s_mov_b32 s11, s47
	s_mov_b32 m0, s30
	s_add_i32 s31, s21, 0x1a000
	s_waitcnt vmcnt(4)
	s_barrier
	buffer_load_dwordx4 v135, s[8:11], s6 offen lds
	s_or_b32 s6, s71, 0x20080
	s_mov_b32 m0, s31
	s_add_i32 s34, s21, 0x8000
	buffer_load_dwordx4 v135, s[8:11], s6 offen lds
	s_or_b32 s6, s72, 0x80
	s_mov_b32 m0, s34
	s_add_i32 s35, s21, 0xa000
	buffer_load_dwordx4 v134, s[44:47], s6 offen lds
	s_or_b32 s6, s72, 0x10080
	s_mov_b32 m0, s35
	s_add_i32 s36, s21, 0x1c000
	buffer_load_dwordx4 v134, s[44:47], s6 offen lds
	s_or_b32 s6, s71, 0x2080
	s_mov_b32 m0, s36
	s_add_i32 s37, s21, 0x1e000
	buffer_load_dwordx4 v135, s[8:11], s6 offen lds
	s_or_b32 s6, s71, 0x22080
	s_mov_b32 m0, s37
	v_and_b32_e32 v3, 15, v2
	buffer_load_dwordx4 v135, s[8:11], s6 offen lds
	v_lshrrev_b32_e32 v4, 1, v2
	s_and_b32 s4, s4, 3
	v_and_b32_e32 v4, 24, v4
	v_lshlrev_b32_e32 v5, 6, v3
	v_lshlrev_b32_e32 v2, 2, v2
	v_lshl_or_b32 v5, v4, 1, v5
	v_and_b32_e32 v2, 32, v2
	s_lshl_b32 s6, s5, 13
	s_lshl_b32 s7, s4, 12
	v_bitop3_b32 v6, v5, s6, v2 bitop3:0xde
	v_bitop3_b32 v2, v5, s7, v2 bitop3:0xde
	s_waitcnt vmcnt(6)
	v_add_u32_e32 v2, 0, v2
	s_add_i32 s38, s21, 0xc000
	v_lshl_or_b32 v136, s5, 6, v3
	s_add_i32 s39, s21, 0xe000
	s_ashr_i32 s40, s56, 31
	v_lshl_or_b32 v137, s4, 5, v4
	v_add_u32_e32 v138, 0x10000, v2
	v_add_u32_e32 v139, 0, v6
	v_add_u32_e32 v254, 0x14000, v2
	v_add_u32_e32 v252, 0x18000, v2
	v_add_u32_e32 v253, 0x1c000, v2
	s_mov_b64 s[12:13], 0x20000
	s_mov_b64 s[14:15], 0x24000
	s_mov_b32 s41, 0x24000
	s_mov_b64 s[16:17], 0x28000
	s_mov_b32 s42, 0x28000
	s_mov_b64 s[18:19], 0x2c000
	s_mov_b32 s43, 0x2c000
	s_barrier

.LBB0_3184:
	s_lshl_b32 s58, s51, 18
	s_and_b64 s[6:7], s[6:7], exec
	v_mov_b32_e32 v2, 0
	s_cselect_b32 s6, s58, s72
	s_add_i32 s7, s72, 0x30080
	s_addk_i32 s71, 0x100
	s_mov_b32 s72, -2
	ds_read_b128 v[144:147], v138
	ds_read_b128 v[148:151], v138 offset:1024
	ds_read_b128 v[152:155], v138 offset:2048
	ds_read_b128 v[156:159], v138 offset:3072
	s_add_i32 s10, s7, 0xfffd0080
	s_cmp_eq_u32 s72, 4
	s_cselect_b32 s74, s6, s10
	s_cselect_b32 s73, s57, s71
	s_or_b32 s75, s74, 0x80
	s_add_i32 s10, s7, 0xffff0000
	s_mov_b32 m0, s38
	ds_read_b128 v[160:163], v139
	ds_read_b128 v[164:167], v139 offset:1024
	ds_read_b128 v[168:171], v139 offset:2048
	ds_read_b128 v[172:175], v139 offset:3072
	ds_read_b128 v[176:179], v139 offset:4096
	ds_read_b128 v[180:183], v139 offset:5120
	ds_read_b128 v[184:187], v139 offset:6144
	ds_read_b128 v[188:191], v139 offset:7168
	buffer_load_dwordx4 v134, s[44:47], s10 offen lds
	s_mov_b32 m0, s39
	s_nop 0
	buffer_load_dwordx4 v134, s[44:47], s7 offen lds
	s_waitcnt lgkmcnt(8)
	s_barrier
	s_waitcnt lgkmcnt(0)
	s_setprio 1
	s_waitcnt lgkmcnt(4)
	v_mfma_f32_16x16x128_f8f6f4 v[114:117], v[144:151], v[168:175], 0
	v_mfma_f32_16x16x128_f8f6f4 v[106:109], v[152:159], v[168:175], 0
	s_waitcnt lgkmcnt(2)
	v_mfma_f32_16x16x128_f8f6f4 v[98:101], v[144:151], v[176:183], 0
	v_mfma_f32_16x16x128_f8f6f4 v[200:203], v[144:151], v[160:167], 0
	v_mfma_f32_16x16x128_f8f6f4 v[204:207], v[152:159], v[160:167], 0
	v_mfma_f32_16x16x128_f8f6f4 v[208:211], v[152:159], v[176:183], 0
	s_waitcnt lgkmcnt(0)
	v_mfma_f32_16x16x128_f8f6f4 v[212:215], v[144:151], v[184:191], 0
	v_mfma_f32_16x16x128_f8f6f4 v[216:219], v[152:159], v[184:191], 0
	s_setprio 0
	s_barrier
	s_mov_b32 m0, s22
	s_mov_b32 s10, s46
	s_mov_b32 s11, s47
	ds_read_b128 v[122:125], v254
	ds_read_b128 v[126:129], v254 offset:1024
	ds_read_b128 v[192:195], v254 offset:2048
	ds_read_b128 v[196:199], v254 offset:3072
	buffer_load_dwordx4 v135, s[8:11], s73 offen lds
	s_add_i32 s33, s73, 0x20000
	s_mov_b32 m0, s23
	s_nop 0
	buffer_load_dwordx4 v135, s[8:11], s33 offen lds
	s_barrier
	s_waitcnt lgkmcnt(0)
	s_setprio 1
	s_waitcnt lgkmcnt(2)
	v_mfma_f32_16x16x128_f8f6f4 v[118:121], v[122:129], v[160:167], 0
	s_waitcnt lgkmcnt(0)
	v_mfma_f32_16x16x128_f8f6f4 v[110:113], v[192:199], v[160:167], 0
	v_mfma_f32_16x16x128_f8f6f4 v[102:105], v[122:129], v[168:175], 0
	v_mfma_f32_16x16x128_f8f6f4 v[160:163], v[192:199], v[168:175], 0
	v_mfma_f32_16x16x128_f8f6f4 v[164:167], v[122:129], v[176:183], 0
	v_mfma_f32_16x16x128_f8f6f4 v[168:171], v[192:199], v[176:183], 0
	v_mfma_f32_16x16x128_f8f6f4 v[172:175], v[122:129], v[184:191], 0
	v_mfma_f32_16x16x128_f8f6f4 v[176:179], v[192:199], v[184:191], 0
	s_setprio 0
	s_mov_b32 m0, s21
	s_barrier
	ds_read_b128 v[66:69], v139 offset:16384
	s_nop 1
	ds_read_b128 v[70:73], v139 offset:17408
	ds_read_b128 v[74:77], v139 offset:18432
	ds_read_b128 v[78:81], v139 offset:19456
	ds_read_b128 v[82:85], v139 offset:20480
	ds_read_b128 v[86:89], v139 offset:21504
	ds_read_b128 v[90:93], v139 offset:22528
	ds_read_b128 v[94:97], v139 offset:23552
	buffer_load_dwordx4 v134, s[44:47], s74 offen lds
	s_add_i32 s33, s74, 0x10000
	s_mov_b32 m0, s24
	s_nop 0
	buffer_load_dwordx4 v134, s[44:47], s33 offen lds
	s_barrier
	s_waitcnt lgkmcnt(0)
	s_setprio 1
	s_waitcnt lgkmcnt(6)
	v_mfma_f32_16x16x128_f8f6f4 v[62:65], v[144:151], v[66:73], 0
	v_mfma_f32_16x16x128_f8f6f4 v[58:61], v[152:159], v[66:73], 0
	s_waitcnt lgkmcnt(4)
	v_mfma_f32_16x16x128_f8f6f4 v[50:53], v[144:151], v[74:81], 0
	s_waitcnt lgkmcnt(0)
	v_mfma_f32_16x16x128_f8f6f4 v[232:235], v[144:151], v[90:97], 0
	v_mfma_f32_16x16x128_f8f6f4 v[220:223], v[152:159], v[74:81], 0
	v_mfma_f32_16x16x128_f8f6f4 v[224:227], v[144:151], v[82:89], 0
	v_mfma_f32_16x16x128_f8f6f4 v[228:231], v[152:159], v[82:89], 0
	v_mfma_f32_16x16x128_f8f6f4 v[236:239], v[152:159], v[90:97], 0
	s_setprio 0
	s_barrier
	s_mov_b32 m0, s25
	s_add_i32 s33, s73, 0x2000
	buffer_load_dwordx4 v135, s[8:11], s33 offen lds
	s_add_i32 s33, s73, 0x22000
	s_mov_b32 m0, s26
	s_nop 0
	buffer_load_dwordx4 v135, s[8:11], s33 offen lds
	s_cmp_eq_u32 s100, 0
	s_cbranch_scc1 .Lfw_16_a_p
	s_waitcnt vmcnt(16)
	s_mov_b32 s100, 0
	s_branch .Lfw_16_b_p

.Lfw_16_b_p:
	s_barrier
	s_setprio 1
	v_mfma_f32_16x16x128_f8f6f4 v[54:57], v[122:129], v[66:73], 0
	v_mfma_f32_16x16x128_f8f6f4 v[240:243], v[192:199], v[66:73], 0
	v_mfma_f32_16x16x128_f8f6f4 v[244:247], v[122:129], v[74:81], 0
	v_mfma_f32_16x16x128_f8f6f4 v[248:251], v[192:199], v[74:81], 0
	v_mfma_f32_16x16x128_f8f6f4 v[130:133], v[122:129], v[82:89], 0
	v_mfma_f32_16x16x128_f8f6f4 v[140:143], v[192:199], v[82:89], 0
	v_mfma_f32_16x16x128_f8f6f4 v[66:69], v[122:129], v[90:97], 0
	v_mfma_f32_16x16x128_f8f6f4 v[192:195], v[192:199], v[90:97], 0
	s_setprio 0
	s_barrier
	s_nop 4
	ds_read_b128 v[2:5], v252
	ds_read_b128 v[6:9], v252 offset:1024
	ds_read_b128 v[10:13], v252 offset:2048
	ds_read_b128 v[14:17], v252 offset:3072
	s_mov_b32 m0, s27
	s_add_i32 s33, s74, 0x20000
	ds_read_b128 v[18:21], v139 offset:32768
	ds_read_b128 v[22:25], v139 offset:33792
	ds_read_b128 v[26:29], v139 offset:34816
	ds_read_b128 v[30:33], v139 offset:35840
	ds_read_b128 v[34:37], v139 offset:36864
	ds_read_b128 v[38:41], v139 offset:37888
	ds_read_b128 v[42:45], v139 offset:38912
	ds_read_b128 v[46:49], v139 offset:39936
	buffer_load_dwordx4 v134, s[44:47], s33 offen lds
	s_add_i32 s33, s74, 0x30000
	s_mov_b32 m0, s28
	s_nop 0
	buffer_load_dwordx4 v134, s[44:47], s33 offen lds
	s_waitcnt lgkmcnt(8)
	s_barrier
	s_waitcnt lgkmcnt(0)
	s_setprio 1
	s_waitcnt lgkmcnt(6)
	v_mfma_f32_16x16x128_f8f6f4 v[126:129], v[2:9], v[18:25], v[200:203]
	v_mfma_f32_16x16x128_f8f6f4 v[122:125], v[10:17], v[18:25], v[204:207]
	s_waitcnt lgkmcnt(4)
	v_mfma_f32_16x16x128_f8f6f4 v[114:117], v[2:9], v[26:33], v[114:117]
	v_mfma_f32_16x16x128_f8f6f4 v[106:109], v[10:17], v[26:33], v[106:109]
	s_waitcnt lgkmcnt(2)
	v_mfma_f32_16x16x128_f8f6f4 v[98:101], v[2:9], v[34:41], v[98:101]
	v_mfma_f32_16x16x128_f8f6f4 v[90:93], v[10:17], v[34:41], v[208:211]
	s_waitcnt lgkmcnt(0)
	v_mfma_f32_16x16x128_f8f6f4 v[82:85], v[2:9], v[42:49], v[212:215]
	v_mfma_f32_16x16x128_f8f6f4 v[74:77], v[10:17], v[42:49], v[216:219]
	s_setprio 0
	s_barrier
	s_mov_b32 m0, s30
	s_add_i32 s33, s73, 0x80
	ds_read_b128 v[144:147], v253
	ds_read_b128 v[148:151], v253 offset:1024
	ds_read_b128 v[152:155], v253 offset:2048
	ds_read_b128 v[156:159], v253 offset:3072
	buffer_load_dwordx4 v135, s[8:11], s33 offen lds
	s_add_i32 s33, s73, 0x20080
	s_mov_b32 m0, s31
	s_nop 0
	buffer_load_dwordx4 v135, s[8:11], s33 offen lds
	s_waitcnt vmcnt(10)
	s_barrier
	s_waitcnt lgkmcnt(0)
	s_setprio 1
	s_waitcnt lgkmcnt(2)
	v_mfma_f32_16x16x128_f8f6f4 v[118:121], v[144:151], v[18:25], v[118:121]
	s_waitcnt lgkmcnt(0)
	v_mfma_f32_16x16x128_f8f6f4 v[110:113], v[152:159], v[18:25], v[110:113]
	v_mfma_f32_16x16x128_f8f6f4 v[102:105], v[144:151], v[26:33], v[102:105]
	v_mfma_f32_16x16x128_f8f6f4 v[94:97], v[152:159], v[26:33], v[160:163]
	v_mfma_f32_16x16x128_f8f6f4 v[86:89], v[144:151], v[34:41], v[164:167]
	v_mfma_f32_16x16x128_f8f6f4 v[78:81], v[152:159], v[34:41], v[168:171]
	v_mfma_f32_16x16x128_f8f6f4 v[70:73], v[144:151], v[42:49], v[172:175]
	v_mfma_f32_16x16x128_f8f6f4 v[18:21], v[152:159], v[42:49], v[176:179]
	s_setprio 0
	s_mov_b32 m0, s34
	s_barrier
	ds_read_b128 v[160:163], v139 offset:49152
	ds_read_b128 v[164:167], v139 offset:50176
	ds_read_b128 v[168:171], v139 offset:51200
	ds_read_b128 v[172:175], v139 offset:52224
	ds_read_b128 v[176:179], v139 offset:53248
	ds_read_b128 v[180:183], v139 offset:54272
	ds_read_b128 v[184:187], v139 offset:55296
	ds_read_b128 v[188:191], v139 offset:56320
	buffer_load_dwordx4 v134, s[44:47], s75 offen lds
	s_add_i32 s74, s74, 0x10080
	s_mov_b32 m0, s35
	s_nop 0
	buffer_load_dwordx4 v134, s[44:47], s74 offen lds
	s_barrier
	s_waitcnt lgkmcnt(0)
	s_setprio 1
	s_waitcnt lgkmcnt(6)
	v_mfma_f32_16x16x128_f8f6f4 v[62:65], v[2:9], v[160:167], v[62:65]
	v_mfma_f32_16x16x128_f8f6f4 v[58:61], v[10:17], v[160:167], v[58:61]
	s_waitcnt lgkmcnt(4)
	v_mfma_f32_16x16x128_f8f6f4 v[50:53], v[2:9], v[168:175], v[50:53]
	v_mfma_f32_16x16x128_f8f6f4 v[42:45], v[10:17], v[168:175], v[220:223]
	s_waitcnt lgkmcnt(2)
	v_mfma_f32_16x16x128_f8f6f4 v[34:37], v[2:9], v[176:183], v[224:227]
	v_mfma_f32_16x16x128_f8f6f4 v[26:29], v[10:17], v[176:183], v[228:231]
	s_waitcnt lgkmcnt(0)
	v_mfma_f32_16x16x128_f8f6f4 v[232:235], v[2:9], v[184:191], v[232:235]
	v_mfma_f32_16x16x128_f8f6f4 v[10:13], v[10:17], v[184:191], v[236:239]
	s_setprio 0
	s_barrier
	s_mov_b32 m0, s36
	s_add_i32 s33, s73, 0x2080
	buffer_load_dwordx4 v135, s[8:11], s33 offen lds
	s_add_i32 s73, s73, 0x22080
	s_mov_b32 m0, s37
	s_nop 0
	buffer_load_dwordx4 v135, s[8:11], s73 offen lds
	s_waitcnt vmcnt(6)
	s_barrier
	s_setprio 1
	v_mfma_f32_16x16x128_f8f6f4 v[54:57], v[144:151], v[160:167], v[54:57]
	v_mfma_f32_16x16x128_f8f6f4 v[46:49], v[152:159], v[160:167], v[240:243]
	v_mfma_f32_16x16x128_f8f6f4 v[38:41], v[144:151], v[168:175], v[244:247]
	v_mfma_f32_16x16x128_f8f6f4 v[30:33], v[152:159], v[168:175], v[248:251]
	v_mfma_f32_16x16x128_f8f6f4 v[22:25], v[144:151], v[176:183], v[130:133]
	v_mfma_f32_16x16x128_f8f6f4 v[14:17], v[152:159], v[176:183], v[140:143]
	v_mfma_f32_16x16x128_f8f6f4 v[6:9], v[144:151], v[184:191], v[66:69]
	v_mfma_f32_16x16x128_f8f6f4 v[2:5], v[152:159], v[184:191], v[192:195]
	s_setprio 0
	s_add_i32 s72, s72, 2
	s_addk_i32 s7, 0x100
	s_addk_i32 s71, 0x100
	s_cmp_gt_u32 s72, 5
	s_barrier
.LBB0_3185:
	ds_read_b128 v[144:147], v138
	ds_read_b128 v[148:151], v138 offset:1024
	ds_read_b128 v[152:155], v138 offset:2048
	ds_read_b128 v[156:159], v138 offset:3072
	s_add_i32 s10, s7, 0xfffd0080
	s_cmp_eq_u32 s72, 4
	s_cselect_b32 s74, s6, s10
	s_cselect_b32 s73, s57, s71
	s_or_b32 s75, s74, 0x80
	s_add_i32 s10, s7, 0xffff0000
	s_mov_b32 m0, s38
	ds_read_b128 v[160:163], v139
	ds_read_b128 v[164:167], v139 offset:1024
	ds_read_b128 v[168:171], v139 offset:2048
	ds_read_b128 v[172:175], v139 offset:3072
	ds_read_b128 v[176:179], v139 offset:4096
	ds_read_b128 v[180:183], v139 offset:5120
	ds_read_b128 v[184:187], v139 offset:6144
	ds_read_b128 v[188:191], v139 offset:7168
	buffer_load_dwordx4 v134, s[44:47], s10 offen lds
	s_mov_b32 m0, s39
	s_nop 0
	buffer_load_dwordx4 v134, s[44:47], s7 offen lds
	s_waitcnt lgkmcnt(8)
	s_barrier
	s_waitcnt lgkmcnt(0)
	s_setprio 1
	s_waitcnt lgkmcnt(4)
	v_mfma_f32_16x16x128_f8f6f4 v[114:117], v[144:151], v[168:175], v[114:117]
	v_mfma_f32_16x16x128_f8f6f4 v[106:109], v[152:159], v[168:175], v[106:109]
	s_waitcnt lgkmcnt(2)
	v_mfma_f32_16x16x128_f8f6f4 v[98:101], v[144:151], v[176:183], v[98:101]
	v_mfma_f32_16x16x128_f8f6f4 v[200:203], v[144:151], v[160:167], v[126:129]
	v_mfma_f32_16x16x128_f8f6f4 v[204:207], v[152:159], v[160:167], v[122:125]
	v_mfma_f32_16x16x128_f8f6f4 v[208:211], v[152:159], v[176:183], v[90:93]
	s_waitcnt lgkmcnt(0)
	v_mfma_f32_16x16x128_f8f6f4 v[212:215], v[144:151], v[184:191], v[82:85]
	v_mfma_f32_16x16x128_f8f6f4 v[216:219], v[152:159], v[184:191], v[74:77]
	s_setprio 0
	s_barrier
	s_mov_b32 m0, s22
	s_mov_b32 s10, s46
	s_mov_b32 s11, s47
	ds_read_b128 v[122:125], v254
	ds_read_b128 v[126:129], v254 offset:1024
	ds_read_b128 v[192:195], v254 offset:2048
	ds_read_b128 v[196:199], v254 offset:3072
	buffer_load_dwordx4 v135, s[8:11], s73 offen lds
	s_add_i32 s33, s73, 0x20000
	s_mov_b32 m0, s23
	s_nop 0
	buffer_load_dwordx4 v135, s[8:11], s33 offen lds
	s_barrier
	s_waitcnt lgkmcnt(0)
	s_setprio 1
	s_waitcnt lgkmcnt(2)
	v_mfma_f32_16x16x128_f8f6f4 v[118:121], v[122:129], v[160:167], v[118:121]
	s_waitcnt lgkmcnt(0)
	v_mfma_f32_16x16x128_f8f6f4 v[110:113], v[192:199], v[160:167], v[110:113]
	v_mfma_f32_16x16x128_f8f6f4 v[102:105], v[122:129], v[168:175], v[102:105]
	v_mfma_f32_16x16x128_f8f6f4 v[160:163], v[192:199], v[168:175], v[94:97]
	v_mfma_f32_16x16x128_f8f6f4 v[164:167], v[122:129], v[176:183], v[86:89]
	v_mfma_f32_16x16x128_f8f6f4 v[168:171], v[192:199], v[176:183], v[78:81]
	v_mfma_f32_16x16x128_f8f6f4 v[172:175], v[122:129], v[184:191], v[70:73]
	v_mfma_f32_16x16x128_f8f6f4 v[176:179], v[192:199], v[184:191], v[18:21]
	s_setprio 0
	s_mov_b32 m0, s21
	s_barrier
	ds_read_b128 v[66:69], v139 offset:16384
	s_nop 1
	ds_read_b128 v[70:73], v139 offset:17408
	ds_read_b128 v[74:77], v139 offset:18432
	ds_read_b128 v[78:81], v139 offset:19456
	ds_read_b128 v[82:85], v139 offset:20480
	ds_read_b128 v[86:89], v139 offset:21504
	ds_read_b128 v[90:93], v139 offset:22528
	ds_read_b128 v[94:97], v139 offset:23552
	buffer_load_dwordx4 v134, s[44:47], s74 offen lds
	s_add_i32 s33, s74, 0x10000
	s_mov_b32 m0, s24
	s_nop 0
	buffer_load_dwordx4 v134, s[44:47], s33 offen lds
	s_barrier
	s_waitcnt lgkmcnt(0)
	s_setprio 1
	s_waitcnt lgkmcnt(6)
	v_mfma_f32_16x16x128_f8f6f4 v[62:65], v[144:151], v[66:73], v[62:65]
	v_mfma_f32_16x16x128_f8f6f4 v[58:61], v[152:159], v[66:73], v[58:61]
	s_waitcnt lgkmcnt(4)
	v_mfma_f32_16x16x128_f8f6f4 v[50:53], v[144:151], v[74:81], v[50:53]
	s_waitcnt lgkmcnt(0)
	v_mfma_f32_16x16x128_f8f6f4 v[232:235], v[144:151], v[90:97], v[232:235]
	v_mfma_f32_16x16x128_f8f6f4 v[220:223], v[152:159], v[74:81], v[42:45]
	v_mfma_f32_16x16x128_f8f6f4 v[224:227], v[144:151], v[82:89], v[34:37]
	v_mfma_f32_16x16x128_f8f6f4 v[228:231], v[152:159], v[82:89], v[26:29]
	v_mfma_f32_16x16x128_f8f6f4 v[236:239], v[152:159], v[90:97], v[10:13]
	s_setprio 0
	s_barrier
	s_mov_b32 m0, s25
	s_add_i32 s33, s73, 0x2000
	buffer_load_dwordx4 v135, s[8:11], s33 offen lds
	s_add_i32 s33, s73, 0x22000
	s_mov_b32 m0, s26
	s_nop 0
	buffer_load_dwordx4 v135, s[8:11], s33 offen lds
	s_cmp_eq_u32 s100, 0
	s_cbranch_scc1 .Lfw_16_a
	s_waitcnt vmcnt(16)
	s_mov_b32 s100, 0
	s_branch .Lfw_16_b

.Lfw_16_b:
	s_barrier
	s_setprio 1
	v_mfma_f32_16x16x128_f8f6f4 v[54:57], v[122:129], v[66:73], v[54:57]
	v_mfma_f32_16x16x128_f8f6f4 v[240:243], v[192:199], v[66:73], v[46:49]
	v_mfma_f32_16x16x128_f8f6f4 v[244:247], v[122:129], v[74:81], v[38:41]
	v_mfma_f32_16x16x128_f8f6f4 v[248:251], v[192:199], v[74:81], v[30:33]
	v_mfma_f32_16x16x128_f8f6f4 v[130:133], v[122:129], v[82:89], v[22:25]
	v_mfma_f32_16x16x128_f8f6f4 v[140:143], v[192:199], v[82:89], v[14:17]
	v_mfma_f32_16x16x128_f8f6f4 v[66:69], v[122:129], v[90:97], v[6:9]
	v_mfma_f32_16x16x128_f8f6f4 v[192:195], v[192:199], v[90:97], v[2:5]
	s_setprio 0
	s_barrier
	s_nop 4
	ds_read_b128 v[2:5], v252
	ds_read_b128 v[6:9], v252 offset:1024
	ds_read_b128 v[10:13], v252 offset:2048
	ds_read_b128 v[14:17], v252 offset:3072
	s_mov_b32 m0, s27
	s_add_i32 s33, s74, 0x20000
	ds_read_b128 v[18:21], v139 offset:32768
	ds_read_b128 v[22:25], v139 offset:33792
	ds_read_b128 v[26:29], v139 offset:34816
	ds_read_b128 v[30:33], v139 offset:35840
	ds_read_b128 v[34:37], v139 offset:36864
	ds_read_b128 v[38:41], v139 offset:37888
	ds_read_b128 v[42:45], v139 offset:38912
	ds_read_b128 v[46:49], v139 offset:39936
	buffer_load_dwordx4 v134, s[44:47], s33 offen lds
	s_add_i32 s33, s74, 0x30000
	s_mov_b32 m0, s28
	s_nop 0
	buffer_load_dwordx4 v134, s[44:47], s33 offen lds
	s_waitcnt lgkmcnt(8)
	s_barrier
	s_waitcnt lgkmcnt(0)
	s_setprio 1
	s_waitcnt lgkmcnt(6)
	v_mfma_f32_16x16x128_f8f6f4 v[126:129], v[2:9], v[18:25], v[200:203]
	v_mfma_f32_16x16x128_f8f6f4 v[122:125], v[10:17], v[18:25], v[204:207]
	s_waitcnt lgkmcnt(4)
	v_mfma_f32_16x16x128_f8f6f4 v[114:117], v[2:9], v[26:33], v[114:117]
	v_mfma_f32_16x16x128_f8f6f4 v[106:109], v[10:17], v[26:33], v[106:109]
	s_waitcnt lgkmcnt(2)
	v_mfma_f32_16x16x128_f8f6f4 v[98:101], v[2:9], v[34:41], v[98:101]
	v_mfma_f32_16x16x128_f8f6f4 v[90:93], v[10:17], v[34:41], v[208:211]
	s_waitcnt lgkmcnt(0)
	v_mfma_f32_16x16x128_f8f6f4 v[82:85], v[2:9], v[42:49], v[212:215]
	v_mfma_f32_16x16x128_f8f6f4 v[74:77], v[10:17], v[42:49], v[216:219]
	s_setprio 0
	s_barrier
	s_mov_b32 m0, s30
	s_add_i32 s33, s73, 0x80
	ds_read_b128 v[144:147], v253
	ds_read_b128 v[148:151], v253 offset:1024
	ds_read_b128 v[152:155], v253 offset:2048
	ds_read_b128 v[156:159], v253 offset:3072
	buffer_load_dwordx4 v135, s[8:11], s33 offen lds
	s_add_i32 s33, s73, 0x20080
	s_mov_b32 m0, s31
	s_nop 0
	buffer_load_dwordx4 v135, s[8:11], s33 offen lds
	s_waitcnt vmcnt(10)
	s_barrier
	s_waitcnt lgkmcnt(0)
	s_setprio 1
	s_waitcnt lgkmcnt(2)
	v_mfma_f32_16x16x128_f8f6f4 v[118:121], v[144:151], v[18:25], v[118:121]
	s_waitcnt lgkmcnt(0)
	v_mfma_f32_16x16x128_f8f6f4 v[110:113], v[152:159], v[18:25], v[110:113]
	v_mfma_f32_16x16x128_f8f6f4 v[102:105], v[144:151], v[26:33], v[102:105]
	v_mfma_f32_16x16x128_f8f6f4 v[94:97], v[152:159], v[26:33], v[160:163]
	v_mfma_f32_16x16x128_f8f6f4 v[86:89], v[144:151], v[34:41], v[164:167]
	v_mfma_f32_16x16x128_f8f6f4 v[78:81], v[152:159], v[34:41], v[168:171]
	v_mfma_f32_16x16x128_f8f6f4 v[70:73], v[144:151], v[42:49], v[172:175]
	v_mfma_f32_16x16x128_f8f6f4 v[18:21], v[152:159], v[42:49], v[176:179]
	s_setprio 0
	s_mov_b32 m0, s34
	s_barrier
	ds_read_b128 v[160:163], v139 offset:49152
	ds_read_b128 v[164:167], v139 offset:50176
	ds_read_b128 v[168:171], v139 offset:51200
	ds_read_b128 v[172:175], v139 offset:52224
	ds_read_b128 v[176:179], v139 offset:53248
	ds_read_b128 v[180:183], v139 offset:54272
	ds_read_b128 v[184:187], v139 offset:55296
	ds_read_b128 v[188:191], v139 offset:56320
	buffer_load_dwordx4 v134, s[44:47], s75 offen lds
	s_add_i32 s74, s74, 0x10080
	s_mov_b32 m0, s35
	s_nop 0
	buffer_load_dwordx4 v134, s[44:47], s74 offen lds
	s_barrier
	s_waitcnt lgkmcnt(0)
	s_setprio 1
	s_waitcnt lgkmcnt(6)
	v_mfma_f32_16x16x128_f8f6f4 v[62:65], v[2:9], v[160:167], v[62:65]
	v_mfma_f32_16x16x128_f8f6f4 v[58:61], v[10:17], v[160:167], v[58:61]
	s_waitcnt lgkmcnt(4)
	v_mfma_f32_16x16x128_f8f6f4 v[50:53], v[2:9], v[168:175], v[50:53]
	v_mfma_f32_16x16x128_f8f6f4 v[42:45], v[10:17], v[168:175], v[220:223]
	s_waitcnt lgkmcnt(2)
	v_mfma_f32_16x16x128_f8f6f4 v[34:37], v[2:9], v[176:183], v[224:227]
	v_mfma_f32_16x16x128_f8f6f4 v[26:29], v[10:17], v[176:183], v[228:231]
	s_waitcnt lgkmcnt(0)
	v_mfma_f32_16x16x128_f8f6f4 v[232:235], v[2:9], v[184:191], v[232:235]
	v_mfma_f32_16x16x128_f8f6f4 v[10:13], v[10:17], v[184:191], v[236:239]
	s_setprio 0
	s_barrier
	s_mov_b32 m0, s36
	s_add_i32 s33, s73, 0x2080
	buffer_load_dwordx4 v135, s[8:11], s33 offen lds
	s_add_i32 s73, s73, 0x22080
	s_mov_b32 m0, s37
	s_nop 0
	buffer_load_dwordx4 v135, s[8:11], s73 offen lds
	s_waitcnt vmcnt(6)
	s_barrier
	s_setprio 1
	v_mfma_f32_16x16x128_f8f6f4 v[54:57], v[144:151], v[160:167], v[54:57]
	v_mfma_f32_16x16x128_f8f6f4 v[46:49], v[152:159], v[160:167], v[240:243]
	v_mfma_f32_16x16x128_f8f6f4 v[38:41], v[144:151], v[168:175], v[244:247]
	v_mfma_f32_16x16x128_f8f6f4 v[30:33], v[152:159], v[168:175], v[248:251]
	v_mfma_f32_16x16x128_f8f6f4 v[22:25], v[144:151], v[176:183], v[130:133]
	v_mfma_f32_16x16x128_f8f6f4 v[14:17], v[152:159], v[176:183], v[140:143]
	v_mfma_f32_16x16x128_f8f6f4 v[6:9], v[144:151], v[184:191], v[66:69]
	v_mfma_f32_16x16x128_f8f6f4 v[2:5], v[152:159], v[184:191], v[192:195]
	s_setprio 0
	s_add_i32 s72, s72, 2
	s_addk_i32 s7, 0x100
	s_addk_i32 s71, 0x100
	s_cmp_gt_u32 s72, 5
	s_barrier
	s_cbranch_scc0 .LBB0_3185
	v_lshl_add_u32 v152, s70, 8, v136
	v_lshlrev_b32_e32 v153, 1, v137
	v_lshl_or_b32 v153, s59, 8, v153
	v_lshl_add_u32 v152, v152, 10, v153
	s_mov_b32 s59, s50
	s_mov_b32 s70, s51
	s_mov_b32 s71, s57
	s_mov_b32 s72, s58
	v_pk_mul_f32 v[126:127], v[126:127], 0.5 op_sel_hi:[1,0]
	v_pk_mul_f32 v[128:129], v[128:129], 0.5 op_sel_hi:[1,0]
	v_pk_mul_f32 v[122:123], v[122:123], 0.5 op_sel_hi:[1,0]
	v_pk_mul_f32 v[124:125], v[124:125], 0.5 op_sel_hi:[1,0]
	v_pk_mul_f32 v[118:119], v[118:119], 0.5 op_sel_hi:[1,0]
	v_pk_mul_f32 v[120:121], v[120:121], 0.5 op_sel_hi:[1,0]
	v_pk_mul_f32 v[110:111], v[110:111], 0.5 op_sel_hi:[1,0]
	v_pk_mul_f32 v[112:113], v[112:113], 0.5 op_sel_hi:[1,0]
	v_cvt_pk_fp8_f32 v144, v126, v127
	v_cvt_pk_fp8_f32 v145, v122, v123
	v_cvt_pk_fp8_f32 v146, v118, v119
	v_cvt_pk_fp8_f32 v147, v110, v111
	v_cvt_pk_fp8_f32 v144, v128, v129 op_sel:[0,0,1]
	v_cvt_pk_fp8_f32 v145, v124, v125 op_sel:[0,0,1]
	v_cvt_pk_fp8_f32 v146, v120, v121 op_sel:[0,0,1]
	v_cvt_pk_fp8_f32 v147, v112, v113 op_sel:[0,0,1]
	v_mov_b32_e32 v154, v152
	s_nop 0
	global_store_dwordx4 v154, v[144:147], s[68:69]
	s_mov_b32 s100, 1
	v_pk_mul_f32 v[114:115], v[114:115], 0.5 op_sel_hi:[1,0]
	v_pk_mul_f32 v[116:117], v[116:117], 0.5 op_sel_hi:[1,0]
	v_pk_mul_f32 v[106:107], v[106:107], 0.5 op_sel_hi:[1,0]
	v_pk_mul_f32 v[108:109], v[108:109], 0.5 op_sel_hi:[1,0]
	v_pk_mul_f32 v[102:103], v[102:103], 0.5 op_sel_hi:[1,0]
	v_pk_mul_f32 v[104:105], v[104:105], 0.5 op_sel_hi:[1,0]
	v_pk_mul_f32 v[94:95], v[94:95], 0.5 op_sel_hi:[1,0]
	v_pk_mul_f32 v[96:97], v[96:97], 0.5 op_sel_hi:[1,0]
	v_cvt_pk_fp8_f32 v148, v114, v115
	v_cvt_pk_fp8_f32 v149, v106, v107
	v_cvt_pk_fp8_f32 v150, v102, v103
	v_cvt_pk_fp8_f32 v151, v94, v95
	v_cvt_pk_fp8_f32 v148, v116, v117 op_sel:[0,0,1]
	v_cvt_pk_fp8_f32 v149, v108, v109 op_sel:[0,0,1]
	v_cvt_pk_fp8_f32 v150, v104, v105 op_sel:[0,0,1]
	v_cvt_pk_fp8_f32 v151, v96, v97 op_sel:[0,0,1]
	v_add_u32_e32 v155, 0x4000, v152
	s_nop 0
	global_store_dwordx4 v155, v[148:151], s[68:69]
	s_mov_b32 s100, 1
	v_pk_mul_f32 v[98:99], v[98:99], 0.5 op_sel_hi:[1,0]
	v_pk_mul_f32 v[100:101], v[100:101], 0.5 op_sel_hi:[1,0]
	v_pk_mul_f32 v[90:91], v[90:91], 0.5 op_sel_hi:[1,0]
	v_pk_mul_f32 v[92:93], v[92:93], 0.5 op_sel_hi:[1,0]
	v_pk_mul_f32 v[86:87], v[86:87], 0.5 op_sel_hi:[1,0]
	v_pk_mul_f32 v[88:89], v[88:89], 0.5 op_sel_hi:[1,0]
	v_pk_mul_f32 v[78:79], v[78:79], 0.5 op_sel_hi:[1,0]
	v_pk_mul_f32 v[80:81], v[80:81], 0.5 op_sel_hi:[1,0]
	v_cvt_pk_fp8_f32 v144, v98, v99
	v_cvt_pk_fp8_f32 v145, v90, v91
	v_cvt_pk_fp8_f32 v146, v86, v87
	v_cvt_pk_fp8_f32 v147, v78, v79
	v_cvt_pk_fp8_f32 v144, v100, v101 op_sel:[0,0,1]
	v_cvt_pk_fp8_f32 v145, v92, v93 op_sel:[0,0,1]
	v_cvt_pk_fp8_f32 v146, v88, v89 op_sel:[0,0,1]
	v_cvt_pk_fp8_f32 v147, v80, v81 op_sel:[0,0,1]
	v_add_u32_e32 v154, 0x8000, v152
	s_nop 0
	global_store_dwordx4 v154, v[144:147], s[68:69]
	s_mov_b32 s100, 1
	v_pk_mul_f32 v[82:83], v[82:83], 0.5 op_sel_hi:[1,0]
	v_pk_mul_f32 v[84:85], v[84:85], 0.5 op_sel_hi:[1,0]
	v_pk_mul_f32 v[74:75], v[74:75], 0.5 op_sel_hi:[1,0]
	v_pk_mul_f32 v[76:77], v[76:77], 0.5 op_sel_hi:[1,0]
	v_pk_mul_f32 v[70:71], v[70:71], 0.5 op_sel_hi:[1,0]
	v_pk_mul_f32 v[72:73], v[72:73], 0.5 op_sel_hi:[1,0]
	v_pk_mul_f32 v[18:19], v[18:19], 0.5 op_sel_hi:[1,0]
	v_pk_mul_f32 v[20:21], v[20:21], 0.5 op_sel_hi:[1,0]
	v_cvt_pk_fp8_f32 v148, v82, v83
	v_cvt_pk_fp8_f32 v149, v74, v75
	v_cvt_pk_fp8_f32 v150, v70, v71
	v_cvt_pk_fp8_f32 v151, v18, v19
	v_cvt_pk_fp8_f32 v148, v84, v85 op_sel:[0,0,1]
	v_cvt_pk_fp8_f32 v149, v76, v77 op_sel:[0,0,1]
	v_cvt_pk_fp8_f32 v150, v72, v73 op_sel:[0,0,1]
	v_cvt_pk_fp8_f32 v151, v20, v21 op_sel:[0,0,1]
	v_add_u32_e32 v155, 0xc000, v152
	s_nop 0
	global_store_dwordx4 v155, v[148:151], s[68:69]
	s_mov_b32 s100, 1
	v_pk_mul_f32 v[62:63], v[62:63], 0.5 op_sel_hi:[1,0]
	v_pk_mul_f32 v[64:65], v[64:65], 0.5 op_sel_hi:[1,0]
	v_pk_mul_f32 v[58:59], v[58:59], 0.5 op_sel_hi:[1,0]
	v_pk_mul_f32 v[60:61], v[60:61], 0.5 op_sel_hi:[1,0]
	v_pk_mul_f32 v[54:55], v[54:55], 0.5 op_sel_hi:[1,0]
	v_pk_mul_f32 v[56:57], v[56:57], 0.5 op_sel_hi:[1,0]
	v_pk_mul_f32 v[46:47], v[46:47], 0.5 op_sel_hi:[1,0]
	v_pk_mul_f32 v[48:49], v[48:49], 0.5 op_sel_hi:[1,0]
	v_cvt_pk_fp8_f32 v144, v62, v63
	v_cvt_pk_fp8_f32 v145, v58, v59
	v_cvt_pk_fp8_f32 v146, v54, v55
	v_cvt_pk_fp8_f32 v147, v46, v47
	v_cvt_pk_fp8_f32 v144, v64, v65 op_sel:[0,0,1]
	v_cvt_pk_fp8_f32 v145, v60, v61 op_sel:[0,0,1]
	v_cvt_pk_fp8_f32 v146, v56, v57 op_sel:[0,0,1]
	v_cvt_pk_fp8_f32 v147, v48, v49 op_sel:[0,0,1]
	v_add_u32_e32 v154, 0x20000, v152
	s_nop 0
	global_store_dwordx4 v154, v[144:147], s[68:69]
	s_mov_b32 s100, 1
	v_pk_mul_f32 v[50:51], v[50:51], 0.5 op_sel_hi:[1,0]
	v_pk_mul_f32 v[52:53], v[52:53], 0.5 op_sel_hi:[1,0]
	v_pk_mul_f32 v[42:43], v[42:43], 0.5 op_sel_hi:[1,0]
	v_pk_mul_f32 v[44:45], v[44:45], 0.5 op_sel_hi:[1,0]
	v_pk_mul_f32 v[38:39], v[38:39], 0.5 op_sel_hi:[1,0]
	v_pk_mul_f32 v[40:41], v[40:41], 0.5 op_sel_hi:[1,0]
	v_pk_mul_f32 v[30:31], v[30:31], 0.5 op_sel_hi:[1,0]
	v_pk_mul_f32 v[32:33], v[32:33], 0.5 op_sel_hi:[1,0]
	v_cvt_pk_fp8_f32 v148, v50, v51
	v_cvt_pk_fp8_f32 v149, v42, v43
	v_cvt_pk_fp8_f32 v150, v38, v39
	v_cvt_pk_fp8_f32 v151, v30, v31
	v_cvt_pk_fp8_f32 v148, v52, v53 op_sel:[0,0,1]
	v_cvt_pk_fp8_f32 v149, v44, v45 op_sel:[0,0,1]
	v_cvt_pk_fp8_f32 v150, v40, v41 op_sel:[0,0,1]
	v_cvt_pk_fp8_f32 v151, v32, v33 op_sel:[0,0,1]
	v_add_u32_e32 v155, 0x24000, v152
	s_nop 0
	global_store_dwordx4 v155, v[148:151], s[68:69]
	s_mov_b32 s100, 1
	v_pk_mul_f32 v[34:35], v[34:35], 0.5 op_sel_hi:[1,0]
	v_pk_mul_f32 v[36:37], v[36:37], 0.5 op_sel_hi:[1,0]
	v_pk_mul_f32 v[26:27], v[26:27], 0.5 op_sel_hi:[1,0]
	v_pk_mul_f32 v[28:29], v[28:29], 0.5 op_sel_hi:[1,0]
	v_pk_mul_f32 v[22:23], v[22:23], 0.5 op_sel_hi:[1,0]
	v_pk_mul_f32 v[24:25], v[24:25], 0.5 op_sel_hi:[1,0]
	v_pk_mul_f32 v[14:15], v[14:15], 0.5 op_sel_hi:[1,0]
	v_pk_mul_f32 v[16:17], v[16:17], 0.5 op_sel_hi:[1,0]
	v_cvt_pk_fp8_f32 v144, v34, v35
	v_cvt_pk_fp8_f32 v145, v26, v27
	v_cvt_pk_fp8_f32 v146, v22, v23
	v_cvt_pk_fp8_f32 v147, v14, v15
	v_cvt_pk_fp8_f32 v144, v36, v37 op_sel:[0,0,1]
	v_cvt_pk_fp8_f32 v145, v28, v29 op_sel:[0,0,1]
	v_cvt_pk_fp8_f32 v146, v24, v25 op_sel:[0,0,1]
	v_cvt_pk_fp8_f32 v147, v16, v17 op_sel:[0,0,1]
	v_add_u32_e32 v154, 0x28000, v152
	s_nop 0
	global_store_dwordx4 v154, v[144:147], s[68:69]
	s_mov_b32 s100, 1
	v_pk_mul_f32 v[232:233], v[232:233], 0.5 op_sel_hi:[1,0]
	v_pk_mul_f32 v[234:235], v[234:235], 0.5 op_sel_hi:[1,0]
	v_pk_mul_f32 v[10:11], v[10:11], 0.5 op_sel_hi:[1,0]
	v_pk_mul_f32 v[12:13], v[12:13], 0.5 op_sel_hi:[1,0]
	v_pk_mul_f32 v[6:7], v[6:7], 0.5 op_sel_hi:[1,0]
	v_pk_mul_f32 v[8:9], v[8:9], 0.5 op_sel_hi:[1,0]
	v_pk_mul_f32 v[2:3], v[2:3], 0.5 op_sel_hi:[1,0]
	v_pk_mul_f32 v[4:5], v[4:5], 0.5 op_sel_hi:[1,0]
	v_cvt_pk_fp8_f32 v148, v232, v233
	v_cvt_pk_fp8_f32 v149, v10, v11
	v_cvt_pk_fp8_f32 v150, v6, v7
	v_cvt_pk_fp8_f32 v151, v2, v3
	v_cvt_pk_fp8_f32 v148, v234, v235 op_sel:[0,0,1]
	v_cvt_pk_fp8_f32 v149, v12, v13 op_sel:[0,0,1]
	v_cvt_pk_fp8_f32 v150, v8, v9 op_sel:[0,0,1]
	v_cvt_pk_fp8_f32 v151, v4, v5 op_sel:[0,0,1]
	v_add_u32_e32 v155, 0x2c000, v152
	s_nop 0
	global_store_dwordx4 v155, v[148:151], s[68:69]
	s_mov_b32 s100, 1
	s_and_b64 vcc, exec, s[4:5]
	s_cbranch_vccz .LBB0_3176
	s_waitcnt vmcnt(0)
	s_cmpk_gt_u32 s3, 0xff
	s_cbranch_scc1 .LBB0_3189
	s_barrier
